# K-loop memory segments: ds_read run issued first after the segment-opening barrier; the 3 SALU/VALU address instrs for the DMA issue moved behind it (21 sites)
# baseline (speedup 1.0000x reference)
; #define G8_STA(bufoff, ptr, sg, h) G8_STAGE1(bufoff, (ptr) + (h) * ((sg) ? hA1 : hA0), ((sg) ? voffA1 : voffA0), ((sg) ? r64A1 : r64A0))
; #define G8_STB(bufoff, ptr, sg, h) G8_STAGE1(bufoff, (ptr) + (h) * ((sg) ? hB1 : hB0), ((sg) ? voffB1 : voffB0), ((sg) ? r64B1 : r64B0))
; #define G8_LDA(dst, b, h) do { _Pragma("unroll") for (int m = 0; m < 4; ++m) _Pragma("unroll") for (int k = 0; k < 2; ++k) dst[m][k] = *(const LAS bf16x8*)(lds + G8_SA(b, h) + aoff + m * 2048 + k * 1024); } while (0)
; #define G8_LDB(dst, b, h) do { _Pragma("unroll") for (int n = 0; n < 2; ++n) _Pragma("unroll") for (int k = 0; k < 2; ++k) dst[n][k] = *(const LAS bf16x8*)(lds + G8_SB(b, h) + boff + n * 2048 + k * 1024); } while (0)
; #define G8_WAIT_V(n) asm volatile("s_waitcnt vmcnt(" #n ")" ::: "memory")
; #define G8_WAIT_L(n) asm volatile("s_waitcnt lgkmcnt(" #n ")" ::: "memory")
; template <class P>
; __device__ __forceinline__ void gemm_phase(LAS unsigned char* lds, const P& p, const int G, const int c) {
;     ...
;         const bool has_next = p.unit((ui + 1) * G + c, nxt);
;         const int nt = p.nt(cur);
;         const char* nA0 = has_next ? p.a_base(nxt, 0) - p.a_bias(0) : cA0; const char* nA1 = has_next ? p.a_base(nxt, S1) - p.a_bias(S1) : cA1;
;         const char* nB0 = has_next ? p.b_base(nxt, 0) - p.b_bias(0) : cB0; const char* nB1 = has_next ? p.b_base(nxt, S1) - p.b_bias(S1) : cB1;
;         for (int t = 0; t < nt; t += 2) {
;             const bool last = (t == nt - 2);
;             const bool sg1 = (NS > 1) && (t + 1 >= nt0);
;             const bool sg2 = (NS > 1) && !last && (t + 2 >= nt0);
;             const char* a1 = sg1 ? cA1 + (long)(t + 1 - nt0) * ksA1 : cA0 + (long)(t + 1) * ksA0;
;             const char* a2 = last ? nA0 : (sg2 ? cA1 + (long)(t + 2 - nt0) * ksA1 : cA0 + (long)(t + 2) * ksA0);
;             const char* b2 = last ? nB0 : (sg2 ? cB1 + (long)(t + 2 - nt0) * ksB1 : cB0 + (long)(t + 2) * ksB0);
;             const char* a3 = a2 + (sg2 ? ksA1 : ksA0); const char* b3 = b2 + (sg2 ? ksB1 : ksB0);
;             G8_LDB(B0, 0, 0); G8_LDB(B1, 0, 1); G8_SCHED; G8_LDA(At, 0, 0); G8_STA(G8_SA(1, 1), a1, sg1, 1);
;             G8_WAIT_V(8); G8_WAIT_L(0); G8_BAR; G8_MMA(0, 0, At, B0); G8_MMA(0, 1, At, B1); G8_BAR; G8_SCHED;
;             G8_LDA(At, 0, 1); G8_STB(G8_SB(0, 0), b2, sg2, 0); G8_STB(G8_SB(0, 1), b2, sg2, 1); G8_STA(G8_SA(0, 0), a2, sg2, 0);
.LBB0_154:
	s_cmp_lt_i32 s88, 16
	s_cselect_b64 s[18:19], -1, 0
	s_cmpk_gt_i32 s68, 0x7f
	s_cselect_b64 s[30:31], -1, 0
	s_ashr_i32 s69, s68, 31
	s_or_b64 s[18:19], s[18:19], s[30:31]
	s_lshl_b64 s[30:31], s[68:69], 15
	v_readlane_b32 s52, v253, 7
	s_and_b64 s[18:19], s[18:19], exec
	v_readlane_b32 s66, v253, 21
	v_readlane_b32 s67, v253, 22
	s_cselect_b32 s19, s3, s66
	s_cselect_b32 s18, s24, s67
	s_add_u32 s72, s19, s30
	s_addc_u32 s73, s18, s31
	s_and_b64 s[18:19], s[70:71], exec
	s_cselect_b32 s18, s73, s83
	s_cselect_b32 s19, s72, s82
	s_ashr_i32 s89, s88, 31
	s_lshl_b64 s[30:31], s[88:89], 15
	s_add_u32 s76, s25, s30
	s_addc_u32 s77, s26, s31
	s_and_b64 s[30:31], s[70:71], exec
	s_cselect_b32 s30, s77, s29
	s_cselect_b32 s31, s76, s28
	s_add_u32 s28, s28, 0x200000
	s_addc_u32 s29, s29, 0
	v_lshl_add_u64 v[54:55], s[82:83], 0, v[148:149]
	s_mov_b32 s52, -2
	s_mov_b64 s[84:85], 0
	v_readlane_b32 s53, v253, 8
	v_readlane_b32 s54, v253, 9
	v_readlane_b32 s55, v253, 10
	v_readlane_b32 s56, v253, 11
	v_readlane_b32 s57, v253, 12
	v_readlane_b32 s58, v253, 13
	v_readlane_b32 s59, v253, 14
	v_readlane_b32 s60, v253, 15
	v_readlane_b32 s61, v253, 16
	v_readlane_b32 s62, v253, 17
	v_readlane_b32 s63, v253, 18
	v_readlane_b32 s64, v253, 19
	v_readlane_b32 s65, v253, 20
	ds_read_b128 v[56:59], v173
	ds_read_b128 v[60:63], v173 offset:1024
	ds_read_b128 v[176:179], v173 offset:2048
	ds_read_b128 v[180:183], v173 offset:3072
	ds_read_b128 v[184:187], v174
	ds_read_b128 v[188:191], v174 offset:1024
	ds_read_b128 v[192:195], v174 offset:2048
	ds_read_b128 v[196:199], v174 offset:3072
	s_add_u32 s53, s82, s84
	s_addc_u32 s56, s83, s85
	s_add_u32 s53, s53, 0x820000
	s_addc_u32 s56, s56, 0
	s_cmp_eq_u32 s84, 0x38e0000
	s_cselect_b32 s57, s18, s56
	s_cselect_b32 s56, s19, s53
	s_cselect_b32 s65, s30, s29
	s_cselect_b32 s64, s31, s28
	v_lshl_add_u64 v[64:65], v[54:55], 0, s[84:85]
	s_mov_b64 s[66:67], 0x414000
	v_lshl_add_u64 v[234:235], v[64:65], 0, s[66:67]
	s_add_i32 m0, s27, 0xc000
	s_mov_b64 s[66:67], 0x416000
	ds_read_b128 v[200:203], v175
	ds_read_b128 v[204:207], v175 offset:1024
	ds_read_b128 v[210:213], v175 offset:2048
	ds_read_b128 v[214:217], v175 offset:3072
	ds_read_b128 v[218:221], v175 offset:4096
	ds_read_b128 v[222:225], v175 offset:5120
	ds_read_b128 v[226:229], v175 offset:6144
	ds_read_b128 v[230:233], v175 offset:7168
	global_load_lds_dwordx4 v[234:235], off
	v_lshl_add_u64 v[64:65], v[64:65], 0, s[66:67]
	s_add_i32 m0, s27, 0xe000
	s_nop 0
	global_load_lds_dwordx4 v[64:65], off
	s_waitcnt vmcnt(8)
	s_waitcnt lgkmcnt(0)
	s_barrier
	s_waitcnt lgkmcnt(0)
	v_mfma_f32_16x16x32_bf16 v[98:101], v[56:59], v[200:203], 0
	v_mfma_f32_16x16x32_bf16 v[138:141], v[176:179], v[200:203], 0
	v_mfma_f32_16x16x32_bf16 v[70:73], v[56:59], v[210:213], 0
	v_mfma_f32_16x16x32_bf16 v[114:117], v[176:179], v[210:213], 0
	v_mfma_f32_16x16x32_bf16 v[46:49], v[56:59], v[218:221], 0
	v_mfma_f32_16x16x32_bf16 v[110:113], v[176:179], v[218:221], 0
	v_mfma_f32_16x16x32_bf16 v[38:41], v[56:59], v[226:229], 0
	v_mfma_f32_16x16x32_bf16 v[130:133], v[176:179], v[226:229], 0
	v_mfma_f32_16x16x32_bf16 v[98:101], v[60:63], v[204:207], v[98:101]
	v_mfma_f32_16x16x32_bf16 v[138:141], v[180:183], v[204:207], v[138:141]
	v_mfma_f32_16x16x32_bf16 v[70:73], v[60:63], v[214:217], v[70:73]
	v_mfma_f32_16x16x32_bf16 v[114:117], v[180:183], v[214:217], v[114:117]
	v_mfma_f32_16x16x32_bf16 v[46:49], v[60:63], v[222:225], v[46:49]
	v_mfma_f32_16x16x32_bf16 v[110:113], v[180:183], v[222:225], v[110:113]
	v_mfma_f32_16x16x32_bf16 v[38:41], v[60:63], v[230:233], v[38:41]
	v_mfma_f32_16x16x32_bf16 v[130:133], v[180:183], v[230:233], v[130:133]
	v_mfma_f32_16x16x32_bf16 v[134:137], v[184:187], v[200:203], 0
	v_mfma_f32_16x16x32_bf16 v[74:77], v[192:195], v[200:203], 0
	v_mfma_f32_16x16x32_bf16 v[106:109], v[184:187], v[210:213], 0
	v_mfma_f32_16x16x32_bf16 v[50:53], v[192:195], v[210:213], 0
	v_mfma_f32_16x16x32_bf16 v[102:105], v[184:187], v[218:221], 0
	v_mfma_f32_16x16x32_bf16 v[42:45], v[192:195], v[218:221], 0
	v_mfma_f32_16x16x32_bf16 v[126:129], v[184:187], v[226:229], 0
	v_mfma_f32_16x16x32_bf16 v[34:37], v[192:195], v[226:229], 0
	v_mfma_f32_16x16x32_bf16 v[134:137], v[188:191], v[204:207], v[134:137]
	v_mfma_f32_16x16x32_bf16 v[74:77], v[196:199], v[204:207], v[74:77]
	v_mfma_f32_16x16x32_bf16 v[106:109], v[188:191], v[214:217], v[106:109]
	v_mfma_f32_16x16x32_bf16 v[50:53], v[196:199], v[214:217], v[50:53]
	v_mfma_f32_16x16x32_bf16 v[102:105], v[188:191], v[222:225], v[102:105]
	v_mfma_f32_16x16x32_bf16 v[42:45], v[196:199], v[222:225], v[42:45]
	v_mfma_f32_16x16x32_bf16 v[126:129], v[188:191], v[230:233], v[126:129]
	v_mfma_f32_16x16x32_bf16 v[34:37], v[196:199], v[230:233], v[34:37]
	s_barrier
	ds_read_b128 v[200:203], v175 offset:16384
	ds_read_b128 v[204:207], v175 offset:17408
	ds_read_b128 v[210:213], v175 offset:18432
	ds_read_b128 v[214:217], v175 offset:19456
	ds_read_b128 v[218:221], v175 offset:20480
	ds_read_b128 v[222:225], v175 offset:21504
	ds_read_b128 v[226:229], v175 offset:22528
	ds_read_b128 v[230:233], v175 offset:23552
	s_add_i32 s53, s50, s2
	s_mov_b32 m0, s53
	v_lshl_add_u64 v[234:235], s[64:65], 0, v[142:143]
	global_load_lds_dwordx4 v[234:235], off
	v_lshl_add_u64 v[64:65], v[234:235], 0, s[4:5]
	s_add_i32 m0, s53, 0x2000
	s_add_i32 s53, s51, s2
	global_load_lds_dwordx4 v[64:65], off
	v_lshl_add_u64 v[64:65], v[234:235], 0, s[6:7]
	s_mov_b32 m0, s53
	v_lshl_add_u64 v[236:237], s[56:57], 0, v[144:145]
	global_load_lds_dwordx4 v[64:65], off
	v_lshl_add_u64 v[64:65], v[234:235], 0, s[8:9]
	s_add_i32 m0, s53, 0x2000
	s_nop 0
	global_load_lds_dwordx4 v[64:65], off
	s_mov_b32 m0, s27
	v_lshl_add_u64 v[64:65], v[236:237], 0, s[4:5]
	global_load_lds_dwordx4 v[236:237], off
	s_mov_b32 m0, s33
	s_nop 0
	global_load_lds_dwordx4 v[64:65], off
	s_waitcnt vmcnt(8)
	s_waitcnt lgkmcnt(0)
	s_barrier
; #define G8_STA(bufoff, ptr, sg, h) G8_STAGE1(bufoff, (ptr) + (h) * ((sg) ? hA1 : hA0), ((sg) ? voffA1 : voffA0), ((sg) ? r64A1 : r64A0))
; #define G8_STB(bufoff, ptr, sg, h) G8_STAGE1(bufoff, (ptr) + (h) * ((sg) ? hB1 : hB0), ((sg) ? voffB1 : voffB0), ((sg) ? r64B1 : r64B0))
; #define G8_LDA(dst, b, h) do { _Pragma("unroll") for (int m = 0; m < 4; ++m) _Pragma("unroll") for (int k = 0; k < 2; ++k) dst[m][k] = *(const LAS bf16x8*)(lds + G8_SA(b, h) + aoff + m * 2048 + k * 1024); } while (0)
; #define G8_LDB(dst, b, h) do { _Pragma("unroll") for (int n = 0; n < 2; ++n) _Pragma("unroll") for (int k = 0; k < 2; ++k) dst[n][k] = *(const LAS bf16x8*)(lds + G8_SB(b, h) + boff + n * 2048 + k * 1024); } while (0)
; #define G8_MMA(ai, bj, At, Bt) do { __builtin_amdgcn_s_setprio(1); _Pragma("unroll") for (int m = 0; m < 4; ++m) _Pragma("unroll") for (int n = 0; n < 2; ++n) _Pragma("unroll") for (int k = 0; k < 2; ++k) \
;         acc[ai][bj][m][n] = __builtin_amdgcn_mfma_f32_16x16x32_bf16(Bt[n][k], At[m][k], acc[ai][bj][m][n], 0, 0, 0); __builtin_amdgcn_s_setprio(0); } while (0)
; #define G8_WAIT_V(n) asm volatile("s_waitcnt vmcnt(" #n ")" ::: "memory")
; #define G8_WAIT_L(n) asm volatile("s_waitcnt lgkmcnt(" #n ")" ::: "memory")
; #define G8_BAR __builtin_amdgcn_s_barrier()
; #define G8_SCHED __builtin_amdgcn_sched_barrier(0)
; template <class P>
; __device__ __forceinline__ void gemm_phase(LAS unsigned char* lds, const P& p, const int G, const int c) {
;     ...
;             G8_LDB(B0, 0, 0); G8_LDB(B1, 0, 1); G8_SCHED; G8_LDA(At, 0, 0); G8_STA(G8_SA(1, 1), a1, sg1, 1);
;             G8_WAIT_V(8); G8_WAIT_L(0); G8_BAR; G8_MMA(0, 0, At, B0); G8_MMA(0, 1, At, B1); G8_BAR; G8_SCHED;
;             G8_LDA(At, 0, 1); G8_STB(G8_SB(0, 0), b2, sg2, 0); G8_STB(G8_SB(0, 1), b2, sg2, 1); G8_STA(G8_SA(0, 0), a2, sg2, 0);
;             G8_WAIT_V(8); G8_WAIT_L(0); G8_BAR; G8_MMA(1, 0, At, B0); G8_MMA(1, 1, At, B1); G8_BAR; G8_SCHED;
	s_waitcnt lgkmcnt(0)
	v_mfma_f32_16x16x32_bf16 v[30:33], v[56:59], v[200:203], 0
	v_mfma_f32_16x16x32_bf16 v[122:125], v[176:179], v[200:203], 0
	v_mfma_f32_16x16x32_bf16 v[22:25], v[56:59], v[210:213], 0
	v_mfma_f32_16x16x32_bf16 v[94:97], v[176:179], v[210:213], 0
	v_mfma_f32_16x16x32_bf16 v[14:17], v[56:59], v[218:221], 0
	v_mfma_f32_16x16x32_bf16 v[90:93], v[176:179], v[218:221], 0
	v_mfma_f32_16x16x32_bf16 v[6:9], v[56:59], v[226:229], 0
	v_mfma_f32_16x16x32_bf16 v[30:33], v[60:63], v[204:207], v[30:33]
	v_mfma_f32_16x16x32_bf16 v[122:125], v[180:183], v[204:207], v[122:125]
	v_mfma_f32_16x16x32_bf16 v[22:25], v[60:63], v[214:217], v[22:25]
	v_mfma_f32_16x16x32_bf16 v[94:97], v[180:183], v[214:217], v[94:97]
	v_mfma_f32_16x16x32_bf16 v[14:17], v[60:63], v[222:225], v[14:17]
	v_mfma_f32_16x16x32_bf16 v[90:93], v[180:183], v[222:225], v[90:93]
	v_mfma_f32_16x16x32_bf16 v[6:9], v[60:63], v[230:233], v[6:9]
	v_mfma_f32_16x16x32_bf16 v[56:59], v[176:179], v[226:229], 0
	v_mfma_f32_16x16x32_bf16 v[56:59], v[180:183], v[230:233], v[56:59]
	v_mfma_f32_16x16x32_bf16 v[78:81], v[184:187], v[210:213], 0
	v_mfma_f32_16x16x32_bf16 v[26:29], v[192:195], v[200:203], 0
	v_mfma_f32_16x16x32_bf16 v[86:89], v[188:191], v[214:217], v[78:81]
	v_mfma_f32_16x16x32_bf16 v[18:21], v[192:195], v[210:213], 0
	v_mfma_f32_16x16x32_bf16 v[78:81], v[184:187], v[218:221], 0
	v_mfma_f32_16x16x32_bf16 v[10:13], v[192:195], v[218:221], 0
	v_mfma_f32_16x16x32_bf16 v[64:67], v[184:187], v[226:229], 0
	v_mfma_f32_16x16x32_bf16 v[2:5], v[192:195], v[226:229], 0
	v_mfma_f32_16x16x32_bf16 v[60:63], v[184:187], v[200:203], 0
	v_mfma_f32_16x16x32_bf16 v[26:29], v[196:199], v[204:207], v[26:29]
	v_mfma_f32_16x16x32_bf16 v[18:21], v[196:199], v[214:217], v[18:21]
	v_mfma_f32_16x16x32_bf16 v[82:85], v[188:191], v[222:225], v[78:81]
	v_mfma_f32_16x16x32_bf16 v[10:13], v[196:199], v[222:225], v[10:13]
	v_mfma_f32_16x16x32_bf16 v[64:67], v[188:191], v[230:233], v[64:67]
	v_mfma_f32_16x16x32_bf16 v[2:5], v[196:199], v[230:233], v[2:5]
	v_mfma_f32_16x16x32_bf16 v[60:63], v[188:191], v[204:207], v[60:63]
	s_branch .Lmid_155
.LBB0_155:
	ds_read_b128 v[56:59], v173
	ds_read_b128 v[60:63], v173 offset:1024
	ds_read_b128 v[176:179], v173 offset:2048
	ds_read_b128 v[180:183], v173 offset:3072
	ds_read_b128 v[184:187], v174
	ds_read_b128 v[188:191], v174 offset:1024
	ds_read_b128 v[192:195], v174 offset:2048
	ds_read_b128 v[196:199], v174 offset:3072
	s_add_u32 s53, s82, s84
	s_addc_u32 s56, s83, s85
	s_add_u32 s53, s53, 0x820000
	s_addc_u32 s56, s56, 0
	s_cmp_eq_u32 s84, 0x38e0000
	s_cselect_b32 s57, s18, s56
	s_cselect_b32 s56, s19, s53
	s_cselect_b32 s65, s30, s29
	s_cselect_b32 s64, s31, s28
	v_lshl_add_u64 v[64:65], v[54:55], 0, s[84:85]
	s_mov_b64 s[66:67], 0x414000
	v_lshl_add_u64 v[234:235], v[64:65], 0, s[66:67]
	s_add_i32 m0, s27, 0xc000
	s_mov_b64 s[66:67], 0x416000
	ds_read_b128 v[200:203], v175
	ds_read_b128 v[204:207], v175 offset:1024
	ds_read_b128 v[210:213], v175 offset:2048
	ds_read_b128 v[214:217], v175 offset:3072
	ds_read_b128 v[218:221], v175 offset:4096
	ds_read_b128 v[222:225], v175 offset:5120
	ds_read_b128 v[226:229], v175 offset:6144
	ds_read_b128 v[230:233], v175 offset:7168
	global_load_lds_dwordx4 v[234:235], off
	v_lshl_add_u64 v[64:65], v[64:65], 0, s[66:67]
	s_add_i32 m0, s27, 0xe000
	s_nop 0
	global_load_lds_dwordx4 v[64:65], off
	s_waitcnt vmcnt(8)
	s_waitcnt lgkmcnt(0)
	s_barrier
	s_waitcnt lgkmcnt(0)
	v_mfma_f32_16x16x32_bf16 v[98:101], v[56:59], v[200:203], v[98:101]
	v_mfma_f32_16x16x32_bf16 v[138:141], v[176:179], v[200:203], v[138:141]
	v_mfma_f32_16x16x32_bf16 v[70:73], v[56:59], v[210:213], v[70:73]
	v_mfma_f32_16x16x32_bf16 v[114:117], v[176:179], v[210:213], v[114:117]
	v_mfma_f32_16x16x32_bf16 v[46:49], v[56:59], v[218:221], v[46:49]
	v_mfma_f32_16x16x32_bf16 v[110:113], v[176:179], v[218:221], v[110:113]
	v_mfma_f32_16x16x32_bf16 v[38:41], v[56:59], v[226:229], v[38:41]
	v_mfma_f32_16x16x32_bf16 v[130:133], v[176:179], v[226:229], v[130:133]
	v_mfma_f32_16x16x32_bf16 v[98:101], v[60:63], v[204:207], v[98:101]
	v_mfma_f32_16x16x32_bf16 v[138:141], v[180:183], v[204:207], v[138:141]
	v_mfma_f32_16x16x32_bf16 v[70:73], v[60:63], v[214:217], v[70:73]
	v_mfma_f32_16x16x32_bf16 v[114:117], v[180:183], v[214:217], v[114:117]
	v_mfma_f32_16x16x32_bf16 v[46:49], v[60:63], v[222:225], v[46:49]
	v_mfma_f32_16x16x32_bf16 v[110:113], v[180:183], v[222:225], v[110:113]
	v_mfma_f32_16x16x32_bf16 v[38:41], v[60:63], v[230:233], v[38:41]
	v_mfma_f32_16x16x32_bf16 v[130:133], v[180:183], v[230:233], v[130:133]
	v_mfma_f32_16x16x32_bf16 v[134:137], v[184:187], v[200:203], v[134:137]
	v_mfma_f32_16x16x32_bf16 v[74:77], v[192:195], v[200:203], v[74:77]
	v_mfma_f32_16x16x32_bf16 v[106:109], v[184:187], v[210:213], v[106:109]
	v_mfma_f32_16x16x32_bf16 v[50:53], v[192:195], v[210:213], v[50:53]
	v_mfma_f32_16x16x32_bf16 v[102:105], v[184:187], v[218:221], v[102:105]
	v_mfma_f32_16x16x32_bf16 v[42:45], v[192:195], v[218:221], v[42:45]
	v_mfma_f32_16x16x32_bf16 v[126:129], v[184:187], v[226:229], v[126:129]
	v_mfma_f32_16x16x32_bf16 v[34:37], v[192:195], v[226:229], v[34:37]
	v_mfma_f32_16x16x32_bf16 v[134:137], v[188:191], v[204:207], v[134:137]
	v_mfma_f32_16x16x32_bf16 v[74:77], v[196:199], v[204:207], v[74:77]
	v_mfma_f32_16x16x32_bf16 v[106:109], v[188:191], v[214:217], v[106:109]
	v_mfma_f32_16x16x32_bf16 v[50:53], v[196:199], v[214:217], v[50:53]
	v_mfma_f32_16x16x32_bf16 v[102:105], v[188:191], v[222:225], v[102:105]
	v_mfma_f32_16x16x32_bf16 v[42:45], v[196:199], v[222:225], v[42:45]
	v_mfma_f32_16x16x32_bf16 v[126:129], v[188:191], v[230:233], v[126:129]
	v_mfma_f32_16x16x32_bf16 v[34:37], v[196:199], v[230:233], v[34:37]
	s_barrier
; #define G8_STA(bufoff, ptr, sg, h) G8_STAGE1(bufoff, (ptr) + (h) * ((sg) ? hA1 : hA0), ((sg) ? voffA1 : voffA0), ((sg) ? r64A1 : r64A0))
; #define G8_STB(bufoff, ptr, sg, h) G8_STAGE1(bufoff, (ptr) + (h) * ((sg) ? hB1 : hB0), ((sg) ? voffB1 : voffB0), ((sg) ? r64B1 : r64B0))
; #define G8_LDA(dst, b, h) do { _Pragma("unroll") for (int m = 0; m < 4; ++m) _Pragma("unroll") for (int k = 0; k < 2; ++k) dst[m][k] = *(const LAS bf16x8*)(lds + G8_SA(b, h) + aoff + m * 2048 + k * 1024); } while (0)
; #define G8_MMA(ai, bj, At, Bt) do { __builtin_amdgcn_s_setprio(1); _Pragma("unroll") for (int m = 0; m < 4; ++m) _Pragma("unroll") for (int n = 0; n < 2; ++n) _Pragma("unroll") for (int k = 0; k < 2; ++k) \
;         acc[ai][bj][m][n] = __builtin_amdgcn_mfma_f32_16x16x32_bf16(Bt[n][k], At[m][k], acc[ai][bj][m][n], 0, 0, 0); __builtin_amdgcn_s_setprio(0); } while (0)
; #define G8_WAIT_V(n) asm volatile("s_waitcnt vmcnt(" #n ")" ::: "memory")
; #define G8_WAIT_L(n) asm volatile("s_waitcnt lgkmcnt(" #n ")" ::: "memory")
; #define G8_BAR __builtin_amdgcn_s_barrier()
; #define G8_SCHED __builtin_amdgcn_sched_barrier(0)
; template <class P>
; __device__ __forceinline__ void gemm_phase(LAS unsigned char* lds, const P& p, const int G, const int c) {
;     ...
;             G8_LDA(At, 0, 1); G8_STB(G8_SB(0, 0), b2, sg2, 0); G8_STB(G8_SB(0, 1), b2, sg2, 1); G8_STA(G8_SA(0, 0), a2, sg2, 0);
;             G8_WAIT_V(8); G8_WAIT_L(0); G8_BAR; G8_MMA(1, 0, At, B0); G8_MMA(1, 1, At, B1); G8_BAR; G8_SCHED;
	ds_read_b128 v[200:203], v175 offset:16384
	ds_read_b128 v[204:207], v175 offset:17408
	ds_read_b128 v[210:213], v175 offset:18432
	ds_read_b128 v[214:217], v175 offset:19456
	ds_read_b128 v[218:221], v175 offset:20480
	ds_read_b128 v[222:225], v175 offset:21504
	ds_read_b128 v[226:229], v175 offset:22528
	ds_read_b128 v[230:233], v175 offset:23552
	s_add_i32 s53, s50, s2
	s_mov_b32 m0, s53
	v_lshl_add_u64 v[234:235], s[64:65], 0, v[142:143]
	global_load_lds_dwordx4 v[234:235], off
	v_lshl_add_u64 v[64:65], v[234:235], 0, s[4:5]
	s_add_i32 m0, s53, 0x2000
	s_add_i32 s53, s51, s2
	global_load_lds_dwordx4 v[64:65], off
	v_lshl_add_u64 v[64:65], v[234:235], 0, s[6:7]
	s_mov_b32 m0, s53
	v_lshl_add_u64 v[236:237], s[56:57], 0, v[144:145]
	global_load_lds_dwordx4 v[64:65], off
	v_lshl_add_u64 v[64:65], v[234:235], 0, s[8:9]
	s_add_i32 m0, s53, 0x2000
	s_nop 0
	global_load_lds_dwordx4 v[64:65], off
	s_mov_b32 m0, s27
	v_lshl_add_u64 v[64:65], v[236:237], 0, s[4:5]
	global_load_lds_dwordx4 v[236:237], off
	s_mov_b32 m0, s33
	s_nop 0
	global_load_lds_dwordx4 v[64:65], off
	s_waitcnt vmcnt(8)
	s_waitcnt lgkmcnt(0)
	s_barrier
	s_waitcnt lgkmcnt(0)
	v_mfma_f32_16x16x32_bf16 v[30:33], v[56:59], v[200:203], v[30:33]
	v_mfma_f32_16x16x32_bf16 v[122:125], v[176:179], v[200:203], v[122:125]
	v_mfma_f32_16x16x32_bf16 v[22:25], v[56:59], v[210:213], v[22:25]
	v_mfma_f32_16x16x32_bf16 v[94:97], v[176:179], v[210:213], v[94:97]
	v_mfma_f32_16x16x32_bf16 v[14:17], v[56:59], v[218:221], v[14:17]
	v_mfma_f32_16x16x32_bf16 v[90:93], v[176:179], v[218:221], v[90:93]
	v_mfma_f32_16x16x32_bf16 v[6:9], v[56:59], v[226:229], v[6:9]
	v_mfma_f32_16x16x32_bf16 v[30:33], v[60:63], v[204:207], v[30:33]
	v_mfma_f32_16x16x32_bf16 v[122:125], v[180:183], v[204:207], v[122:125]
	v_mfma_f32_16x16x32_bf16 v[22:25], v[60:63], v[214:217], v[22:25]
	v_mfma_f32_16x16x32_bf16 v[94:97], v[180:183], v[214:217], v[94:97]
	v_mfma_f32_16x16x32_bf16 v[14:17], v[60:63], v[222:225], v[14:17]
	v_mfma_f32_16x16x32_bf16 v[90:93], v[180:183], v[222:225], v[90:93]
	v_mfma_f32_16x16x32_bf16 v[6:9], v[60:63], v[230:233], v[6:9]
	v_mfma_f32_16x16x32_bf16 v[56:59], v[176:179], v[226:229], v[78:81]
	v_mfma_f32_16x16x32_bf16 v[56:59], v[180:183], v[230:233], v[56:59]
	v_mfma_f32_16x16x32_bf16 v[78:81], v[184:187], v[210:213], v[86:89]
	v_mfma_f32_16x16x32_bf16 v[26:29], v[192:195], v[200:203], v[26:29]
	v_mfma_f32_16x16x32_bf16 v[86:89], v[188:191], v[214:217], v[78:81]
	v_mfma_f32_16x16x32_bf16 v[18:21], v[192:195], v[210:213], v[18:21]
	v_mfma_f32_16x16x32_bf16 v[78:81], v[184:187], v[218:221], v[82:85]
	v_mfma_f32_16x16x32_bf16 v[10:13], v[192:195], v[218:221], v[10:13]
	v_mfma_f32_16x16x32_bf16 v[64:67], v[184:187], v[226:229], v[66:69]
	v_mfma_f32_16x16x32_bf16 v[2:5], v[192:195], v[226:229], v[2:5]
	v_mfma_f32_16x16x32_bf16 v[60:63], v[184:187], v[200:203], v[118:121]
	v_mfma_f32_16x16x32_bf16 v[26:29], v[196:199], v[204:207], v[26:29]
	v_mfma_f32_16x16x32_bf16 v[18:21], v[196:199], v[214:217], v[18:21]
	v_mfma_f32_16x16x32_bf16 v[82:85], v[188:191], v[222:225], v[78:81]
	v_mfma_f32_16x16x32_bf16 v[10:13], v[196:199], v[222:225], v[10:13]
	v_mfma_f32_16x16x32_bf16 v[64:67], v[188:191], v[230:233], v[64:67]
	v_mfma_f32_16x16x32_bf16 v[2:5], v[196:199], v[230:233], v[2:5]
	v_mfma_f32_16x16x32_bf16 v[60:63], v[188:191], v[204:207], v[60:63]
; #define G8_STA(bufoff, ptr, sg, h) G8_STAGE1(bufoff, (ptr) + (h) * ((sg) ? hA1 : hA0), ((sg) ? voffA1 : voffA0), ((sg) ? r64A1 : r64A0))
; #define G8_STB(bufoff, ptr, sg, h) G8_STAGE1(bufoff, (ptr) + (h) * ((sg) ? hB1 : hB0), ((sg) ? voffB1 : voffB0), ((sg) ? r64B1 : r64B0))
; #define G8_LDA(dst, b, h) do { _Pragma("unroll") for (int m = 0; m < 4; ++m) _Pragma("unroll") for (int k = 0; k < 2; ++k) dst[m][k] = *(const LAS bf16x8*)(lds + G8_SA(b, h) + aoff + m * 2048 + k * 1024); } while (0)
; #define G8_LDB(dst, b, h) do { _Pragma("unroll") for (int n = 0; n < 2; ++n) _Pragma("unroll") for (int k = 0; k < 2; ++k) dst[n][k] = *(const LAS bf16x8*)(lds + G8_SB(b, h) + boff + n * 2048 + k * 1024); } while (0)
; #define G8_MMA(ai, bj, At, Bt) do { __builtin_amdgcn_s_setprio(1); _Pragma("unroll") for (int m = 0; m < 4; ++m) _Pragma("unroll") for (int n = 0; n < 2; ++n) _Pragma("unroll") for (int k = 0; k < 2; ++k) \
;         acc[ai][bj][m][n] = __builtin_amdgcn_mfma_f32_16x16x32_bf16(Bt[n][k], At[m][k], acc[ai][bj][m][n], 0, 0, 0); __builtin_amdgcn_s_setprio(0); } while (0)
; #define G8_WAIT_V(n) asm volatile("s_waitcnt vmcnt(" #n ")" ::: "memory")
; #define G8_WAIT_L(n) asm volatile("s_waitcnt lgkmcnt(" #n ")" ::: "memory")
; #define G8_BAR __builtin_amdgcn_s_barrier()
; #define G8_SCHED __builtin_amdgcn_sched_barrier(0)
; template <class P>
; __device__ __forceinline__ void gemm_phase(LAS unsigned char* lds, const P& p, const int G, const int c) {
;     ...
;             G8_LDB(B0, 1, 0); G8_LDB(B1, 1, 1); G8_SCHED; G8_LDA(At, 1, 0); G8_STA(G8_SA(0, 1), a2, sg2, 1);
;             G8_WAIT_V(8); G8_WAIT_L(0); G8_BAR; G8_MMA(0, 0, At, B0); G8_MMA(0, 1, At, B1); G8_BAR; G8_SCHED;
;             G8_LDA(At, 1, 1); G8_STB(G8_SB(1, 0), b3, sg2, 0); G8_STB(G8_SB(1, 1), b3, sg2, 1); G8_STA(G8_SA(1, 0), a3, sg2, 0);
;             G8_WAIT_V(8); G8_WAIT_L(0); G8_BAR; G8_MMA(1, 0, At, B0); G8_MMA(1, 1, At, B1); G8_BAR; G8_SCHED;
;         }
.Lmid_155:
	s_barrier
	s_add_i32 s53, 0, 0x18000
	v_add_u32_e32 v68, s53, v152
	s_add_i32 s56, 0, 0x1c000
	ds_read_b128 v[78:81], v68
	ds_read_b128 v[118:121], v68 offset:1024
	ds_read_b128 v[176:179], v68 offset:2048
	ds_read_b128 v[180:183], v68 offset:3072
	v_add_u32_e32 v68, s56, v152
	ds_read_b128 v[184:187], v68
	ds_read_b128 v[188:191], v68 offset:1024
	ds_read_b128 v[192:195], v68 offset:2048
	ds_read_b128 v[196:199], v68 offset:3072
	s_mov_b32 m0, s34
	v_lshl_add_u64 v[68:69], v[236:237], 0, s[6:7]
	ds_read_b128 v[200:203], v175 offset:32768
	ds_read_b128 v[204:207], v175 offset:33792
	ds_read_b128 v[210:213], v175 offset:34816
	ds_read_b128 v[214:217], v175 offset:35840
	ds_read_b128 v[218:221], v175 offset:36864
	ds_read_b128 v[222:225], v175 offset:37888
	ds_read_b128 v[226:229], v175 offset:38912
	ds_read_b128 v[230:233], v175 offset:39936
	global_load_lds_dwordx4 v[68:69], off
	v_lshl_add_u64 v[68:69], v[236:237], 0, s[8:9]
	s_mov_b32 m0, s35
	s_nop 0
	global_load_lds_dwordx4 v[68:69], off
	s_waitcnt vmcnt(8)
	s_waitcnt lgkmcnt(0)
	s_barrier
	s_waitcnt lgkmcnt(0)
	v_mfma_f32_16x16x32_bf16 v[98:101], v[78:81], v[200:203], v[98:101]
	v_mfma_f32_16x16x32_bf16 v[138:141], v[176:179], v[200:203], v[138:141]
	v_mfma_f32_16x16x32_bf16 v[68:71], v[78:81], v[210:213], v[70:73]
	v_mfma_f32_16x16x32_bf16 v[114:117], v[176:179], v[210:213], v[114:117]
	v_mfma_f32_16x16x32_bf16 v[46:49], v[78:81], v[218:221], v[46:49]
	v_mfma_f32_16x16x32_bf16 v[110:113], v[176:179], v[218:221], v[110:113]
	v_mfma_f32_16x16x32_bf16 v[38:41], v[78:81], v[226:229], v[38:41]
	v_mfma_f32_16x16x32_bf16 v[130:133], v[176:179], v[226:229], v[130:133]
	v_mfma_f32_16x16x32_bf16 v[98:101], v[118:121], v[204:207], v[98:101]
	v_mfma_f32_16x16x32_bf16 v[138:141], v[180:183], v[204:207], v[138:141]
	v_mfma_f32_16x16x32_bf16 v[70:73], v[118:121], v[214:217], v[68:71]
	v_mfma_f32_16x16x32_bf16 v[114:117], v[180:183], v[214:217], v[114:117]
	v_mfma_f32_16x16x32_bf16 v[46:49], v[118:121], v[222:225], v[46:49]
	v_mfma_f32_16x16x32_bf16 v[110:113], v[180:183], v[222:225], v[110:113]
	v_mfma_f32_16x16x32_bf16 v[38:41], v[118:121], v[230:233], v[38:41]
	v_mfma_f32_16x16x32_bf16 v[130:133], v[180:183], v[230:233], v[130:133]
	v_mfma_f32_16x16x32_bf16 v[134:137], v[184:187], v[200:203], v[134:137]
	v_mfma_f32_16x16x32_bf16 v[74:77], v[192:195], v[200:203], v[74:77]
	v_mfma_f32_16x16x32_bf16 v[106:109], v[184:187], v[210:213], v[106:109]
	v_mfma_f32_16x16x32_bf16 v[50:53], v[192:195], v[210:213], v[50:53]
	v_mfma_f32_16x16x32_bf16 v[102:105], v[184:187], v[218:221], v[102:105]
	v_mfma_f32_16x16x32_bf16 v[42:45], v[192:195], v[218:221], v[42:45]
	v_mfma_f32_16x16x32_bf16 v[126:129], v[184:187], v[226:229], v[126:129]
	v_mfma_f32_16x16x32_bf16 v[34:37], v[192:195], v[226:229], v[34:37]
	v_mfma_f32_16x16x32_bf16 v[134:137], v[188:191], v[204:207], v[134:137]
	v_mfma_f32_16x16x32_bf16 v[74:77], v[196:199], v[204:207], v[74:77]
	v_mfma_f32_16x16x32_bf16 v[106:109], v[188:191], v[214:217], v[106:109]
	v_mfma_f32_16x16x32_bf16 v[50:53], v[196:199], v[214:217], v[50:53]
	v_mfma_f32_16x16x32_bf16 v[102:105], v[188:191], v[222:225], v[102:105]
	v_mfma_f32_16x16x32_bf16 v[42:45], v[196:199], v[222:225], v[42:45]
	v_mfma_f32_16x16x32_bf16 v[126:129], v[188:191], v[230:233], v[126:129]
	v_mfma_f32_16x16x32_bf16 v[34:37], v[196:199], v[230:233], v[34:37]
	s_barrier
	ds_read_b128 v[200:203], v175 offset:49152
	ds_read_b128 v[204:207], v175 offset:50176
	ds_read_b128 v[210:213], v175 offset:51200
	ds_read_b128 v[214:217], v175 offset:52224
	ds_read_b128 v[218:221], v175 offset:53248
	ds_read_b128 v[222:225], v175 offset:54272
	ds_read_b128 v[226:229], v175 offset:55296
	ds_read_b128 v[230:233], v175 offset:56320
	s_add_i32 s53, s53, s2
	s_mov_b32 m0, s53
	v_lshl_add_u64 v[68:69], v[234:235], 0, s[12:13]
	global_load_lds_dwordx4 v[68:69], off
	v_lshl_add_u64 v[68:69], v[234:235], 0, s[14:15]
	s_add_i32 m0, s53, 0x2000
	s_add_i32 s53, s56, s2
	global_load_lds_dwordx4 v[68:69], off
	v_lshl_add_u64 v[68:69], v[234:235], 0, s[22:23]
	s_mov_b32 m0, s53
	s_nop 0
	global_load_lds_dwordx4 v[68:69], off
	v_lshl_add_u64 v[68:69], v[234:235], 0, s[36:37]
	s_add_i32 m0, s53, 0x2000
	s_nop 0
	global_load_lds_dwordx4 v[68:69], off
	v_lshl_add_u64 v[68:69], v[236:237], 0, s[16:17]
	s_mov_b32 m0, s47
	s_nop 0
	global_load_lds_dwordx4 v[68:69], off
	v_lshl_add_u64 v[68:69], v[236:237], 0, s[20:21]
	s_mov_b32 m0, s48
	s_nop 0
	global_load_lds_dwordx4 v[68:69], off
	s_waitcnt vmcnt(8)
	s_waitcnt lgkmcnt(0)
	s_barrier
	s_waitcnt lgkmcnt(0)
	v_mfma_f32_16x16x32_bf16 v[30:33], v[78:81], v[200:203], v[30:33]
	v_mfma_f32_16x16x32_bf16 v[122:125], v[176:179], v[200:203], v[122:125]
	v_mfma_f32_16x16x32_bf16 v[22:25], v[78:81], v[210:213], v[22:25]
	v_mfma_f32_16x16x32_bf16 v[94:97], v[176:179], v[210:213], v[94:97]
	s_add_i32 s52, s52, 2
	v_mfma_f32_16x16x32_bf16 v[14:17], v[78:81], v[218:221], v[14:17]
	s_add_u32 s28, s28, 0x200000
	v_mfma_f32_16x16x32_bf16 v[90:93], v[176:179], v[218:221], v[90:93]
	s_addc_u32 s29, s29, 0
	v_mfma_f32_16x16x32_bf16 v[6:9], v[78:81], v[226:229], v[6:9]
	s_add_u32 s84, s84, 0x820000
	v_mfma_f32_16x16x32_bf16 v[56:59], v[176:179], v[226:229], v[56:59]
	s_addc_u32 s85, s85, 0
	v_mfma_f32_16x16x32_bf16 v[30:33], v[118:121], v[204:207], v[30:33]
	s_cmp_gt_u32 s52, 13
	v_mfma_f32_16x16x32_bf16 v[122:125], v[180:183], v[204:207], v[122:125]
	v_mfma_f32_16x16x32_bf16 v[22:25], v[118:121], v[214:217], v[22:25]
	v_mfma_f32_16x16x32_bf16 v[94:97], v[180:183], v[214:217], v[94:97]
	v_mfma_f32_16x16x32_bf16 v[14:17], v[118:121], v[222:225], v[14:17]
	v_mfma_f32_16x16x32_bf16 v[90:93], v[180:183], v[222:225], v[90:93]
	v_mfma_f32_16x16x32_bf16 v[6:9], v[118:121], v[230:233], v[6:9]
	v_mfma_f32_16x16x32_bf16 v[78:81], v[180:183], v[230:233], v[56:59]
	v_mfma_f32_16x16x32_bf16 v[56:59], v[184:187], v[200:203], v[60:63]
	v_mfma_f32_16x16x32_bf16 v[118:121], v[188:191], v[204:207], v[56:59]
	v_mfma_f32_16x16x32_bf16 v[56:59], v[184:187], v[210:213], v[86:89]
	v_mfma_f32_16x16x32_bf16 v[86:89], v[188:191], v[214:217], v[56:59]
	v_mfma_f32_16x16x32_bf16 v[56:59], v[184:187], v[218:221], v[82:85]
	v_mfma_f32_16x16x32_bf16 v[26:29], v[192:195], v[200:203], v[26:29]
	v_mfma_f32_16x16x32_bf16 v[18:21], v[192:195], v[210:213], v[18:21]
	v_mfma_f32_16x16x32_bf16 v[82:85], v[188:191], v[222:225], v[56:59]
	v_mfma_f32_16x16x32_bf16 v[10:13], v[192:195], v[218:221], v[10:13]
	v_mfma_f32_16x16x32_bf16 v[56:59], v[184:187], v[226:229], v[64:67]
	v_mfma_f32_16x16x32_bf16 v[2:5], v[192:195], v[226:229], v[2:5]
	v_mfma_f32_16x16x32_bf16 v[26:29], v[196:199], v[204:207], v[26:29]
	v_mfma_f32_16x16x32_bf16 v[18:21], v[196:199], v[214:217], v[18:21]
	v_mfma_f32_16x16x32_bf16 v[10:13], v[196:199], v[222:225], v[10:13]
	v_mfma_f32_16x16x32_bf16 v[66:69], v[188:191], v[230:233], v[56:59]
	v_mfma_f32_16x16x32_bf16 v[2:5], v[196:199], v[230:233], v[2:5]
	s_barrier
	s_cbranch_scc0 .LBB0_155
	s_and_b64 vcc, exec, s[38:39]
	s_cbranch_vccz .LBB0_158
	s_barrier

; #define G8_STA(bufoff, ptr, sg, h) G8_STAGE1(bufoff, (ptr) + (h) * ((sg) ? hA1 : hA0), ((sg) ? voffA1 : voffA0), ((sg) ? r64A1 : r64A0))
; #define G8_STB(bufoff, ptr, sg, h) G8_STAGE1(bufoff, (ptr) + (h) * ((sg) ? hB1 : hB0), ((sg) ? voffB1 : voffB0), ((sg) ? r64B1 : r64B0))
; #define G8_LDA(dst, b, h) do { _Pragma("unroll") for (int m = 0; m < 4; ++m) _Pragma("unroll") for (int k = 0; k < 2; ++k) dst[m][k] = *(const LAS bf16x8*)(lds + G8_SA(b, h) + aoff + m * 2048 + k * 1024); } while (0)
; #define G8_LDB(dst, b, h) do { _Pragma("unroll") for (int n = 0; n < 2; ++n) _Pragma("unroll") for (int k = 0; k < 2; ++k) dst[n][k] = *(const LAS bf16x8*)(lds + G8_SB(b, h) + boff + n * 2048 + k * 1024); } while (0)
; #define G8_MMA(ai, bj, At, Bt) do { __builtin_amdgcn_s_setprio(1); _Pragma("unroll") for (int m = 0; m < 4; ++m) _Pragma("unroll") for (int n = 0; n < 2; ++n) _Pragma("unroll") for (int k = 0; k < 2; ++k) \
;         acc[ai][bj][m][n] = __builtin_amdgcn_mfma_f32_16x16x32_bf16(Bt[n][k], At[m][k], acc[ai][bj][m][n], 0, 0, 0); __builtin_amdgcn_s_setprio(0); } while (0)
; #define G8_WAIT_V(n) asm volatile("s_waitcnt vmcnt(" #n ")" ::: "memory")
; #define G8_WAIT_L(n) asm volatile("s_waitcnt lgkmcnt(" #n ")" ::: "memory")
; #define G8_BAR __builtin_amdgcn_s_barrier()
; #define G8_SCHED __builtin_amdgcn_sched_barrier(0)
; template <class P>
; __device__ __forceinline__ void gemm_phase(LAS unsigned char* lds, const P& p, const int G, const int c) {
;     ...
;             G8_LDB(B0, 0, 0); G8_LDB(B1, 0, 1); G8_SCHED; G8_LDA(At, 0, 0); G8_STA(G8_SA(1, 1), a1, sg1, 1);
;             G8_WAIT_V(8); G8_WAIT_L(0); G8_BAR; G8_MMA(0, 0, At, B0); G8_MMA(0, 1, At, B1); G8_BAR; G8_SCHED;
;             G8_LDA(At, 0, 1); G8_STB(G8_SB(0, 0), b2, sg2, 0); G8_STB(G8_SB(0, 1), b2, sg2, 1); G8_STA(G8_SA(0, 0), a2, sg2, 0);
;             G8_WAIT_V(8); G8_WAIT_L(0); G8_BAR; G8_MMA(1, 0, At, B0); G8_MMA(1, 1, At, B1); G8_BAR; G8_SCHED;
.Lpeel_277:
	v_add_u32_e32 v144, s52, v1
	ds_read_b128 v[132:135], v144
	ds_read_b128 v[136:139], v144 offset:1024
	ds_read_b128 v[140:143], v144 offset:2048
	ds_read_b128 v[176:179], v144 offset:3072
	v_add_u32_e32 v144, s53, v1
	ds_read_b128 v[180:183], v144
	ds_read_b128 v[184:187], v144 offset:1024
	ds_read_b128 v[188:191], v144 offset:2048
	ds_read_b128 v[192:195], v144 offset:3072
	s_add_i32 s57, s57, 2
	s_and_b64 s[30:31], exec, s[30:31]
	s_cselect_b32 s31, s7, s49
	s_cselect_b32 s30, s18, s19
	v_lshl_add_u64 v[144:145], v[130:131], 0, s[76:77]
	s_mov_b64 s[64:65], 0x414000
	v_lshl_add_u64 v[230:231], v[144:145], 0, s[64:65]
	s_add_i32 m0, s27, 0xc000
	s_mov_b64 s[64:65], 0x416000
	ds_read_b128 v[196:199], v175
	ds_read_b128 v[200:203], v175 offset:1024
	ds_read_b128 v[204:207], v175 offset:2048
	ds_read_b128 v[210:213], v175 offset:3072
	ds_read_b128 v[214:217], v175 offset:4096
	ds_read_b128 v[218:221], v175 offset:5120
	ds_read_b128 v[222:225], v175 offset:6144
	ds_read_b128 v[226:229], v175 offset:7168
	global_load_lds_dwordx4 v[230:231], off
	v_lshl_add_u64 v[144:145], v[144:145], 0, s[64:65]
	s_add_i32 m0, s27, 0xe000
	s_nop 0
	global_load_lds_dwordx4 v[144:145], off
	s_waitcnt vmcnt(8)
	s_waitcnt lgkmcnt(0)
	s_barrier
	s_waitcnt lgkmcnt(0)
	v_mfma_f32_16x16x32_bf16 v[126:129], v[132:135], v[196:199], 0
	v_mfma_f32_16x16x32_bf16 v[122:125], v[140:143], v[196:199], 0
	v_mfma_f32_16x16x32_bf16 v[118:121], v[132:135], v[204:207], 0
	v_mfma_f32_16x16x32_bf16 v[114:117], v[140:143], v[204:207], 0
	v_mfma_f32_16x16x32_bf16 v[106:109], v[132:135], v[214:217], 0
	v_mfma_f32_16x16x32_bf16 v[98:101], v[140:143], v[214:217], 0
	v_mfma_f32_16x16x32_bf16 v[94:97], v[132:135], v[222:225], 0
	v_mfma_f32_16x16x32_bf16 v[86:89], v[140:143], v[222:225], 0
	v_mfma_f32_16x16x32_bf16 v[126:129], v[136:139], v[200:203], v[126:129]
	v_mfma_f32_16x16x32_bf16 v[122:125], v[176:179], v[200:203], v[122:125]
	v_mfma_f32_16x16x32_bf16 v[118:121], v[136:139], v[210:213], v[118:121]
	v_mfma_f32_16x16x32_bf16 v[114:117], v[176:179], v[210:213], v[114:117]
	v_mfma_f32_16x16x32_bf16 v[106:109], v[136:139], v[218:221], v[106:109]
	v_mfma_f32_16x16x32_bf16 v[98:101], v[176:179], v[218:221], v[98:101]
	v_mfma_f32_16x16x32_bf16 v[94:97], v[136:139], v[226:229], v[94:97]
	v_mfma_f32_16x16x32_bf16 v[86:89], v[176:179], v[226:229], v[86:89]
	v_mfma_f32_16x16x32_bf16 v[110:113], v[180:183], v[196:199], 0
	v_mfma_f32_16x16x32_bf16 v[102:105], v[188:191], v[196:199], 0
	v_mfma_f32_16x16x32_bf16 v[90:93], v[180:183], v[204:207], 0
	v_mfma_f32_16x16x32_bf16 v[82:85], v[188:191], v[204:207], 0
	v_mfma_f32_16x16x32_bf16 v[78:81], v[180:183], v[214:217], 0
	v_mfma_f32_16x16x32_bf16 v[74:77], v[188:191], v[214:217], 0
	v_mfma_f32_16x16x32_bf16 v[70:73], v[180:183], v[222:225], 0
	v_mfma_f32_16x16x32_bf16 v[66:69], v[188:191], v[222:225], 0
	v_mfma_f32_16x16x32_bf16 v[110:113], v[184:187], v[200:203], v[110:113]
	v_mfma_f32_16x16x32_bf16 v[102:105], v[192:195], v[200:203], v[102:105]
	v_mfma_f32_16x16x32_bf16 v[90:93], v[184:187], v[210:213], v[90:93]
	v_mfma_f32_16x16x32_bf16 v[82:85], v[192:195], v[210:213], v[82:85]
	v_mfma_f32_16x16x32_bf16 v[78:81], v[184:187], v[218:221], v[78:81]
	v_mfma_f32_16x16x32_bf16 v[74:77], v[192:195], v[218:221], v[74:77]
	v_mfma_f32_16x16x32_bf16 v[70:73], v[184:187], v[226:229], v[70:73]
	v_mfma_f32_16x16x32_bf16 v[66:69], v[192:195], v[226:229], v[66:69]
	s_barrier
	ds_read_b128 v[196:199], v175 offset:16384
	ds_read_b128 v[200:203], v175 offset:17408
	ds_read_b128 v[204:207], v175 offset:18432
	ds_read_b128 v[210:213], v175 offset:19456
	ds_read_b128 v[214:217], v175 offset:20480
	ds_read_b128 v[218:221], v175 offset:21504
	ds_read_b128 v[222:225], v175 offset:22528
	ds_read_b128 v[226:229], v175 offset:23552
	v_lshl_add_u64 v[144:145], s[30:31], 0, v[148:149]
	s_add_i32 s30, s52, s26
	s_mov_b32 m0, s30
	s_nop 0
	global_load_lds_dwordx4 v[144:145], off
	v_lshl_add_u64 v[230:231], v[144:145], 0, s[10:11]
	s_add_i32 m0, s30, 0x2000
	s_add_i32 s30, s53, s26
	global_load_lds_dwordx4 v[230:231], off
	v_lshl_add_u64 v[230:231], v[144:145], 0, s[12:13]
	s_mov_b32 m0, s30
	s_nop 0
	global_load_lds_dwordx4 v[230:231], off
	v_lshl_add_u64 v[230:231], v[144:145], 0, s[14:15]
	s_add_i32 m0, s30, 0x2000
	s_nop 0
	global_load_lds_dwordx4 v[230:231], off
	v_lshl_add_u64 v[230:231], s[28:29], 0, v[150:151]
	s_mov_b32 m0, s27
	v_lshl_add_u64 v[232:233], v[230:231], 0, s[10:11]
	global_load_lds_dwordx4 v[230:231], off
	s_mov_b32 m0, s33
	s_nop 0
	global_load_lds_dwordx4 v[232:233], off
	s_waitcnt vmcnt(8)
	s_waitcnt lgkmcnt(0)
	s_barrier
	s_waitcnt lgkmcnt(0)
	v_mfma_f32_16x16x32_bf16 v[62:65], v[132:135], v[196:199], 0
	v_mfma_f32_16x16x32_bf16 v[58:61], v[140:143], v[196:199], 0
	v_mfma_f32_16x16x32_bf16 v[54:57], v[132:135], v[204:207], 0
	v_mfma_f32_16x16x32_bf16 v[50:53], v[140:143], v[204:207], 0
	v_mfma_f32_16x16x32_bf16 v[46:49], v[132:135], v[214:217], 0
	v_mfma_f32_16x16x32_bf16 v[38:41], v[140:143], v[214:217], 0
	v_mfma_f32_16x16x32_bf16 v[30:33], v[132:135], v[222:225], 0
	v_mfma_f32_16x16x32_bf16 v[22:25], v[140:143], v[222:225], 0
	v_mfma_f32_16x16x32_bf16 v[62:65], v[136:139], v[200:203], v[62:65]
	v_mfma_f32_16x16x32_bf16 v[58:61], v[176:179], v[200:203], v[58:61]
	v_mfma_f32_16x16x32_bf16 v[54:57], v[136:139], v[210:213], v[54:57]
	v_mfma_f32_16x16x32_bf16 v[50:53], v[176:179], v[210:213], v[50:53]
	v_mfma_f32_16x16x32_bf16 v[46:49], v[136:139], v[218:221], v[46:49]
	v_mfma_f32_16x16x32_bf16 v[38:41], v[176:179], v[218:221], v[38:41]
	v_mfma_f32_16x16x32_bf16 v[30:33], v[136:139], v[226:229], v[30:33]
	v_mfma_f32_16x16x32_bf16 v[22:25], v[176:179], v[226:229], v[22:25]
	v_mfma_f32_16x16x32_bf16 v[42:45], v[180:183], v[196:199], 0
	v_mfma_f32_16x16x32_bf16 v[34:37], v[188:191], v[196:199], 0
	v_mfma_f32_16x16x32_bf16 v[26:29], v[180:183], v[204:207], 0
	v_mfma_f32_16x16x32_bf16 v[18:21], v[188:191], v[204:207], 0
	v_mfma_f32_16x16x32_bf16 v[14:17], v[180:183], v[214:217], 0
	v_mfma_f32_16x16x32_bf16 v[10:13], v[188:191], v[214:217], 0
	v_mfma_f32_16x16x32_bf16 v[6:9], v[180:183], v[222:225], 0
	v_mfma_f32_16x16x32_bf16 v[2:5], v[188:191], v[222:225], 0
	v_mfma_f32_16x16x32_bf16 v[42:45], v[184:187], v[200:203], v[42:45]
	v_mfma_f32_16x16x32_bf16 v[34:37], v[192:195], v[200:203], v[34:37]
	v_mfma_f32_16x16x32_bf16 v[26:29], v[184:187], v[210:213], v[26:29]
	v_mfma_f32_16x16x32_bf16 v[18:21], v[192:195], v[210:213], v[18:21]
	v_mfma_f32_16x16x32_bf16 v[14:17], v[184:187], v[218:221], v[14:17]
	v_mfma_f32_16x16x32_bf16 v[10:13], v[192:195], v[218:221], v[10:13]
	v_mfma_f32_16x16x32_bf16 v[6:9], v[184:187], v[226:229], v[6:9]
	v_mfma_f32_16x16x32_bf16 v[2:5], v[192:195], v[226:229], v[2:5]
	s_branch .Lmid_277
; #define G8_STA(bufoff, ptr, sg, h) G8_STAGE1(bufoff, (ptr) + (h) * ((sg) ? hA1 : hA0), ((sg) ? voffA1 : voffA0), ((sg) ? r64A1 : r64A0))
; #define G8_STB(bufoff, ptr, sg, h) G8_STAGE1(bufoff, (ptr) + (h) * ((sg) ? hB1 : hB0), ((sg) ? voffB1 : voffB0), ((sg) ? r64B1 : r64B0))
; #define G8_LDA(dst, b, h) do { _Pragma("unroll") for (int m = 0; m < 4; ++m) _Pragma("unroll") for (int k = 0; k < 2; ++k) dst[m][k] = *(const LAS bf16x8*)(lds + G8_SA(b, h) + aoff + m * 2048 + k * 1024); } while (0)
; #define G8_LDB(dst, b, h) do { _Pragma("unroll") for (int n = 0; n < 2; ++n) _Pragma("unroll") for (int k = 0; k < 2; ++k) dst[n][k] = *(const LAS bf16x8*)(lds + G8_SB(b, h) + boff + n * 2048 + k * 1024); } while (0)
; #define G8_MMA(ai, bj, At, Bt) do { __builtin_amdgcn_s_setprio(1); _Pragma("unroll") for (int m = 0; m < 4; ++m) _Pragma("unroll") for (int n = 0; n < 2; ++n) _Pragma("unroll") for (int k = 0; k < 2; ++k) \
;         acc[ai][bj][m][n] = __builtin_amdgcn_mfma_f32_16x16x32_bf16(Bt[n][k], At[m][k], acc[ai][bj][m][n], 0, 0, 0); __builtin_amdgcn_s_setprio(0); } while (0)
; #define G8_WAIT_V(n) asm volatile("s_waitcnt vmcnt(" #n ")" ::: "memory")
; #define G8_WAIT_L(n) asm volatile("s_waitcnt lgkmcnt(" #n ")" ::: "memory")
; #define G8_BAR __builtin_amdgcn_s_barrier()
; #define G8_SCHED __builtin_amdgcn_sched_barrier(0)
; template <class P>
; __device__ __forceinline__ void gemm_phase(LAS unsigned char* lds, const P& p, const int G, const int c) {
;     ...
;             G8_LDB(B0, 0, 0); G8_LDB(B1, 0, 1); G8_SCHED; G8_LDA(At, 0, 0); G8_STA(G8_SA(1, 1), a1, sg1, 1);
;             G8_WAIT_V(8); G8_WAIT_L(0); G8_BAR; G8_MMA(0, 0, At, B0); G8_MMA(0, 1, At, B1); G8_BAR; G8_SCHED;
;             G8_LDA(At, 0, 1); G8_STB(G8_SB(0, 0), b2, sg2, 0); G8_STB(G8_SB(0, 1), b2, sg2, 1); G8_STA(G8_SA(0, 0), a2, sg2, 0);
;             G8_WAIT_V(8); G8_WAIT_L(0); G8_BAR; G8_MMA(1, 0, At, B0); G8_MMA(1, 1, At, B1); G8_BAR; G8_SCHED;
.LBB0_277:
	v_add_u32_e32 v144, s52, v1
	ds_read_b128 v[132:135], v144
	ds_read_b128 v[136:139], v144 offset:1024
	ds_read_b128 v[140:143], v144 offset:2048
	ds_read_b128 v[176:179], v144 offset:3072
	v_add_u32_e32 v144, s53, v1
	ds_read_b128 v[180:183], v144
	ds_read_b128 v[184:187], v144 offset:1024
	ds_read_b128 v[188:191], v144 offset:2048
	ds_read_b128 v[192:195], v144 offset:3072
	s_add_i32 s57, s57, 2
	s_and_b64 s[30:31], exec, s[30:31]
	s_cselect_b32 s31, s7, s49
	s_cselect_b32 s30, s18, s19
	v_lshl_add_u64 v[144:145], v[130:131], 0, s[76:77]
	s_mov_b64 s[64:65], 0x414000
	v_lshl_add_u64 v[230:231], v[144:145], 0, s[64:65]
	s_add_i32 m0, s27, 0xc000
	s_mov_b64 s[64:65], 0x416000
	ds_read_b128 v[196:199], v175
	ds_read_b128 v[200:203], v175 offset:1024
	ds_read_b128 v[204:207], v175 offset:2048
	ds_read_b128 v[210:213], v175 offset:3072
	ds_read_b128 v[214:217], v175 offset:4096
	ds_read_b128 v[218:221], v175 offset:5120
	ds_read_b128 v[222:225], v175 offset:6144
	ds_read_b128 v[226:229], v175 offset:7168
	global_load_lds_dwordx4 v[230:231], off
	v_lshl_add_u64 v[144:145], v[144:145], 0, s[64:65]
	s_add_i32 m0, s27, 0xe000
	s_nop 0
	global_load_lds_dwordx4 v[144:145], off
	s_waitcnt vmcnt(8)
	s_waitcnt lgkmcnt(0)
	s_barrier
	s_waitcnt lgkmcnt(0)
	v_mfma_f32_16x16x32_bf16 v[126:129], v[132:135], v[196:199], v[126:129]
	v_mfma_f32_16x16x32_bf16 v[122:125], v[140:143], v[196:199], v[122:125]
	v_mfma_f32_16x16x32_bf16 v[118:121], v[132:135], v[204:207], v[118:121]
	v_mfma_f32_16x16x32_bf16 v[114:117], v[140:143], v[204:207], v[114:117]
	v_mfma_f32_16x16x32_bf16 v[106:109], v[132:135], v[214:217], v[106:109]
	v_mfma_f32_16x16x32_bf16 v[98:101], v[140:143], v[214:217], v[98:101]
	v_mfma_f32_16x16x32_bf16 v[94:97], v[132:135], v[222:225], v[94:97]
	v_mfma_f32_16x16x32_bf16 v[86:89], v[140:143], v[222:225], v[86:89]
	v_mfma_f32_16x16x32_bf16 v[126:129], v[136:139], v[200:203], v[126:129]
	v_mfma_f32_16x16x32_bf16 v[122:125], v[176:179], v[200:203], v[122:125]
	v_mfma_f32_16x16x32_bf16 v[118:121], v[136:139], v[210:213], v[118:121]
	v_mfma_f32_16x16x32_bf16 v[114:117], v[176:179], v[210:213], v[114:117]
	v_mfma_f32_16x16x32_bf16 v[106:109], v[136:139], v[218:221], v[106:109]
	v_mfma_f32_16x16x32_bf16 v[98:101], v[176:179], v[218:221], v[98:101]
	v_mfma_f32_16x16x32_bf16 v[94:97], v[136:139], v[226:229], v[94:97]
	v_mfma_f32_16x16x32_bf16 v[86:89], v[176:179], v[226:229], v[86:89]
	v_mfma_f32_16x16x32_bf16 v[110:113], v[180:183], v[196:199], v[110:113]
	v_mfma_f32_16x16x32_bf16 v[102:105], v[188:191], v[196:199], v[102:105]
	v_mfma_f32_16x16x32_bf16 v[90:93], v[180:183], v[204:207], v[90:93]
	v_mfma_f32_16x16x32_bf16 v[82:85], v[188:191], v[204:207], v[82:85]
	v_mfma_f32_16x16x32_bf16 v[78:81], v[180:183], v[214:217], v[78:81]
	v_mfma_f32_16x16x32_bf16 v[74:77], v[188:191], v[214:217], v[74:77]
	v_mfma_f32_16x16x32_bf16 v[70:73], v[180:183], v[222:225], v[70:73]
	v_mfma_f32_16x16x32_bf16 v[66:69], v[188:191], v[222:225], v[66:69]
	v_mfma_f32_16x16x32_bf16 v[110:113], v[184:187], v[200:203], v[110:113]
	v_mfma_f32_16x16x32_bf16 v[102:105], v[192:195], v[200:203], v[102:105]
	v_mfma_f32_16x16x32_bf16 v[90:93], v[184:187], v[210:213], v[90:93]
	v_mfma_f32_16x16x32_bf16 v[82:85], v[192:195], v[210:213], v[82:85]
	v_mfma_f32_16x16x32_bf16 v[78:81], v[184:187], v[218:221], v[78:81]
	v_mfma_f32_16x16x32_bf16 v[74:77], v[192:195], v[218:221], v[74:77]
	v_mfma_f32_16x16x32_bf16 v[70:73], v[184:187], v[226:229], v[70:73]
	v_mfma_f32_16x16x32_bf16 v[66:69], v[192:195], v[226:229], v[66:69]
	s_barrier
	ds_read_b128 v[196:199], v175 offset:16384
	ds_read_b128 v[200:203], v175 offset:17408
	ds_read_b128 v[204:207], v175 offset:18432
	ds_read_b128 v[210:213], v175 offset:19456
	ds_read_b128 v[214:217], v175 offset:20480
	ds_read_b128 v[218:221], v175 offset:21504
	ds_read_b128 v[222:225], v175 offset:22528
	ds_read_b128 v[226:229], v175 offset:23552
	v_lshl_add_u64 v[144:145], s[30:31], 0, v[148:149]
	s_add_i32 s30, s52, s26
	s_mov_b32 m0, s30
	s_nop 0
	global_load_lds_dwordx4 v[144:145], off
	v_lshl_add_u64 v[230:231], v[144:145], 0, s[10:11]
	s_add_i32 m0, s30, 0x2000
	s_add_i32 s30, s53, s26
	global_load_lds_dwordx4 v[230:231], off
	v_lshl_add_u64 v[230:231], v[144:145], 0, s[12:13]
	s_mov_b32 m0, s30
	s_nop 0
	global_load_lds_dwordx4 v[230:231], off
	v_lshl_add_u64 v[230:231], v[144:145], 0, s[14:15]
	s_add_i32 m0, s30, 0x2000
	s_nop 0
	global_load_lds_dwordx4 v[230:231], off
	v_lshl_add_u64 v[230:231], s[28:29], 0, v[150:151]
	s_mov_b32 m0, s27
	v_lshl_add_u64 v[232:233], v[230:231], 0, s[10:11]
	global_load_lds_dwordx4 v[230:231], off
	s_mov_b32 m0, s33
	s_nop 0
	global_load_lds_dwordx4 v[232:233], off
	s_waitcnt vmcnt(8)
	s_waitcnt lgkmcnt(0)
	s_barrier
	s_waitcnt lgkmcnt(0)
	v_mfma_f32_16x16x32_bf16 v[62:65], v[132:135], v[196:199], v[62:65]
	v_mfma_f32_16x16x32_bf16 v[58:61], v[140:143], v[196:199], v[58:61]
	v_mfma_f32_16x16x32_bf16 v[54:57], v[132:135], v[204:207], v[54:57]
	v_mfma_f32_16x16x32_bf16 v[50:53], v[140:143], v[204:207], v[50:53]
	v_mfma_f32_16x16x32_bf16 v[46:49], v[132:135], v[214:217], v[46:49]
	v_mfma_f32_16x16x32_bf16 v[38:41], v[140:143], v[214:217], v[38:41]
	v_mfma_f32_16x16x32_bf16 v[30:33], v[132:135], v[222:225], v[30:33]
	v_mfma_f32_16x16x32_bf16 v[22:25], v[140:143], v[222:225], v[22:25]
	v_mfma_f32_16x16x32_bf16 v[62:65], v[136:139], v[200:203], v[62:65]
	v_mfma_f32_16x16x32_bf16 v[58:61], v[176:179], v[200:203], v[58:61]
	v_mfma_f32_16x16x32_bf16 v[54:57], v[136:139], v[210:213], v[54:57]
	v_mfma_f32_16x16x32_bf16 v[50:53], v[176:179], v[210:213], v[50:53]
	v_mfma_f32_16x16x32_bf16 v[46:49], v[136:139], v[218:221], v[46:49]
	v_mfma_f32_16x16x32_bf16 v[38:41], v[176:179], v[218:221], v[38:41]
	v_mfma_f32_16x16x32_bf16 v[30:33], v[136:139], v[226:229], v[30:33]
	v_mfma_f32_16x16x32_bf16 v[22:25], v[176:179], v[226:229], v[22:25]
	v_mfma_f32_16x16x32_bf16 v[42:45], v[180:183], v[196:199], v[42:45]
	v_mfma_f32_16x16x32_bf16 v[34:37], v[188:191], v[196:199], v[34:37]
	v_mfma_f32_16x16x32_bf16 v[26:29], v[180:183], v[204:207], v[26:29]
	v_mfma_f32_16x16x32_bf16 v[18:21], v[188:191], v[204:207], v[18:21]
	v_mfma_f32_16x16x32_bf16 v[14:17], v[180:183], v[214:217], v[14:17]
	v_mfma_f32_16x16x32_bf16 v[10:13], v[188:191], v[214:217], v[10:13]
	v_mfma_f32_16x16x32_bf16 v[6:9], v[180:183], v[222:225], v[6:9]
	v_mfma_f32_16x16x32_bf16 v[2:5], v[188:191], v[222:225], v[2:5]
	v_mfma_f32_16x16x32_bf16 v[42:45], v[184:187], v[200:203], v[42:45]
	v_mfma_f32_16x16x32_bf16 v[34:37], v[192:195], v[200:203], v[34:37]
	v_mfma_f32_16x16x32_bf16 v[26:29], v[184:187], v[210:213], v[26:29]
	v_mfma_f32_16x16x32_bf16 v[18:21], v[192:195], v[210:213], v[18:21]
	v_mfma_f32_16x16x32_bf16 v[14:17], v[184:187], v[218:221], v[14:17]
	v_mfma_f32_16x16x32_bf16 v[10:13], v[192:195], v[218:221], v[10:13]
	v_mfma_f32_16x16x32_bf16 v[6:9], v[184:187], v[226:229], v[6:9]
	v_mfma_f32_16x16x32_bf16 v[2:5], v[192:195], v[226:229], v[2:5]
; #define G8_STA(bufoff, ptr, sg, h) G8_STAGE1(bufoff, (ptr) + (h) * ((sg) ? hA1 : hA0), ((sg) ? voffA1 : voffA0), ((sg) ? r64A1 : r64A0))
; #define G8_STB(bufoff, ptr, sg, h) G8_STAGE1(bufoff, (ptr) + (h) * ((sg) ? hB1 : hB0), ((sg) ? voffB1 : voffB0), ((sg) ? r64B1 : r64B0))
; #define G8_LDA(dst, b, h) do { _Pragma("unroll") for (int m = 0; m < 4; ++m) _Pragma("unroll") for (int k = 0; k < 2; ++k) dst[m][k] = *(const LAS bf16x8*)(lds + G8_SA(b, h) + aoff + m * 2048 + k * 1024); } while (0)
; #define G8_LDB(dst, b, h) do { _Pragma("unroll") for (int n = 0; n < 2; ++n) _Pragma("unroll") for (int k = 0; k < 2; ++k) dst[n][k] = *(const LAS bf16x8*)(lds + G8_SB(b, h) + boff + n * 2048 + k * 1024); } while (0)
; #define G8_MMA(ai, bj, At, Bt) do { __builtin_amdgcn_s_setprio(1); _Pragma("unroll") for (int m = 0; m < 4; ++m) _Pragma("unroll") for (int n = 0; n < 2; ++n) _Pragma("unroll") for (int k = 0; k < 2; ++k) \
;         acc[ai][bj][m][n] = __builtin_amdgcn_mfma_f32_16x16x32_bf16(Bt[n][k], At[m][k], acc[ai][bj][m][n], 0, 0, 0); __builtin_amdgcn_s_setprio(0); } while (0)
; #define G8_WAIT_V(n) asm volatile("s_waitcnt vmcnt(" #n ")" ::: "memory")
; #define G8_WAIT_L(n) asm volatile("s_waitcnt lgkmcnt(" #n ")" ::: "memory")
; #define G8_BAR __builtin_amdgcn_s_barrier()
; #define G8_SCHED __builtin_amdgcn_sched_barrier(0)
; template <class P>
; __device__ __forceinline__ void gemm_phase(LAS unsigned char* lds, const P& p, const int G, const int c) {
;     ...
;             G8_LDB(B0, 1, 0); G8_LDB(B1, 1, 1); G8_SCHED; G8_LDA(At, 1, 0); G8_STA(G8_SA(0, 1), a2, sg2, 1);
;             G8_WAIT_V(8); G8_WAIT_L(0); G8_BAR; G8_MMA(0, 0, At, B0); G8_MMA(0, 1, At, B1); G8_BAR; G8_SCHED;
;             G8_LDA(At, 1, 1); G8_STB(G8_SB(1, 0), b3, sg2, 0); G8_STB(G8_SB(1, 1), b3, sg2, 1); G8_STA(G8_SA(1, 0), a3, sg2, 0);
;             G8_WAIT_V(8); G8_WAIT_L(0); G8_BAR; G8_MMA(1, 0, At, B0); G8_MMA(1, 1, At, B1); G8_BAR; G8_SCHED;
;         }
.Lmid_277:
	s_barrier
	s_add_i32 s28, 0, 0x18000
	s_add_i32 s29, 0, 0x1c000
	v_add_u32_e32 v176, s28, v1
	v_add_u32_e32 v192, s29, v1
	ds_read_b128 v[132:135], v176
	ds_read_b128 v[136:139], v176 offset:1024
	ds_read_b128 v[140:143], v176 offset:2048
	ds_read_b128 v[176:179], v176 offset:3072
	ds_read_b128 v[180:183], v192
	ds_read_b128 v[184:187], v192 offset:1024
	ds_read_b128 v[188:191], v192 offset:2048
	ds_read_b128 v[192:195], v192 offset:3072
	s_mov_b32 m0, s34
	v_lshl_add_u64 v[232:233], v[230:231], 0, s[12:13]
	ds_read_b128 v[196:199], v175 offset:32768
	ds_read_b128 v[200:203], v175 offset:33792
	ds_read_b128 v[204:207], v175 offset:34816
	ds_read_b128 v[210:213], v175 offset:35840
	ds_read_b128 v[214:217], v175 offset:36864
	ds_read_b128 v[218:221], v175 offset:37888
	ds_read_b128 v[222:225], v175 offset:38912
	ds_read_b128 v[226:229], v175 offset:39936
	global_load_lds_dwordx4 v[232:233], off
	v_lshl_add_u64 v[232:233], v[230:231], 0, s[14:15]
	s_mov_b32 m0, s35
	s_nop 0
	global_load_lds_dwordx4 v[232:233], off
	s_waitcnt vmcnt(8)
	s_waitcnt lgkmcnt(0)
	s_barrier
	s_waitcnt lgkmcnt(0)
	v_mfma_f32_16x16x32_bf16 v[126:129], v[132:135], v[196:199], v[126:129]
	v_mfma_f32_16x16x32_bf16 v[122:125], v[140:143], v[196:199], v[122:125]
	v_mfma_f32_16x16x32_bf16 v[118:121], v[132:135], v[204:207], v[118:121]
	v_mfma_f32_16x16x32_bf16 v[114:117], v[140:143], v[204:207], v[114:117]
	v_mfma_f32_16x16x32_bf16 v[106:109], v[132:135], v[214:217], v[106:109]
	v_mfma_f32_16x16x32_bf16 v[98:101], v[140:143], v[214:217], v[98:101]
	v_mfma_f32_16x16x32_bf16 v[94:97], v[132:135], v[222:225], v[94:97]
	v_mfma_f32_16x16x32_bf16 v[86:89], v[140:143], v[222:225], v[86:89]
	v_mfma_f32_16x16x32_bf16 v[126:129], v[136:139], v[200:203], v[126:129]
	v_mfma_f32_16x16x32_bf16 v[122:125], v[176:179], v[200:203], v[122:125]
	v_mfma_f32_16x16x32_bf16 v[118:121], v[136:139], v[210:213], v[118:121]
	v_mfma_f32_16x16x32_bf16 v[114:117], v[176:179], v[210:213], v[114:117]
	v_mfma_f32_16x16x32_bf16 v[106:109], v[136:139], v[218:221], v[106:109]
	v_mfma_f32_16x16x32_bf16 v[98:101], v[176:179], v[218:221], v[98:101]
	v_mfma_f32_16x16x32_bf16 v[94:97], v[136:139], v[226:229], v[94:97]
	v_mfma_f32_16x16x32_bf16 v[86:89], v[176:179], v[226:229], v[86:89]
	v_mfma_f32_16x16x32_bf16 v[110:113], v[180:183], v[196:199], v[110:113]
	v_mfma_f32_16x16x32_bf16 v[102:105], v[188:191], v[196:199], v[102:105]
	v_mfma_f32_16x16x32_bf16 v[90:93], v[180:183], v[204:207], v[90:93]
	v_mfma_f32_16x16x32_bf16 v[82:85], v[188:191], v[204:207], v[82:85]
	v_mfma_f32_16x16x32_bf16 v[78:81], v[180:183], v[214:217], v[78:81]
	v_mfma_f32_16x16x32_bf16 v[74:77], v[188:191], v[214:217], v[74:77]
	v_mfma_f32_16x16x32_bf16 v[70:73], v[180:183], v[222:225], v[70:73]
	v_mfma_f32_16x16x32_bf16 v[66:69], v[188:191], v[222:225], v[66:69]
	v_mfma_f32_16x16x32_bf16 v[110:113], v[184:187], v[200:203], v[110:113]
	v_mfma_f32_16x16x32_bf16 v[102:105], v[192:195], v[200:203], v[102:105]
	v_mfma_f32_16x16x32_bf16 v[90:93], v[184:187], v[210:213], v[90:93]
	v_mfma_f32_16x16x32_bf16 v[82:85], v[192:195], v[210:213], v[82:85]
	v_mfma_f32_16x16x32_bf16 v[78:81], v[184:187], v[218:221], v[78:81]
	v_mfma_f32_16x16x32_bf16 v[74:77], v[192:195], v[218:221], v[74:77]
	v_mfma_f32_16x16x32_bf16 v[70:73], v[184:187], v[226:229], v[70:73]
	v_mfma_f32_16x16x32_bf16 v[66:69], v[192:195], v[226:229], v[66:69]
	s_barrier
	ds_read_b128 v[196:199], v175 offset:49152
	ds_read_b128 v[200:203], v175 offset:50176
	ds_read_b128 v[204:207], v175 offset:51200
	ds_read_b128 v[210:213], v175 offset:52224
	ds_read_b128 v[214:217], v175 offset:53248
	ds_read_b128 v[218:221], v175 offset:54272
	ds_read_b128 v[222:225], v175 offset:55296
	ds_read_b128 v[226:229], v175 offset:56320
	s_add_i32 s28, s28, s26
	s_mov_b32 m0, s28
	v_lshl_add_u64 v[232:233], v[144:145], 0, s[20:21]
	global_load_lds_dwordx4 v[232:233], off
	v_lshl_add_u64 v[232:233], v[144:145], 0, s[22:23]
	s_add_i32 m0, s28, 0x2000
	s_add_i32 s28, s29, s26
	global_load_lds_dwordx4 v[232:233], off
	v_lshl_add_u64 v[232:233], v[144:145], 0, s[40:41]
	s_mov_b32 m0, s28
	v_lshl_add_u64 v[144:145], v[144:145], 0, s[42:43]
	global_load_lds_dwordx4 v[232:233], off
	s_add_i32 m0, s28, 0x2000
	s_nop 0
	global_load_lds_dwordx4 v[144:145], off
	v_lshl_add_u64 v[144:145], v[230:231], 0, s[36:37]
	s_mov_b32 m0, s50
	s_nop 0
	global_load_lds_dwordx4 v[144:145], off
	v_lshl_add_u64 v[144:145], v[230:231], 0, s[38:39]
	s_mov_b32 m0, s51
	s_nop 0
	global_load_lds_dwordx4 v[144:145], off
	s_waitcnt vmcnt(8)
	s_waitcnt lgkmcnt(0)
	s_barrier
	s_waitcnt lgkmcnt(0)
	v_mfma_f32_16x16x32_bf16 v[62:65], v[132:135], v[196:199], v[62:65]
	v_mfma_f32_16x16x32_bf16 v[58:61], v[140:143], v[196:199], v[58:61]
	v_mfma_f32_16x16x32_bf16 v[54:57], v[132:135], v[204:207], v[54:57]
	v_mfma_f32_16x16x32_bf16 v[50:53], v[140:143], v[204:207], v[50:53]
	s_add_u32 s19, s19, 0x40000
	v_mfma_f32_16x16x32_bf16 v[46:49], v[132:135], v[214:217], v[46:49]
	s_addc_u32 s49, s49, 0
	v_mfma_f32_16x16x32_bf16 v[38:41], v[140:143], v[214:217], v[38:41]
	s_add_u32 s76, s76, 0x820000
	v_mfma_f32_16x16x32_bf16 v[30:33], v[132:135], v[222:225], v[30:33]
	s_addc_u32 s77, s77, 0
	v_mfma_f32_16x16x32_bf16 v[22:25], v[140:143], v[222:225], v[22:25]
	s_cmp_ge_u32 s57, s5
	v_mfma_f32_16x16x32_bf16 v[62:65], v[136:139], v[200:203], v[62:65]
	v_mfma_f32_16x16x32_bf16 v[58:61], v[176:179], v[200:203], v[58:61]
	v_mfma_f32_16x16x32_bf16 v[54:57], v[136:139], v[210:213], v[54:57]
	v_mfma_f32_16x16x32_bf16 v[50:53], v[176:179], v[210:213], v[50:53]
	v_mfma_f32_16x16x32_bf16 v[46:49], v[136:139], v[218:221], v[46:49]
	v_mfma_f32_16x16x32_bf16 v[38:41], v[176:179], v[218:221], v[38:41]
	v_mfma_f32_16x16x32_bf16 v[30:33], v[136:139], v[226:229], v[30:33]
	v_mfma_f32_16x16x32_bf16 v[22:25], v[176:179], v[226:229], v[22:25]
	v_mfma_f32_16x16x32_bf16 v[42:45], v[180:183], v[196:199], v[42:45]
	v_mfma_f32_16x16x32_bf16 v[34:37], v[188:191], v[196:199], v[34:37]
	v_mfma_f32_16x16x32_bf16 v[26:29], v[180:183], v[204:207], v[26:29]
	v_mfma_f32_16x16x32_bf16 v[18:21], v[188:191], v[204:207], v[18:21]
	v_mfma_f32_16x16x32_bf16 v[14:17], v[180:183], v[214:217], v[14:17]
	v_mfma_f32_16x16x32_bf16 v[10:13], v[188:191], v[214:217], v[10:13]
	v_mfma_f32_16x16x32_bf16 v[6:9], v[180:183], v[222:225], v[6:9]
	v_mfma_f32_16x16x32_bf16 v[2:5], v[188:191], v[222:225], v[2:5]
	v_mfma_f32_16x16x32_bf16 v[42:45], v[184:187], v[200:203], v[42:45]
	v_mfma_f32_16x16x32_bf16 v[34:37], v[192:195], v[200:203], v[34:37]
	v_mfma_f32_16x16x32_bf16 v[26:29], v[184:187], v[210:213], v[26:29]
	v_mfma_f32_16x16x32_bf16 v[18:21], v[192:195], v[210:213], v[18:21]
	v_mfma_f32_16x16x32_bf16 v[14:17], v[184:187], v[218:221], v[14:17]
	v_mfma_f32_16x16x32_bf16 v[10:13], v[192:195], v[218:221], v[10:13]
	v_mfma_f32_16x16x32_bf16 v[6:9], v[184:187], v[226:229], v[6:9]
	v_mfma_f32_16x16x32_bf16 v[2:5], v[192:195], v[226:229], v[2:5]
	s_barrier
	s_cbranch_scc1 .LBB0_282

; #define G8_STA(bufoff, ptr, sg, h) G8_STAGE1(bufoff, (ptr) + (h) * ((sg) ? hA1 : hA0), ((sg) ? voffA1 : voffA0), ((sg) ? r64A1 : r64A0))
; #define G8_STB(bufoff, ptr, sg, h) G8_STAGE1(bufoff, (ptr) + (h) * ((sg) ? hB1 : hB0), ((sg) ? voffB1 : voffB0), ((sg) ? r64B1 : r64B0))
; #define G8_LDA(dst, b, h) do { _Pragma("unroll") for (int m = 0; m < 4; ++m) _Pragma("unroll") for (int k = 0; k < 2; ++k) dst[m][k] = *(const LAS bf16x8*)(lds + G8_SA(b, h) + aoff + m * 2048 + k * 1024); } while (0)
; #define G8_LDB(dst, b, h) do { _Pragma("unroll") for (int n = 0; n < 2; ++n) _Pragma("unroll") for (int k = 0; k < 2; ++k) dst[n][k] = *(const LAS bf16x8*)(lds + G8_SB(b, h) + boff + n * 2048 + k * 1024); } while (0)
; #define G8_MMA(ai, bj, At, Bt) do { __builtin_amdgcn_s_setprio(1); _Pragma("unroll") for (int m = 0; m < 4; ++m) _Pragma("unroll") for (int n = 0; n < 2; ++n) _Pragma("unroll") for (int k = 0; k < 2; ++k) \
;         acc[ai][bj][m][n] = __builtin_amdgcn_mfma_f32_16x16x32_bf16(Bt[n][k], At[m][k], acc[ai][bj][m][n], 0, 0, 0); __builtin_amdgcn_s_setprio(0); } while (0)
; #define G8_WAIT_V(n) asm volatile("s_waitcnt vmcnt(" #n ")" ::: "memory")
; #define G8_WAIT_L(n) asm volatile("s_waitcnt lgkmcnt(" #n ")" ::: "memory")
; #define G8_BAR __builtin_amdgcn_s_barrier()
; #define G8_SCHED __builtin_amdgcn_sched_barrier(0)
; template <class P>
; __device__ __forceinline__ void gemm_phase(LAS unsigned char* lds, const P& p, const int G, const int c) {
;     ...
;             G8_LDB(B0, 0, 0); G8_LDB(B1, 0, 1); G8_SCHED; G8_LDA(At, 0, 0); G8_STA(G8_SA(1, 1), a1, sg1, 1);
;             G8_WAIT_V(8); G8_WAIT_L(0); G8_BAR; G8_MMA(0, 0, At, B0); G8_MMA(0, 1, At, B1); G8_BAR; G8_SCHED;
;             G8_LDA(At, 0, 1); G8_STB(G8_SB(0, 0), b2, sg2, 0); G8_STB(G8_SB(0, 1), b2, sg2, 1); G8_STA(G8_SA(0, 0), a2, sg2, 0);
;             G8_WAIT_V(8); G8_WAIT_L(0); G8_BAR; G8_MMA(1, 0, At, B0); G8_MMA(1, 1, At, B1); G8_BAR; G8_SCHED;
.Lpeel_410:
	v_add_u32_e32 v130, s65, v137
	ds_read_b128 v[142:145], v130
	ds_read_b128 v[146:149], v130 offset:1024
	ds_read_b128 v[162:165], v130 offset:2048
	ds_read_b128 v[166:169], v130 offset:3072
	v_add_u32_e32 v130, s66, v137
	ds_read_b128 v[170:173], v130
	ds_read_b128 v[174:177], v130 offset:1024
	ds_read_b128 v[178:181], v130 offset:2048
	ds_read_b128 v[182:185], v130 offset:3072
	s_add_i32 s74, s74, 2
	s_and_b64 s[30:31], exec, s[30:31]
	s_cselect_b32 s31, s7, s53
	s_cselect_b32 s30, s18, s19
	v_lshl_add_u64 v[206:207], v[140:141], 0, s[70:71]
	v_lshl_add_u64 v[222:223], v[206:207], 0, s[76:77]
	s_add_i32 m0, s27, 0xc000
	ds_read_b128 v[186:189], v158
	ds_read_b128 v[190:193], v158 offset:1024
	ds_read_b128 v[194:197], v158 offset:2048
	ds_read_b128 v[198:201], v158 offset:3072
	ds_read_b128 v[202:205], v158 offset:4096
	ds_read_b128 v[210:213], v158 offset:5120
	ds_read_b128 v[214:217], v158 offset:6144
	ds_read_b128 v[218:221], v158 offset:7168
	global_load_lds_dwordx4 v[222:223], off
	v_lshl_add_u64 v[206:207], v[206:207], 0, s[48:49]
	s_add_i32 m0, s27, 0xe000
	s_nop 0
	global_load_lds_dwordx4 v[206:207], off
	s_waitcnt vmcnt(8)
	s_waitcnt lgkmcnt(0)
	s_barrier
	s_waitcnt lgkmcnt(0)
	v_mfma_f32_16x16x32_bf16 v[126:129], v[142:145], v[186:189], 0
	v_mfma_f32_16x16x32_bf16 v[122:125], v[162:165], v[186:189], 0
	v_mfma_f32_16x16x32_bf16 v[110:113], v[142:145], v[194:197], 0
	v_mfma_f32_16x16x32_bf16 v[106:109], v[162:165], v[194:197], 0
	v_mfma_f32_16x16x32_bf16 v[94:97], v[142:145], v[202:205], 0
	v_mfma_f32_16x16x32_bf16 v[90:93], v[162:165], v[202:205], 0
	v_mfma_f32_16x16x32_bf16 v[78:81], v[142:145], v[214:217], 0
	v_mfma_f32_16x16x32_bf16 v[74:77], v[162:165], v[214:217], 0
	v_mfma_f32_16x16x32_bf16 v[126:129], v[146:149], v[190:193], v[126:129]
	v_mfma_f32_16x16x32_bf16 v[122:125], v[166:169], v[190:193], v[122:125]
	v_mfma_f32_16x16x32_bf16 v[110:113], v[146:149], v[198:201], v[110:113]
	v_mfma_f32_16x16x32_bf16 v[106:109], v[166:169], v[198:201], v[106:109]
	v_mfma_f32_16x16x32_bf16 v[94:97], v[146:149], v[210:213], v[94:97]
	v_mfma_f32_16x16x32_bf16 v[90:93], v[166:169], v[210:213], v[90:93]
	v_mfma_f32_16x16x32_bf16 v[78:81], v[146:149], v[218:221], v[78:81]
	v_mfma_f32_16x16x32_bf16 v[74:77], v[166:169], v[218:221], v[74:77]
	v_mfma_f32_16x16x32_bf16 v[118:121], v[170:173], v[186:189], 0
	v_mfma_f32_16x16x32_bf16 v[114:117], v[178:181], v[186:189], 0
	v_mfma_f32_16x16x32_bf16 v[102:105], v[170:173], v[194:197], 0
	v_mfma_f32_16x16x32_bf16 v[98:101], v[178:181], v[194:197], 0
	v_mfma_f32_16x16x32_bf16 v[86:89], v[170:173], v[202:205], 0
	v_mfma_f32_16x16x32_bf16 v[82:85], v[178:181], v[202:205], 0
	v_mfma_f32_16x16x32_bf16 v[70:73], v[170:173], v[214:217], 0
	v_mfma_f32_16x16x32_bf16 v[66:69], v[178:181], v[214:217], 0
	v_mfma_f32_16x16x32_bf16 v[118:121], v[174:177], v[190:193], v[118:121]
	v_mfma_f32_16x16x32_bf16 v[114:117], v[182:185], v[190:193], v[114:117]
	v_mfma_f32_16x16x32_bf16 v[102:105], v[174:177], v[198:201], v[102:105]
	v_mfma_f32_16x16x32_bf16 v[98:101], v[182:185], v[198:201], v[98:101]
	v_mfma_f32_16x16x32_bf16 v[86:89], v[174:177], v[210:213], v[86:89]
	v_mfma_f32_16x16x32_bf16 v[82:85], v[182:185], v[210:213], v[82:85]
	v_mfma_f32_16x16x32_bf16 v[70:73], v[174:177], v[218:221], v[70:73]
	v_mfma_f32_16x16x32_bf16 v[66:69], v[182:185], v[218:221], v[66:69]
	s_barrier
	ds_read_b128 v[186:189], v158 offset:16384
	ds_read_b128 v[190:193], v158 offset:17408
	ds_read_b128 v[194:197], v158 offset:18432
	ds_read_b128 v[198:201], v158 offset:19456
	ds_read_b128 v[202:205], v158 offset:20480
	ds_read_b128 v[210:213], v158 offset:21504
	ds_read_b128 v[214:217], v158 offset:22528
	ds_read_b128 v[218:221], v158 offset:23552
	v_lshl_add_u64 v[206:207], s[30:31], 0, v[132:133]
	s_add_i32 s30, s65, s26
	s_mov_b32 m0, s30
	s_nop 0
	global_load_lds_dwordx4 v[206:207], off
	v_lshl_add_u64 v[222:223], v[206:207], 0, s[8:9]
	s_add_i32 m0, s30, 0x2000
	s_add_i32 s30, s66, s26
	global_load_lds_dwordx4 v[222:223], off
	v_lshl_add_u64 v[222:223], v[206:207], 0, s[10:11]
	s_mov_b32 m0, s30
	s_nop 0
	global_load_lds_dwordx4 v[222:223], off
	v_lshl_add_u64 v[222:223], v[206:207], 0, s[12:13]
	s_add_i32 m0, s30, 0x2000
	s_nop 0
	global_load_lds_dwordx4 v[222:223], off
	v_lshl_add_u64 v[222:223], s[28:29], 0, v[134:135]
	s_mov_b32 m0, s27
	v_lshl_add_u64 v[224:225], v[222:223], 0, s[8:9]
	global_load_lds_dwordx4 v[222:223], off
	s_mov_b32 m0, s33
	s_nop 0
	global_load_lds_dwordx4 v[224:225], off
	s_waitcnt vmcnt(8)
	s_waitcnt lgkmcnt(0)
	s_barrier
	s_waitcnt lgkmcnt(0)
	v_mfma_f32_16x16x32_bf16 v[62:65], v[142:145], v[186:189], 0
	v_mfma_f32_16x16x32_bf16 v[58:61], v[162:165], v[186:189], 0
	v_mfma_f32_16x16x32_bf16 v[46:49], v[142:145], v[194:197], 0
	v_mfma_f32_16x16x32_bf16 v[42:45], v[162:165], v[194:197], 0
	v_mfma_f32_16x16x32_bf16 v[30:33], v[142:145], v[202:205], 0
	v_mfma_f32_16x16x32_bf16 v[26:29], v[162:165], v[202:205], 0
	v_mfma_f32_16x16x32_bf16 v[14:17], v[142:145], v[214:217], 0
	v_mfma_f32_16x16x32_bf16 v[10:13], v[162:165], v[214:217], 0
	v_mfma_f32_16x16x32_bf16 v[62:65], v[146:149], v[190:193], v[62:65]
	v_mfma_f32_16x16x32_bf16 v[58:61], v[166:169], v[190:193], v[58:61]
	v_mfma_f32_16x16x32_bf16 v[46:49], v[146:149], v[198:201], v[46:49]
	v_mfma_f32_16x16x32_bf16 v[42:45], v[166:169], v[198:201], v[42:45]
	v_mfma_f32_16x16x32_bf16 v[30:33], v[146:149], v[210:213], v[30:33]
	v_mfma_f32_16x16x32_bf16 v[26:29], v[166:169], v[210:213], v[26:29]
	v_mfma_f32_16x16x32_bf16 v[14:17], v[146:149], v[218:221], v[14:17]
	v_mfma_f32_16x16x32_bf16 v[10:13], v[166:169], v[218:221], v[10:13]
	v_mfma_f32_16x16x32_bf16 v[54:57], v[170:173], v[186:189], 0
	v_mfma_f32_16x16x32_bf16 v[50:53], v[178:181], v[186:189], 0
	v_mfma_f32_16x16x32_bf16 v[38:41], v[170:173], v[194:197], 0
	v_mfma_f32_16x16x32_bf16 v[34:37], v[178:181], v[194:197], 0
	v_mfma_f32_16x16x32_bf16 v[22:25], v[170:173], v[202:205], 0
	v_mfma_f32_16x16x32_bf16 v[18:21], v[178:181], v[202:205], 0
	v_mfma_f32_16x16x32_bf16 v[6:9], v[170:173], v[214:217], 0
	v_mfma_f32_16x16x32_bf16 v[2:5], v[178:181], v[214:217], 0
	v_mfma_f32_16x16x32_bf16 v[54:57], v[174:177], v[190:193], v[54:57]
	v_mfma_f32_16x16x32_bf16 v[50:53], v[182:185], v[190:193], v[50:53]
	v_mfma_f32_16x16x32_bf16 v[38:41], v[174:177], v[198:201], v[38:41]
	v_mfma_f32_16x16x32_bf16 v[34:37], v[182:185], v[198:201], v[34:37]
	v_mfma_f32_16x16x32_bf16 v[22:25], v[174:177], v[210:213], v[22:25]
	v_mfma_f32_16x16x32_bf16 v[18:21], v[182:185], v[210:213], v[18:21]
	v_mfma_f32_16x16x32_bf16 v[6:9], v[174:177], v[218:221], v[6:9]
	v_mfma_f32_16x16x32_bf16 v[2:5], v[182:185], v[218:221], v[2:5]
	s_branch .Lmid_410
; #define G8_STA(bufoff, ptr, sg, h) G8_STAGE1(bufoff, (ptr) + (h) * ((sg) ? hA1 : hA0), ((sg) ? voffA1 : voffA0), ((sg) ? r64A1 : r64A0))
; #define G8_STB(bufoff, ptr, sg, h) G8_STAGE1(bufoff, (ptr) + (h) * ((sg) ? hB1 : hB0), ((sg) ? voffB1 : voffB0), ((sg) ? r64B1 : r64B0))
; #define G8_LDA(dst, b, h) do { _Pragma("unroll") for (int m = 0; m < 4; ++m) _Pragma("unroll") for (int k = 0; k < 2; ++k) dst[m][k] = *(const LAS bf16x8*)(lds + G8_SA(b, h) + aoff + m * 2048 + k * 1024); } while (0)
; #define G8_LDB(dst, b, h) do { _Pragma("unroll") for (int n = 0; n < 2; ++n) _Pragma("unroll") for (int k = 0; k < 2; ++k) dst[n][k] = *(const LAS bf16x8*)(lds + G8_SB(b, h) + boff + n * 2048 + k * 1024); } while (0)
; #define G8_MMA(ai, bj, At, Bt) do { __builtin_amdgcn_s_setprio(1); _Pragma("unroll") for (int m = 0; m < 4; ++m) _Pragma("unroll") for (int n = 0; n < 2; ++n) _Pragma("unroll") for (int k = 0; k < 2; ++k) \
;         acc[ai][bj][m][n] = __builtin_amdgcn_mfma_f32_16x16x32_bf16(Bt[n][k], At[m][k], acc[ai][bj][m][n], 0, 0, 0); __builtin_amdgcn_s_setprio(0); } while (0)
; #define G8_WAIT_V(n) asm volatile("s_waitcnt vmcnt(" #n ")" ::: "memory")
; #define G8_WAIT_L(n) asm volatile("s_waitcnt lgkmcnt(" #n ")" ::: "memory")
; #define G8_BAR __builtin_amdgcn_s_barrier()
; #define G8_SCHED __builtin_amdgcn_sched_barrier(0)
; template <class P>
; __device__ __forceinline__ void gemm_phase(LAS unsigned char* lds, const P& p, const int G, const int c) {
;     ...
;             G8_LDB(B0, 0, 0); G8_LDB(B1, 0, 1); G8_SCHED; G8_LDA(At, 0, 0); G8_STA(G8_SA(1, 1), a1, sg1, 1);
;             G8_WAIT_V(8); G8_WAIT_L(0); G8_BAR; G8_MMA(0, 0, At, B0); G8_MMA(0, 1, At, B1); G8_BAR; G8_SCHED;
;             G8_LDA(At, 0, 1); G8_STB(G8_SB(0, 0), b2, sg2, 0); G8_STB(G8_SB(0, 1), b2, sg2, 1); G8_STA(G8_SA(0, 0), a2, sg2, 0);
;             G8_WAIT_V(8); G8_WAIT_L(0); G8_BAR; G8_MMA(1, 0, At, B0); G8_MMA(1, 1, At, B1); G8_BAR; G8_SCHED;
.LBB0_410:
	v_add_u32_e32 v130, s65, v137
	ds_read_b128 v[142:145], v130
	ds_read_b128 v[146:149], v130 offset:1024
	ds_read_b128 v[162:165], v130 offset:2048
	ds_read_b128 v[166:169], v130 offset:3072
	v_add_u32_e32 v130, s66, v137
	ds_read_b128 v[170:173], v130
	ds_read_b128 v[174:177], v130 offset:1024
	ds_read_b128 v[178:181], v130 offset:2048
	ds_read_b128 v[182:185], v130 offset:3072
	s_add_i32 s74, s74, 2
	s_and_b64 s[30:31], exec, s[30:31]
	s_cselect_b32 s31, s7, s53
	s_cselect_b32 s30, s18, s19
	v_lshl_add_u64 v[206:207], v[140:141], 0, s[70:71]
	v_lshl_add_u64 v[222:223], v[206:207], 0, s[76:77]
	s_add_i32 m0, s27, 0xc000
	ds_read_b128 v[186:189], v158
	ds_read_b128 v[190:193], v158 offset:1024
	ds_read_b128 v[194:197], v158 offset:2048
	ds_read_b128 v[198:201], v158 offset:3072
	ds_read_b128 v[202:205], v158 offset:4096
	ds_read_b128 v[210:213], v158 offset:5120
	ds_read_b128 v[214:217], v158 offset:6144
	ds_read_b128 v[218:221], v158 offset:7168
	global_load_lds_dwordx4 v[222:223], off
	v_lshl_add_u64 v[206:207], v[206:207], 0, s[48:49]
	s_add_i32 m0, s27, 0xe000
	s_nop 0
	global_load_lds_dwordx4 v[206:207], off
	s_waitcnt vmcnt(8)
	s_waitcnt lgkmcnt(0)
	s_barrier
	s_waitcnt lgkmcnt(0)
	v_mfma_f32_16x16x32_bf16 v[126:129], v[142:145], v[186:189], v[126:129]
	v_mfma_f32_16x16x32_bf16 v[122:125], v[162:165], v[186:189], v[122:125]
	v_mfma_f32_16x16x32_bf16 v[110:113], v[142:145], v[194:197], v[110:113]
	v_mfma_f32_16x16x32_bf16 v[106:109], v[162:165], v[194:197], v[106:109]
	v_mfma_f32_16x16x32_bf16 v[94:97], v[142:145], v[202:205], v[94:97]
	v_mfma_f32_16x16x32_bf16 v[90:93], v[162:165], v[202:205], v[90:93]
	v_mfma_f32_16x16x32_bf16 v[78:81], v[142:145], v[214:217], v[78:81]
	v_mfma_f32_16x16x32_bf16 v[74:77], v[162:165], v[214:217], v[74:77]
	v_mfma_f32_16x16x32_bf16 v[126:129], v[146:149], v[190:193], v[126:129]
	v_mfma_f32_16x16x32_bf16 v[122:125], v[166:169], v[190:193], v[122:125]
	v_mfma_f32_16x16x32_bf16 v[110:113], v[146:149], v[198:201], v[110:113]
	v_mfma_f32_16x16x32_bf16 v[106:109], v[166:169], v[198:201], v[106:109]
	v_mfma_f32_16x16x32_bf16 v[94:97], v[146:149], v[210:213], v[94:97]
	v_mfma_f32_16x16x32_bf16 v[90:93], v[166:169], v[210:213], v[90:93]
	v_mfma_f32_16x16x32_bf16 v[78:81], v[146:149], v[218:221], v[78:81]
	v_mfma_f32_16x16x32_bf16 v[74:77], v[166:169], v[218:221], v[74:77]
	v_mfma_f32_16x16x32_bf16 v[118:121], v[170:173], v[186:189], v[118:121]
	v_mfma_f32_16x16x32_bf16 v[114:117], v[178:181], v[186:189], v[114:117]
	v_mfma_f32_16x16x32_bf16 v[102:105], v[170:173], v[194:197], v[102:105]
	v_mfma_f32_16x16x32_bf16 v[98:101], v[178:181], v[194:197], v[98:101]
	v_mfma_f32_16x16x32_bf16 v[86:89], v[170:173], v[202:205], v[86:89]
	v_mfma_f32_16x16x32_bf16 v[82:85], v[178:181], v[202:205], v[82:85]
	v_mfma_f32_16x16x32_bf16 v[70:73], v[170:173], v[214:217], v[70:73]
	v_mfma_f32_16x16x32_bf16 v[66:69], v[178:181], v[214:217], v[66:69]
	v_mfma_f32_16x16x32_bf16 v[118:121], v[174:177], v[190:193], v[118:121]
	v_mfma_f32_16x16x32_bf16 v[114:117], v[182:185], v[190:193], v[114:117]
	v_mfma_f32_16x16x32_bf16 v[102:105], v[174:177], v[198:201], v[102:105]
	v_mfma_f32_16x16x32_bf16 v[98:101], v[182:185], v[198:201], v[98:101]
	v_mfma_f32_16x16x32_bf16 v[86:89], v[174:177], v[210:213], v[86:89]
	v_mfma_f32_16x16x32_bf16 v[82:85], v[182:185], v[210:213], v[82:85]
	v_mfma_f32_16x16x32_bf16 v[70:73], v[174:177], v[218:221], v[70:73]
	v_mfma_f32_16x16x32_bf16 v[66:69], v[182:185], v[218:221], v[66:69]
	s_barrier
	ds_read_b128 v[186:189], v158 offset:16384
	ds_read_b128 v[190:193], v158 offset:17408
	ds_read_b128 v[194:197], v158 offset:18432
	ds_read_b128 v[198:201], v158 offset:19456
	ds_read_b128 v[202:205], v158 offset:20480
	ds_read_b128 v[210:213], v158 offset:21504
	ds_read_b128 v[214:217], v158 offset:22528
	ds_read_b128 v[218:221], v158 offset:23552
	v_lshl_add_u64 v[206:207], s[30:31], 0, v[132:133]
	s_add_i32 s30, s65, s26
	s_mov_b32 m0, s30
	s_nop 0
	global_load_lds_dwordx4 v[206:207], off
	v_lshl_add_u64 v[222:223], v[206:207], 0, s[8:9]
	s_add_i32 m0, s30, 0x2000
	s_add_i32 s30, s66, s26
	global_load_lds_dwordx4 v[222:223], off
	v_lshl_add_u64 v[222:223], v[206:207], 0, s[10:11]
	s_mov_b32 m0, s30
	s_nop 0
	global_load_lds_dwordx4 v[222:223], off
	v_lshl_add_u64 v[222:223], v[206:207], 0, s[12:13]
	s_add_i32 m0, s30, 0x2000
	s_nop 0
	global_load_lds_dwordx4 v[222:223], off
	v_lshl_add_u64 v[222:223], s[28:29], 0, v[134:135]
	s_mov_b32 m0, s27
	v_lshl_add_u64 v[224:225], v[222:223], 0, s[8:9]
	global_load_lds_dwordx4 v[222:223], off
	s_mov_b32 m0, s33
	s_nop 0
	global_load_lds_dwordx4 v[224:225], off
	s_waitcnt vmcnt(8)
	s_waitcnt lgkmcnt(0)
	s_barrier
	s_waitcnt lgkmcnt(0)
	v_mfma_f32_16x16x32_bf16 v[62:65], v[142:145], v[186:189], v[62:65]
	v_mfma_f32_16x16x32_bf16 v[58:61], v[162:165], v[186:189], v[58:61]
	v_mfma_f32_16x16x32_bf16 v[46:49], v[142:145], v[194:197], v[46:49]
	v_mfma_f32_16x16x32_bf16 v[42:45], v[162:165], v[194:197], v[42:45]
	v_mfma_f32_16x16x32_bf16 v[30:33], v[142:145], v[202:205], v[30:33]
	v_mfma_f32_16x16x32_bf16 v[26:29], v[162:165], v[202:205], v[26:29]
	v_mfma_f32_16x16x32_bf16 v[14:17], v[142:145], v[214:217], v[14:17]
	v_mfma_f32_16x16x32_bf16 v[10:13], v[162:165], v[214:217], v[10:13]
	v_mfma_f32_16x16x32_bf16 v[62:65], v[146:149], v[190:193], v[62:65]
	v_mfma_f32_16x16x32_bf16 v[58:61], v[166:169], v[190:193], v[58:61]
	v_mfma_f32_16x16x32_bf16 v[46:49], v[146:149], v[198:201], v[46:49]
	v_mfma_f32_16x16x32_bf16 v[42:45], v[166:169], v[198:201], v[42:45]
	v_mfma_f32_16x16x32_bf16 v[30:33], v[146:149], v[210:213], v[30:33]
	v_mfma_f32_16x16x32_bf16 v[26:29], v[166:169], v[210:213], v[26:29]
	v_mfma_f32_16x16x32_bf16 v[14:17], v[146:149], v[218:221], v[14:17]
	v_mfma_f32_16x16x32_bf16 v[10:13], v[166:169], v[218:221], v[10:13]
	v_mfma_f32_16x16x32_bf16 v[54:57], v[170:173], v[186:189], v[54:57]
	v_mfma_f32_16x16x32_bf16 v[50:53], v[178:181], v[186:189], v[50:53]
	v_mfma_f32_16x16x32_bf16 v[38:41], v[170:173], v[194:197], v[38:41]
	v_mfma_f32_16x16x32_bf16 v[34:37], v[178:181], v[194:197], v[34:37]
	v_mfma_f32_16x16x32_bf16 v[22:25], v[170:173], v[202:205], v[22:25]
	v_mfma_f32_16x16x32_bf16 v[18:21], v[178:181], v[202:205], v[18:21]
	v_mfma_f32_16x16x32_bf16 v[6:9], v[170:173], v[214:217], v[6:9]
	v_mfma_f32_16x16x32_bf16 v[2:5], v[178:181], v[214:217], v[2:5]
	v_mfma_f32_16x16x32_bf16 v[54:57], v[174:177], v[190:193], v[54:57]
	v_mfma_f32_16x16x32_bf16 v[50:53], v[182:185], v[190:193], v[50:53]
	v_mfma_f32_16x16x32_bf16 v[38:41], v[174:177], v[198:201], v[38:41]
	v_mfma_f32_16x16x32_bf16 v[34:37], v[182:185], v[198:201], v[34:37]
	v_mfma_f32_16x16x32_bf16 v[22:25], v[174:177], v[210:213], v[22:25]
	v_mfma_f32_16x16x32_bf16 v[18:21], v[182:185], v[210:213], v[18:21]
	v_mfma_f32_16x16x32_bf16 v[6:9], v[174:177], v[218:221], v[6:9]
	v_mfma_f32_16x16x32_bf16 v[2:5], v[182:185], v[218:221], v[2:5]
; #define G8_STA(bufoff, ptr, sg, h) G8_STAGE1(bufoff, (ptr) + (h) * ((sg) ? hA1 : hA0), ((sg) ? voffA1 : voffA0), ((sg) ? r64A1 : r64A0))
; #define G8_STB(bufoff, ptr, sg, h) G8_STAGE1(bufoff, (ptr) + (h) * ((sg) ? hB1 : hB0), ((sg) ? voffB1 : voffB0), ((sg) ? r64B1 : r64B0))
; #define G8_LDA(dst, b, h) do { _Pragma("unroll") for (int m = 0; m < 4; ++m) _Pragma("unroll") for (int k = 0; k < 2; ++k) dst[m][k] = *(const LAS bf16x8*)(lds + G8_SA(b, h) + aoff + m * 2048 + k * 1024); } while (0)
; #define G8_LDB(dst, b, h) do { _Pragma("unroll") for (int n = 0; n < 2; ++n) _Pragma("unroll") for (int k = 0; k < 2; ++k) dst[n][k] = *(const LAS bf16x8*)(lds + G8_SB(b, h) + boff + n * 2048 + k * 1024); } while (0)
; #define G8_MMA(ai, bj, At, Bt) do { __builtin_amdgcn_s_setprio(1); _Pragma("unroll") for (int m = 0; m < 4; ++m) _Pragma("unroll") for (int n = 0; n < 2; ++n) _Pragma("unroll") for (int k = 0; k < 2; ++k) \
;         acc[ai][bj][m][n] = __builtin_amdgcn_mfma_f32_16x16x32_bf16(Bt[n][k], At[m][k], acc[ai][bj][m][n], 0, 0, 0); __builtin_amdgcn_s_setprio(0); } while (0)
; #define G8_WAIT_V(n) asm volatile("s_waitcnt vmcnt(" #n ")" ::: "memory")
; #define G8_WAIT_L(n) asm volatile("s_waitcnt lgkmcnt(" #n ")" ::: "memory")
; #define G8_BAR __builtin_amdgcn_s_barrier()
; #define G8_SCHED __builtin_amdgcn_sched_barrier(0)
; template <class P>
; __device__ __forceinline__ void gemm_phase(LAS unsigned char* lds, const P& p, const int G, const int c) {
;     ...
;             G8_LDB(B0, 1, 0); G8_LDB(B1, 1, 1); G8_SCHED; G8_LDA(At, 1, 0); G8_STA(G8_SA(0, 1), a2, sg2, 1);
;             G8_WAIT_V(8); G8_WAIT_L(0); G8_BAR; G8_MMA(0, 0, At, B0); G8_MMA(0, 1, At, B1); G8_BAR; G8_SCHED;
;             G8_LDA(At, 1, 1); G8_STB(G8_SB(1, 0), b3, sg2, 0); G8_STB(G8_SB(1, 1), b3, sg2, 1); G8_STA(G8_SA(1, 0), a3, sg2, 0);
;             G8_WAIT_V(8); G8_WAIT_L(0); G8_BAR; G8_MMA(1, 0, At, B0); G8_MMA(1, 1, At, B1); G8_BAR; G8_SCHED;
;         }
.Lmid_410:
	s_barrier
	s_add_i32 s28, 0, 0x18000
	v_add_u32_e32 v130, s28, v137
	s_add_i32 s29, 0, 0x1c000
	ds_read_b128 v[142:145], v130
	ds_read_b128 v[146:149], v130 offset:1024
	ds_read_b128 v[162:165], v130 offset:2048
	ds_read_b128 v[166:169], v130 offset:3072
	v_add_u32_e32 v130, s29, v137
	ds_read_b128 v[170:173], v130
	ds_read_b128 v[174:177], v130 offset:1024
	ds_read_b128 v[178:181], v130 offset:2048
	ds_read_b128 v[182:185], v130 offset:3072
	s_mov_b32 m0, s34
	v_lshl_add_u64 v[224:225], v[222:223], 0, s[10:11]
	ds_read_b128 v[186:189], v158 offset:32768
	ds_read_b128 v[190:193], v158 offset:33792
	ds_read_b128 v[194:197], v158 offset:34816
	ds_read_b128 v[198:201], v158 offset:35840
	ds_read_b128 v[202:205], v158 offset:36864
	ds_read_b128 v[210:213], v158 offset:37888
	ds_read_b128 v[214:217], v158 offset:38912
	ds_read_b128 v[218:221], v158 offset:39936
	global_load_lds_dwordx4 v[224:225], off
	v_lshl_add_u64 v[224:225], v[222:223], 0, s[12:13]
	s_mov_b32 m0, s35
	s_nop 0
	global_load_lds_dwordx4 v[224:225], off
	s_waitcnt vmcnt(8)
	s_waitcnt lgkmcnt(0)
	s_barrier
	s_waitcnt lgkmcnt(0)
	v_mfma_f32_16x16x32_bf16 v[126:129], v[142:145], v[186:189], v[126:129]
	v_mfma_f32_16x16x32_bf16 v[122:125], v[162:165], v[186:189], v[122:125]
	v_mfma_f32_16x16x32_bf16 v[110:113], v[142:145], v[194:197], v[110:113]
	v_mfma_f32_16x16x32_bf16 v[106:109], v[162:165], v[194:197], v[106:109]
	v_mfma_f32_16x16x32_bf16 v[94:97], v[142:145], v[202:205], v[94:97]
	v_mfma_f32_16x16x32_bf16 v[90:93], v[162:165], v[202:205], v[90:93]
	v_mfma_f32_16x16x32_bf16 v[78:81], v[142:145], v[214:217], v[78:81]
	v_mfma_f32_16x16x32_bf16 v[74:77], v[162:165], v[214:217], v[74:77]
	v_mfma_f32_16x16x32_bf16 v[126:129], v[146:149], v[190:193], v[126:129]
	v_mfma_f32_16x16x32_bf16 v[122:125], v[166:169], v[190:193], v[122:125]
	v_mfma_f32_16x16x32_bf16 v[110:113], v[146:149], v[198:201], v[110:113]
	v_mfma_f32_16x16x32_bf16 v[106:109], v[166:169], v[198:201], v[106:109]
	v_mfma_f32_16x16x32_bf16 v[94:97], v[146:149], v[210:213], v[94:97]
	v_mfma_f32_16x16x32_bf16 v[90:93], v[166:169], v[210:213], v[90:93]
	v_mfma_f32_16x16x32_bf16 v[78:81], v[146:149], v[218:221], v[78:81]
	v_mfma_f32_16x16x32_bf16 v[74:77], v[166:169], v[218:221], v[74:77]
	v_mfma_f32_16x16x32_bf16 v[118:121], v[170:173], v[186:189], v[118:121]
	v_mfma_f32_16x16x32_bf16 v[114:117], v[178:181], v[186:189], v[114:117]
	v_mfma_f32_16x16x32_bf16 v[102:105], v[170:173], v[194:197], v[102:105]
	v_mfma_f32_16x16x32_bf16 v[98:101], v[178:181], v[194:197], v[98:101]
	v_mfma_f32_16x16x32_bf16 v[86:89], v[170:173], v[202:205], v[86:89]
	v_mfma_f32_16x16x32_bf16 v[82:85], v[178:181], v[202:205], v[82:85]
	v_mfma_f32_16x16x32_bf16 v[70:73], v[170:173], v[214:217], v[70:73]
	v_mfma_f32_16x16x32_bf16 v[66:69], v[178:181], v[214:217], v[66:69]
	v_mfma_f32_16x16x32_bf16 v[118:121], v[174:177], v[190:193], v[118:121]
	v_mfma_f32_16x16x32_bf16 v[114:117], v[182:185], v[190:193], v[114:117]
	v_mfma_f32_16x16x32_bf16 v[102:105], v[174:177], v[198:201], v[102:105]
	v_mfma_f32_16x16x32_bf16 v[98:101], v[182:185], v[198:201], v[98:101]
	v_mfma_f32_16x16x32_bf16 v[86:89], v[174:177], v[210:213], v[86:89]
	v_mfma_f32_16x16x32_bf16 v[82:85], v[182:185], v[210:213], v[82:85]
	v_mfma_f32_16x16x32_bf16 v[70:73], v[174:177], v[218:221], v[70:73]
	v_mfma_f32_16x16x32_bf16 v[66:69], v[182:185], v[218:221], v[66:69]
	s_barrier
	ds_read_b128 v[186:189], v158 offset:49152
	ds_read_b128 v[190:193], v158 offset:50176
	ds_read_b128 v[194:197], v158 offset:51200
	ds_read_b128 v[198:201], v158 offset:52224
	ds_read_b128 v[202:205], v158 offset:53248
	ds_read_b128 v[210:213], v158 offset:54272
	ds_read_b128 v[214:217], v158 offset:55296
	ds_read_b128 v[218:221], v158 offset:56320
	s_add_i32 s28, s28, s26
	s_mov_b32 m0, s28
	v_lshl_add_u64 v[224:225], v[206:207], 0, s[20:21]
	global_load_lds_dwordx4 v[224:225], off
	v_lshl_add_u64 v[224:225], v[206:207], 0, s[22:23]
	s_add_i32 m0, s28, 0x2000
	s_add_i32 s28, s29, s26
	global_load_lds_dwordx4 v[224:225], off
	v_lshl_add_u64 v[224:225], v[206:207], 0, s[40:41]
	s_mov_b32 m0, s28
	v_lshl_add_u64 v[206:207], v[206:207], 0, s[42:43]
	global_load_lds_dwordx4 v[224:225], off
	s_add_i32 m0, s28, 0x2000
	s_nop 0
	global_load_lds_dwordx4 v[206:207], off
	v_lshl_add_u64 v[206:207], v[222:223], 0, s[36:37]
	s_mov_b32 m0, s51
	s_nop 0
	global_load_lds_dwordx4 v[206:207], off
	v_lshl_add_u64 v[206:207], v[222:223], 0, s[38:39]
	s_mov_b32 m0, s64
	s_nop 0
	global_load_lds_dwordx4 v[206:207], off
	s_waitcnt vmcnt(8)
	s_waitcnt lgkmcnt(0)
	s_barrier
	s_waitcnt lgkmcnt(0)
	v_mfma_f32_16x16x32_bf16 v[62:65], v[142:145], v[186:189], v[62:65]
	v_mfma_f32_16x16x32_bf16 v[58:61], v[162:165], v[186:189], v[58:61]
	v_mfma_f32_16x16x32_bf16 v[46:49], v[142:145], v[194:197], v[46:49]
	v_mfma_f32_16x16x32_bf16 v[42:45], v[162:165], v[194:197], v[42:45]
	s_add_u32 s19, s19, 0x100000
	v_mfma_f32_16x16x32_bf16 v[30:33], v[142:145], v[202:205], v[30:33]
	s_addc_u32 s53, s53, 0
	v_mfma_f32_16x16x32_bf16 v[26:29], v[162:165], v[202:205], v[26:29]
	s_add_u32 s70, s70, 0x820000
	v_mfma_f32_16x16x32_bf16 v[14:17], v[142:145], v[214:217], v[14:17]
	s_addc_u32 s71, s71, 0
	v_mfma_f32_16x16x32_bf16 v[10:13], v[162:165], v[214:217], v[10:13]
	s_cmp_ge_u32 s74, s1
	v_mfma_f32_16x16x32_bf16 v[62:65], v[146:149], v[190:193], v[62:65]
	v_mfma_f32_16x16x32_bf16 v[58:61], v[166:169], v[190:193], v[58:61]
	v_mfma_f32_16x16x32_bf16 v[46:49], v[146:149], v[198:201], v[46:49]
	v_mfma_f32_16x16x32_bf16 v[42:45], v[166:169], v[198:201], v[42:45]
	v_mfma_f32_16x16x32_bf16 v[30:33], v[146:149], v[210:213], v[30:33]
	v_mfma_f32_16x16x32_bf16 v[26:29], v[166:169], v[210:213], v[26:29]
	v_mfma_f32_16x16x32_bf16 v[14:17], v[146:149], v[218:221], v[14:17]
	v_mfma_f32_16x16x32_bf16 v[10:13], v[166:169], v[218:221], v[10:13]
	v_mfma_f32_16x16x32_bf16 v[54:57], v[170:173], v[186:189], v[54:57]
	v_mfma_f32_16x16x32_bf16 v[50:53], v[178:181], v[186:189], v[50:53]
	v_mfma_f32_16x16x32_bf16 v[38:41], v[170:173], v[194:197], v[38:41]
	v_mfma_f32_16x16x32_bf16 v[34:37], v[178:181], v[194:197], v[34:37]
	v_mfma_f32_16x16x32_bf16 v[22:25], v[170:173], v[202:205], v[22:25]
	v_mfma_f32_16x16x32_bf16 v[18:21], v[178:181], v[202:205], v[18:21]
	v_mfma_f32_16x16x32_bf16 v[6:9], v[170:173], v[214:217], v[6:9]
	v_mfma_f32_16x16x32_bf16 v[2:5], v[178:181], v[214:217], v[2:5]
	v_mfma_f32_16x16x32_bf16 v[54:57], v[174:177], v[190:193], v[54:57]
	v_mfma_f32_16x16x32_bf16 v[50:53], v[182:185], v[190:193], v[50:53]
	v_mfma_f32_16x16x32_bf16 v[38:41], v[174:177], v[198:201], v[38:41]
	v_mfma_f32_16x16x32_bf16 v[34:37], v[182:185], v[198:201], v[34:37]
	v_mfma_f32_16x16x32_bf16 v[22:25], v[174:177], v[210:213], v[22:25]
	v_mfma_f32_16x16x32_bf16 v[18:21], v[182:185], v[210:213], v[18:21]
	v_mfma_f32_16x16x32_bf16 v[6:9], v[174:177], v[218:221], v[6:9]
	v_mfma_f32_16x16x32_bf16 v[2:5], v[182:185], v[218:221], v[2:5]
	s_barrier
	s_cbranch_scc1 .LBB0_415

; #define G8_STA(bufoff, ptr, sg, h) G8_STAGE1(bufoff, (ptr) + (h) * ((sg) ? hA1 : hA0), ((sg) ? voffA1 : voffA0), ((sg) ? r64A1 : r64A0))
; #define G8_STB(bufoff, ptr, sg, h) G8_STAGE1(bufoff, (ptr) + (h) * ((sg) ? hB1 : hB0), ((sg) ? voffB1 : voffB0), ((sg) ? r64B1 : r64B0))
; #define G8_LDA(dst, b, h) do { _Pragma("unroll") for (int m = 0; m < 4; ++m) _Pragma("unroll") for (int k = 0; k < 2; ++k) dst[m][k] = *(const LAS bf16x8*)(lds + G8_SA(b, h) + aoff + m * 2048 + k * 1024); } while (0)
; #define G8_LDB(dst, b, h) do { _Pragma("unroll") for (int n = 0; n < 2; ++n) _Pragma("unroll") for (int k = 0; k < 2; ++k) dst[n][k] = *(const LAS bf16x8*)(lds + G8_SB(b, h) + boff + n * 2048 + k * 1024); } while (0)
; #define G8_WAIT_V(n) asm volatile("s_waitcnt vmcnt(" #n ")" ::: "memory")
; #define G8_WAIT_L(n) asm volatile("s_waitcnt lgkmcnt(" #n ")" ::: "memory")
; template <class P>
; __device__ __forceinline__ void gemm_phase(LAS unsigned char* lds, const P& p, const int G, const int c) {
;     ...
;         const bool has_next = p.unit((ui + 1) * G + c, nxt);
;         const int nt = p.nt(cur);
;         const char* nA0 = has_next ? p.a_base(nxt, 0) - p.a_bias(0) : cA0; const char* nA1 = has_next ? p.a_base(nxt, S1) - p.a_bias(S1) : cA1;
;         const char* nB0 = has_next ? p.b_base(nxt, 0) - p.b_bias(0) : cB0; const char* nB1 = has_next ? p.b_base(nxt, S1) - p.b_bias(S1) : cB1;
;         for (int t = 0; t < nt; t += 2) {
;             const bool last = (t == nt - 2);
;             const bool sg1 = (NS > 1) && (t + 1 >= nt0);
;             const bool sg2 = (NS > 1) && !last && (t + 2 >= nt0);
;             const char* a1 = sg1 ? cA1 + (long)(t + 1 - nt0) * ksA1 : cA0 + (long)(t + 1) * ksA0;
;             const char* a2 = last ? nA0 : (sg2 ? cA1 + (long)(t + 2 - nt0) * ksA1 : cA0 + (long)(t + 2) * ksA0);
;             const char* b2 = last ? nB0 : (sg2 ? cB1 + (long)(t + 2 - nt0) * ksB1 : cB0 + (long)(t + 2) * ksB0);
;             const char* a3 = a2 + (sg2 ? ksA1 : ksA0); const char* b3 = b2 + (sg2 ? ksB1 : ksB0);
;             G8_LDB(B0, 0, 0); G8_LDB(B1, 0, 1); G8_SCHED; G8_LDA(At, 0, 0); G8_STA(G8_SA(1, 1), a1, sg1, 1);
;             G8_WAIT_V(8); G8_WAIT_L(0); G8_BAR; G8_MMA(0, 0, At, B0); G8_MMA(0, 1, At, B1); G8_BAR; G8_SCHED;
;             G8_LDA(At, 0, 1); G8_STB(G8_SB(0, 0), b2, sg2, 0); G8_STB(G8_SB(0, 1), b2, sg2, 1); G8_STA(G8_SA(0, 0), a2, sg2, 0);
.LBB0_538:
	s_lshl_b64 s[18:19], s[18:19], 20
	s_add_u32 s90, s26, s18
	s_addc_u32 s91, s27, s19
	s_and_b64 s[6:7], s[6:7], exec
	s_cselect_b32 s18, s91, s93
	s_cselect_b32 s19, s90, s92
	s_add_u32 s28, s28, 0x40000
	s_addc_u32 s29, s29, 0
	v_lshl_add_u64 v[154:155], s[92:93], 0, v[152:153]
	s_mov_b32 s47, -2
	s_mov_b64 s[94:95], 0
	s_add_u32 s6, s92, s94
	s_addc_u32 s7, s93, s95
	s_add_u32 s6, s6, 0x10000
	s_addc_u32 s7, s7, 0
	s_add_i32 s65, 0, 0x10000
	s_cmp_eq_u32 s94, 0x30000
	s_cselect_b32 s7, s18, s7
	s_cselect_b32 s6, s19, s6
	v_add_u32_e32 v130, s65, v156
	s_cselect_b32 s51, s89, s29
	s_cselect_b32 s50, s88, s28
	s_add_i32 s34, 0, 0x14000
	ds_read_b128 v[160:163], v130
	ds_read_b128 v[164:167], v130 offset:1024
	ds_read_b128 v[168:171], v130 offset:2048
	ds_read_b128 v[172:175], v130 offset:3072
	v_add_u32_e32 v130, s34, v156
	ds_read_b128 v[176:179], v130
	ds_read_b128 v[180:183], v130 offset:1024
	ds_read_b128 v[184:187], v130 offset:2048
	ds_read_b128 v[188:191], v130 offset:3072
	v_lshl_add_u64 v[226:227], v[154:155], 0, s[94:95]
	s_mov_b64 s[54:55], 0xc000
	v_lshl_add_u64 v[228:229], v[226:227], 0, s[54:55]
	s_add_i32 m0, s11, 0xc000
	s_mov_b64 s[54:55], 0xe000
	ds_read_b128 v[192:195], v158
	ds_read_b128 v[196:199], v158 offset:1024
	ds_read_b128 v[200:203], v158 offset:2048
	ds_read_b128 v[204:207], v158 offset:3072
	ds_read_b128 v[210:213], v158 offset:4096
	ds_read_b128 v[214:217], v158 offset:5120
	ds_read_b128 v[218:221], v158 offset:6144
	ds_read_b128 v[222:225], v158 offset:7168
	global_load_lds_dwordx4 v[228:229], off
	v_lshl_add_u64 v[226:227], v[226:227], 0, s[54:55]
	s_add_i32 m0, s11, 0xe000
	s_nop 0
	global_load_lds_dwordx4 v[226:227], off
	s_waitcnt vmcnt(8)
	s_waitcnt lgkmcnt(0)
	s_barrier
	s_waitcnt lgkmcnt(0)
	v_mfma_f32_16x16x32_bf16 v[126:129], v[160:163], v[192:195], 0
	v_mfma_f32_16x16x32_bf16 v[122:125], v[168:171], v[192:195], 0
	v_mfma_f32_16x16x32_bf16 v[118:121], v[160:163], v[200:203], 0
	v_mfma_f32_16x16x32_bf16 v[114:117], v[168:171], v[200:203], 0
	v_mfma_f32_16x16x32_bf16 v[102:105], v[160:163], v[210:213], 0
	v_mfma_f32_16x16x32_bf16 v[98:101], v[168:171], v[210:213], 0
	v_mfma_f32_16x16x32_bf16 v[86:89], v[160:163], v[218:221], 0
	v_mfma_f32_16x16x32_bf16 v[82:85], v[168:171], v[218:221], 0
	v_mfma_f32_16x16x32_bf16 v[126:129], v[164:167], v[196:199], v[126:129]
	v_mfma_f32_16x16x32_bf16 v[122:125], v[172:175], v[196:199], v[122:125]
	v_mfma_f32_16x16x32_bf16 v[118:121], v[164:167], v[204:207], v[118:121]
	v_mfma_f32_16x16x32_bf16 v[114:117], v[172:175], v[204:207], v[114:117]
	v_mfma_f32_16x16x32_bf16 v[102:105], v[164:167], v[214:217], v[102:105]
	v_mfma_f32_16x16x32_bf16 v[98:101], v[172:175], v[214:217], v[98:101]
	v_mfma_f32_16x16x32_bf16 v[86:89], v[164:167], v[222:225], v[86:89]
	v_mfma_f32_16x16x32_bf16 v[82:85], v[172:175], v[222:225], v[82:85]
	v_mfma_f32_16x16x32_bf16 v[110:113], v[176:179], v[192:195], 0
	v_mfma_f32_16x16x32_bf16 v[106:109], v[184:187], v[192:195], 0
	v_mfma_f32_16x16x32_bf16 v[94:97], v[176:179], v[200:203], 0
	v_mfma_f32_16x16x32_bf16 v[90:93], v[184:187], v[200:203], 0
	v_mfma_f32_16x16x32_bf16 v[78:81], v[176:179], v[210:213], 0
	v_mfma_f32_16x16x32_bf16 v[74:77], v[184:187], v[210:213], 0
	v_mfma_f32_16x16x32_bf16 v[70:73], v[176:179], v[218:221], 0
	v_mfma_f32_16x16x32_bf16 v[66:69], v[184:187], v[218:221], 0
	v_mfma_f32_16x16x32_bf16 v[110:113], v[180:183], v[196:199], v[110:113]
	v_mfma_f32_16x16x32_bf16 v[106:109], v[188:191], v[196:199], v[106:109]
	v_mfma_f32_16x16x32_bf16 v[94:97], v[180:183], v[204:207], v[94:97]
	v_mfma_f32_16x16x32_bf16 v[90:93], v[188:191], v[204:207], v[90:93]
	v_mfma_f32_16x16x32_bf16 v[78:81], v[180:183], v[214:217], v[78:81]
	v_mfma_f32_16x16x32_bf16 v[74:77], v[188:191], v[214:217], v[74:77]
	v_mfma_f32_16x16x32_bf16 v[70:73], v[180:183], v[222:225], v[70:73]
	v_mfma_f32_16x16x32_bf16 v[66:69], v[188:191], v[222:225], v[66:69]
	s_barrier
	ds_read_b128 v[192:195], v158 offset:16384
	ds_read_b128 v[196:199], v158 offset:17408
	ds_read_b128 v[200:203], v158 offset:18432
	ds_read_b128 v[204:207], v158 offset:19456
	ds_read_b128 v[210:213], v158 offset:20480
	ds_read_b128 v[214:217], v158 offset:21504
	ds_read_b128 v[218:221], v158 offset:22528
	ds_read_b128 v[222:225], v158 offset:23552
	s_add_i32 s20, s65, s10
	s_mov_b32 m0, s20
	v_lshl_add_u64 v[226:227], s[50:51], 0, v[132:133]
	global_load_lds_dwordx4 v[226:227], off
	v_lshl_add_u64 v[228:229], v[226:227], 0, s[22:23]
	s_add_i32 m0, s20, 0x2000
	s_add_i32 s20, s34, s10
	global_load_lds_dwordx4 v[228:229], off
	v_lshl_add_u64 v[228:229], v[226:227], 0, s[36:37]
	s_mov_b32 m0, s20
	s_nop 0
	global_load_lds_dwordx4 v[228:229], off
	v_lshl_add_u64 v[228:229], v[226:227], 0, s[38:39]
	s_add_i32 m0, s20, 0x2000
	s_nop 0
	global_load_lds_dwordx4 v[228:229], off
	v_lshl_add_u64 v[228:229], s[6:7], 0, v[134:135]
	s_mov_b32 m0, s11
	v_lshl_add_u64 v[230:231], v[228:229], 0, s[22:23]
	global_load_lds_dwordx4 v[228:229], off
	s_mov_b32 m0, s14
	s_nop 0
	global_load_lds_dwordx4 v[230:231], off
	s_waitcnt vmcnt(8)
	s_waitcnt lgkmcnt(0)
	s_barrier
; #define G8_STA(bufoff, ptr, sg, h) G8_STAGE1(bufoff, (ptr) + (h) * ((sg) ? hA1 : hA0), ((sg) ? voffA1 : voffA0), ((sg) ? r64A1 : r64A0))
; #define G8_STB(bufoff, ptr, sg, h) G8_STAGE1(bufoff, (ptr) + (h) * ((sg) ? hB1 : hB0), ((sg) ? voffB1 : voffB0), ((sg) ? r64B1 : r64B0))
; #define G8_LDA(dst, b, h) do { _Pragma("unroll") for (int m = 0; m < 4; ++m) _Pragma("unroll") for (int k = 0; k < 2; ++k) dst[m][k] = *(const LAS bf16x8*)(lds + G8_SA(b, h) + aoff + m * 2048 + k * 1024); } while (0)
; #define G8_LDB(dst, b, h) do { _Pragma("unroll") for (int n = 0; n < 2; ++n) _Pragma("unroll") for (int k = 0; k < 2; ++k) dst[n][k] = *(const LAS bf16x8*)(lds + G8_SB(b, h) + boff + n * 2048 + k * 1024); } while (0)
; #define G8_MMA(ai, bj, At, Bt) do { __builtin_amdgcn_s_setprio(1); _Pragma("unroll") for (int m = 0; m < 4; ++m) _Pragma("unroll") for (int n = 0; n < 2; ++n) _Pragma("unroll") for (int k = 0; k < 2; ++k) \
;         acc[ai][bj][m][n] = __builtin_amdgcn_mfma_f32_16x16x32_bf16(Bt[n][k], At[m][k], acc[ai][bj][m][n], 0, 0, 0); __builtin_amdgcn_s_setprio(0); } while (0)
; #define G8_WAIT_V(n) asm volatile("s_waitcnt vmcnt(" #n ")" ::: "memory")
; #define G8_WAIT_L(n) asm volatile("s_waitcnt lgkmcnt(" #n ")" ::: "memory")
; #define G8_BAR __builtin_amdgcn_s_barrier()
; #define G8_SCHED __builtin_amdgcn_sched_barrier(0)
; template <class P>
; __device__ __forceinline__ void gemm_phase(LAS unsigned char* lds, const P& p, const int G, const int c) {
;     ...
;             G8_LDB(B0, 0, 0); G8_LDB(B1, 0, 1); G8_SCHED; G8_LDA(At, 0, 0); G8_STA(G8_SA(1, 1), a1, sg1, 1);
;             G8_WAIT_V(8); G8_WAIT_L(0); G8_BAR; G8_MMA(0, 0, At, B0); G8_MMA(0, 1, At, B1); G8_BAR; G8_SCHED;
;             G8_LDA(At, 0, 1); G8_STB(G8_SB(0, 0), b2, sg2, 0); G8_STB(G8_SB(0, 1), b2, sg2, 1); G8_STA(G8_SA(0, 0), a2, sg2, 0);
;             G8_WAIT_V(8); G8_WAIT_L(0); G8_BAR; G8_MMA(1, 0, At, B0); G8_MMA(1, 1, At, B1); G8_BAR; G8_SCHED;
	s_waitcnt lgkmcnt(0)
	v_mfma_f32_16x16x32_bf16 v[62:65], v[160:163], v[192:195], 0
	v_mfma_f32_16x16x32_bf16 v[58:61], v[168:171], v[192:195], 0
	v_mfma_f32_16x16x32_bf16 v[54:57], v[160:163], v[200:203], 0
	v_mfma_f32_16x16x32_bf16 v[50:53], v[168:171], v[200:203], 0
	v_mfma_f32_16x16x32_bf16 v[38:41], v[160:163], v[210:213], 0
	v_mfma_f32_16x16x32_bf16 v[34:37], v[168:171], v[210:213], 0
	v_mfma_f32_16x16x32_bf16 v[22:25], v[160:163], v[218:221], 0
	v_mfma_f32_16x16x32_bf16 v[18:21], v[168:171], v[218:221], 0
	v_mfma_f32_16x16x32_bf16 v[62:65], v[164:167], v[196:199], v[62:65]
	v_mfma_f32_16x16x32_bf16 v[58:61], v[172:175], v[196:199], v[58:61]
	v_mfma_f32_16x16x32_bf16 v[54:57], v[164:167], v[204:207], v[54:57]
	v_mfma_f32_16x16x32_bf16 v[50:53], v[172:175], v[204:207], v[50:53]
	v_mfma_f32_16x16x32_bf16 v[38:41], v[164:167], v[214:217], v[38:41]
	v_mfma_f32_16x16x32_bf16 v[34:37], v[172:175], v[214:217], v[34:37]
	v_mfma_f32_16x16x32_bf16 v[22:25], v[164:167], v[222:225], v[22:25]
	v_mfma_f32_16x16x32_bf16 v[18:21], v[172:175], v[222:225], v[18:21]
	v_mfma_f32_16x16x32_bf16 v[46:49], v[176:179], v[192:195], 0
	v_mfma_f32_16x16x32_bf16 v[42:45], v[184:187], v[192:195], 0
	v_mfma_f32_16x16x32_bf16 v[30:33], v[176:179], v[200:203], 0
	v_mfma_f32_16x16x32_bf16 v[26:29], v[184:187], v[200:203], 0
	v_mfma_f32_16x16x32_bf16 v[14:17], v[176:179], v[210:213], 0
	v_mfma_f32_16x16x32_bf16 v[10:13], v[184:187], v[210:213], 0
	v_mfma_f32_16x16x32_bf16 v[6:9], v[176:179], v[218:221], 0
	v_mfma_f32_16x16x32_bf16 v[2:5], v[184:187], v[218:221], 0
	v_mfma_f32_16x16x32_bf16 v[46:49], v[180:183], v[196:199], v[46:49]
	v_mfma_f32_16x16x32_bf16 v[42:45], v[188:191], v[196:199], v[42:45]
	v_mfma_f32_16x16x32_bf16 v[30:33], v[180:183], v[204:207], v[30:33]
	v_mfma_f32_16x16x32_bf16 v[26:29], v[188:191], v[204:207], v[26:29]
	v_mfma_f32_16x16x32_bf16 v[14:17], v[180:183], v[214:217], v[14:17]
	v_mfma_f32_16x16x32_bf16 v[10:13], v[188:191], v[214:217], v[10:13]
	v_mfma_f32_16x16x32_bf16 v[6:9], v[180:183], v[222:225], v[6:9]
	v_mfma_f32_16x16x32_bf16 v[2:5], v[188:191], v[222:225], v[2:5]
	s_branch .Lmid_539
.LBB0_539:
	s_add_u32 s6, s92, s94
	s_addc_u32 s7, s93, s95
	s_add_u32 s6, s6, 0x10000
	s_addc_u32 s7, s7, 0
	s_add_i32 s65, 0, 0x10000
	s_cmp_eq_u32 s94, 0x30000
	s_cselect_b32 s7, s18, s7
	s_cselect_b32 s6, s19, s6
	v_add_u32_e32 v130, s65, v156
	s_cselect_b32 s51, s89, s29
	s_cselect_b32 s50, s88, s28
	s_add_i32 s34, 0, 0x14000
	ds_read_b128 v[160:163], v130
	ds_read_b128 v[164:167], v130 offset:1024
	ds_read_b128 v[168:171], v130 offset:2048
	ds_read_b128 v[172:175], v130 offset:3072
	v_add_u32_e32 v130, s34, v156
	ds_read_b128 v[176:179], v130
	ds_read_b128 v[180:183], v130 offset:1024
	ds_read_b128 v[184:187], v130 offset:2048
	ds_read_b128 v[188:191], v130 offset:3072
	v_lshl_add_u64 v[226:227], v[154:155], 0, s[94:95]
	s_mov_b64 s[54:55], 0xc000
	v_lshl_add_u64 v[228:229], v[226:227], 0, s[54:55]
	s_add_i32 m0, s11, 0xc000
	s_mov_b64 s[54:55], 0xe000
	ds_read_b128 v[192:195], v158
	ds_read_b128 v[196:199], v158 offset:1024
	ds_read_b128 v[200:203], v158 offset:2048
	ds_read_b128 v[204:207], v158 offset:3072
	ds_read_b128 v[210:213], v158 offset:4096
	ds_read_b128 v[214:217], v158 offset:5120
	ds_read_b128 v[218:221], v158 offset:6144
	ds_read_b128 v[222:225], v158 offset:7168
	global_load_lds_dwordx4 v[228:229], off
	v_lshl_add_u64 v[226:227], v[226:227], 0, s[54:55]
	s_add_i32 m0, s11, 0xe000
	s_nop 0
	global_load_lds_dwordx4 v[226:227], off
	s_waitcnt vmcnt(8)
	s_waitcnt lgkmcnt(0)
	s_barrier
	s_waitcnt lgkmcnt(0)
	v_mfma_f32_16x16x32_bf16 v[126:129], v[160:163], v[192:195], v[126:129]
	v_mfma_f32_16x16x32_bf16 v[122:125], v[168:171], v[192:195], v[122:125]
	v_mfma_f32_16x16x32_bf16 v[118:121], v[160:163], v[200:203], v[118:121]
	v_mfma_f32_16x16x32_bf16 v[114:117], v[168:171], v[200:203], v[114:117]
	v_mfma_f32_16x16x32_bf16 v[102:105], v[160:163], v[210:213], v[102:105]
	v_mfma_f32_16x16x32_bf16 v[98:101], v[168:171], v[210:213], v[98:101]
	v_mfma_f32_16x16x32_bf16 v[86:89], v[160:163], v[218:221], v[86:89]
	v_mfma_f32_16x16x32_bf16 v[82:85], v[168:171], v[218:221], v[82:85]
	v_mfma_f32_16x16x32_bf16 v[126:129], v[164:167], v[196:199], v[126:129]
	v_mfma_f32_16x16x32_bf16 v[122:125], v[172:175], v[196:199], v[122:125]
	v_mfma_f32_16x16x32_bf16 v[118:121], v[164:167], v[204:207], v[118:121]
	v_mfma_f32_16x16x32_bf16 v[114:117], v[172:175], v[204:207], v[114:117]
	v_mfma_f32_16x16x32_bf16 v[102:105], v[164:167], v[214:217], v[102:105]
	v_mfma_f32_16x16x32_bf16 v[98:101], v[172:175], v[214:217], v[98:101]
	v_mfma_f32_16x16x32_bf16 v[86:89], v[164:167], v[222:225], v[86:89]
	v_mfma_f32_16x16x32_bf16 v[82:85], v[172:175], v[222:225], v[82:85]
	v_mfma_f32_16x16x32_bf16 v[110:113], v[176:179], v[192:195], v[110:113]
	v_mfma_f32_16x16x32_bf16 v[106:109], v[184:187], v[192:195], v[106:109]
	v_mfma_f32_16x16x32_bf16 v[94:97], v[176:179], v[200:203], v[94:97]
	v_mfma_f32_16x16x32_bf16 v[90:93], v[184:187], v[200:203], v[90:93]
	v_mfma_f32_16x16x32_bf16 v[78:81], v[176:179], v[210:213], v[78:81]
	v_mfma_f32_16x16x32_bf16 v[74:77], v[184:187], v[210:213], v[74:77]
	v_mfma_f32_16x16x32_bf16 v[70:73], v[176:179], v[218:221], v[70:73]
	v_mfma_f32_16x16x32_bf16 v[66:69], v[184:187], v[218:221], v[66:69]
	v_mfma_f32_16x16x32_bf16 v[110:113], v[180:183], v[196:199], v[110:113]
	v_mfma_f32_16x16x32_bf16 v[106:109], v[188:191], v[196:199], v[106:109]
	v_mfma_f32_16x16x32_bf16 v[94:97], v[180:183], v[204:207], v[94:97]
	v_mfma_f32_16x16x32_bf16 v[90:93], v[188:191], v[204:207], v[90:93]
	v_mfma_f32_16x16x32_bf16 v[78:81], v[180:183], v[214:217], v[78:81]
	v_mfma_f32_16x16x32_bf16 v[74:77], v[188:191], v[214:217], v[74:77]
	v_mfma_f32_16x16x32_bf16 v[70:73], v[180:183], v[222:225], v[70:73]
	v_mfma_f32_16x16x32_bf16 v[66:69], v[188:191], v[222:225], v[66:69]
	s_barrier
; #define G8_STA(bufoff, ptr, sg, h) G8_STAGE1(bufoff, (ptr) + (h) * ((sg) ? hA1 : hA0), ((sg) ? voffA1 : voffA0), ((sg) ? r64A1 : r64A0))
; #define G8_STB(bufoff, ptr, sg, h) G8_STAGE1(bufoff, (ptr) + (h) * ((sg) ? hB1 : hB0), ((sg) ? voffB1 : voffB0), ((sg) ? r64B1 : r64B0))
; #define G8_LDA(dst, b, h) do { _Pragma("unroll") for (int m = 0; m < 4; ++m) _Pragma("unroll") for (int k = 0; k < 2; ++k) dst[m][k] = *(const LAS bf16x8*)(lds + G8_SA(b, h) + aoff + m * 2048 + k * 1024); } while (0)
; #define G8_MMA(ai, bj, At, Bt) do { __builtin_amdgcn_s_setprio(1); _Pragma("unroll") for (int m = 0; m < 4; ++m) _Pragma("unroll") for (int n = 0; n < 2; ++n) _Pragma("unroll") for (int k = 0; k < 2; ++k) \
;         acc[ai][bj][m][n] = __builtin_amdgcn_mfma_f32_16x16x32_bf16(Bt[n][k], At[m][k], acc[ai][bj][m][n], 0, 0, 0); __builtin_amdgcn_s_setprio(0); } while (0)
; #define G8_WAIT_V(n) asm volatile("s_waitcnt vmcnt(" #n ")" ::: "memory")
; #define G8_WAIT_L(n) asm volatile("s_waitcnt lgkmcnt(" #n ")" ::: "memory")
; #define G8_BAR __builtin_amdgcn_s_barrier()
; #define G8_SCHED __builtin_amdgcn_sched_barrier(0)
; template <class P>
; __device__ __forceinline__ void gemm_phase(LAS unsigned char* lds, const P& p, const int G, const int c) {
;     ...
;             G8_LDA(At, 0, 1); G8_STB(G8_SB(0, 0), b2, sg2, 0); G8_STB(G8_SB(0, 1), b2, sg2, 1); G8_STA(G8_SA(0, 0), a2, sg2, 0);
;             G8_WAIT_V(8); G8_WAIT_L(0); G8_BAR; G8_MMA(1, 0, At, B0); G8_MMA(1, 1, At, B1); G8_BAR; G8_SCHED;
	ds_read_b128 v[192:195], v158 offset:16384
	ds_read_b128 v[196:199], v158 offset:17408
	ds_read_b128 v[200:203], v158 offset:18432
	ds_read_b128 v[204:207], v158 offset:19456
	ds_read_b128 v[210:213], v158 offset:20480
	ds_read_b128 v[214:217], v158 offset:21504
	ds_read_b128 v[218:221], v158 offset:22528
	ds_read_b128 v[222:225], v158 offset:23552
	s_add_i32 s20, s65, s10
	s_mov_b32 m0, s20
	v_lshl_add_u64 v[226:227], s[50:51], 0, v[132:133]
	global_load_lds_dwordx4 v[226:227], off
	v_lshl_add_u64 v[228:229], v[226:227], 0, s[22:23]
	s_add_i32 m0, s20, 0x2000
	s_add_i32 s20, s34, s10
	global_load_lds_dwordx4 v[228:229], off
	v_lshl_add_u64 v[228:229], v[226:227], 0, s[36:37]
	s_mov_b32 m0, s20
	s_nop 0
	global_load_lds_dwordx4 v[228:229], off
	v_lshl_add_u64 v[228:229], v[226:227], 0, s[38:39]
	s_add_i32 m0, s20, 0x2000
	s_nop 0
	global_load_lds_dwordx4 v[228:229], off
	v_lshl_add_u64 v[228:229], s[6:7], 0, v[134:135]
	s_mov_b32 m0, s11
	v_lshl_add_u64 v[230:231], v[228:229], 0, s[22:23]
	global_load_lds_dwordx4 v[228:229], off
	s_mov_b32 m0, s14
	s_nop 0
	global_load_lds_dwordx4 v[230:231], off
	s_waitcnt vmcnt(8)
	s_waitcnt lgkmcnt(0)
	s_barrier
	s_waitcnt lgkmcnt(0)
	v_mfma_f32_16x16x32_bf16 v[62:65], v[160:163], v[192:195], v[62:65]
	v_mfma_f32_16x16x32_bf16 v[58:61], v[168:171], v[192:195], v[58:61]
	v_mfma_f32_16x16x32_bf16 v[54:57], v[160:163], v[200:203], v[54:57]
	v_mfma_f32_16x16x32_bf16 v[50:53], v[168:171], v[200:203], v[50:53]
	v_mfma_f32_16x16x32_bf16 v[38:41], v[160:163], v[210:213], v[38:41]
	v_mfma_f32_16x16x32_bf16 v[34:37], v[168:171], v[210:213], v[34:37]
	v_mfma_f32_16x16x32_bf16 v[22:25], v[160:163], v[218:221], v[22:25]
	v_mfma_f32_16x16x32_bf16 v[18:21], v[168:171], v[218:221], v[18:21]
	v_mfma_f32_16x16x32_bf16 v[62:65], v[164:167], v[196:199], v[62:65]
	v_mfma_f32_16x16x32_bf16 v[58:61], v[172:175], v[196:199], v[58:61]
	v_mfma_f32_16x16x32_bf16 v[54:57], v[164:167], v[204:207], v[54:57]
	v_mfma_f32_16x16x32_bf16 v[50:53], v[172:175], v[204:207], v[50:53]
	v_mfma_f32_16x16x32_bf16 v[38:41], v[164:167], v[214:217], v[38:41]
	v_mfma_f32_16x16x32_bf16 v[34:37], v[172:175], v[214:217], v[34:37]
	v_mfma_f32_16x16x32_bf16 v[22:25], v[164:167], v[222:225], v[22:25]
	v_mfma_f32_16x16x32_bf16 v[18:21], v[172:175], v[222:225], v[18:21]
	v_mfma_f32_16x16x32_bf16 v[46:49], v[176:179], v[192:195], v[46:49]
	v_mfma_f32_16x16x32_bf16 v[42:45], v[184:187], v[192:195], v[42:45]
	v_mfma_f32_16x16x32_bf16 v[30:33], v[176:179], v[200:203], v[30:33]
	v_mfma_f32_16x16x32_bf16 v[26:29], v[184:187], v[200:203], v[26:29]
	v_mfma_f32_16x16x32_bf16 v[14:17], v[176:179], v[210:213], v[14:17]
	v_mfma_f32_16x16x32_bf16 v[10:13], v[184:187], v[210:213], v[10:13]
	v_mfma_f32_16x16x32_bf16 v[6:9], v[176:179], v[218:221], v[6:9]
	v_mfma_f32_16x16x32_bf16 v[2:5], v[184:187], v[218:221], v[2:5]
	v_mfma_f32_16x16x32_bf16 v[46:49], v[180:183], v[196:199], v[46:49]
	v_mfma_f32_16x16x32_bf16 v[42:45], v[188:191], v[196:199], v[42:45]
	v_mfma_f32_16x16x32_bf16 v[30:33], v[180:183], v[204:207], v[30:33]
	v_mfma_f32_16x16x32_bf16 v[26:29], v[188:191], v[204:207], v[26:29]
	v_mfma_f32_16x16x32_bf16 v[14:17], v[180:183], v[214:217], v[14:17]
	v_mfma_f32_16x16x32_bf16 v[10:13], v[188:191], v[214:217], v[10:13]
	v_mfma_f32_16x16x32_bf16 v[6:9], v[180:183], v[222:225], v[6:9]
	v_mfma_f32_16x16x32_bf16 v[2:5], v[188:191], v[222:225], v[2:5]
; #define G8_STA(bufoff, ptr, sg, h) G8_STAGE1(bufoff, (ptr) + (h) * ((sg) ? hA1 : hA0), ((sg) ? voffA1 : voffA0), ((sg) ? r64A1 : r64A0))
; #define G8_STB(bufoff, ptr, sg, h) G8_STAGE1(bufoff, (ptr) + (h) * ((sg) ? hB1 : hB0), ((sg) ? voffB1 : voffB0), ((sg) ? r64B1 : r64B0))
; #define G8_LDA(dst, b, h) do { _Pragma("unroll") for (int m = 0; m < 4; ++m) _Pragma("unroll") for (int k = 0; k < 2; ++k) dst[m][k] = *(const LAS bf16x8*)(lds + G8_SA(b, h) + aoff + m * 2048 + k * 1024); } while (0)
; #define G8_LDB(dst, b, h) do { _Pragma("unroll") for (int n = 0; n < 2; ++n) _Pragma("unroll") for (int k = 0; k < 2; ++k) dst[n][k] = *(const LAS bf16x8*)(lds + G8_SB(b, h) + boff + n * 2048 + k * 1024); } while (0)
; #define G8_MMA(ai, bj, At, Bt) do { __builtin_amdgcn_s_setprio(1); _Pragma("unroll") for (int m = 0; m < 4; ++m) _Pragma("unroll") for (int n = 0; n < 2; ++n) _Pragma("unroll") for (int k = 0; k < 2; ++k) \
;         acc[ai][bj][m][n] = __builtin_amdgcn_mfma_f32_16x16x32_bf16(Bt[n][k], At[m][k], acc[ai][bj][m][n], 0, 0, 0); __builtin_amdgcn_s_setprio(0); } while (0)
; #define G8_WAIT_V(n) asm volatile("s_waitcnt vmcnt(" #n ")" ::: "memory")
; #define G8_WAIT_L(n) asm volatile("s_waitcnt lgkmcnt(" #n ")" ::: "memory")
; #define G8_BAR __builtin_amdgcn_s_barrier()
; #define G8_SCHED __builtin_amdgcn_sched_barrier(0)
; template <class P>
; __device__ __forceinline__ void gemm_phase(LAS unsigned char* lds, const P& p, const int G, const int c) {
;     ...
;             G8_LDB(B0, 1, 0); G8_LDB(B1, 1, 1); G8_SCHED; G8_LDA(At, 1, 0); G8_STA(G8_SA(0, 1), a2, sg2, 1);
;             G8_WAIT_V(8); G8_WAIT_L(0); G8_BAR; G8_MMA(0, 0, At, B0); G8_MMA(0, 1, At, B1); G8_BAR; G8_SCHED;
;             G8_LDA(At, 1, 1); G8_STB(G8_SB(1, 0), b3, sg2, 0); G8_STB(G8_SB(1, 1), b3, sg2, 1); G8_STA(G8_SA(1, 0), a3, sg2, 0);
;             G8_WAIT_V(8); G8_WAIT_L(0); G8_BAR; G8_MMA(1, 0, At, B0); G8_MMA(1, 1, At, B1); G8_BAR; G8_SCHED;
;         }
.Lmid_539:
	s_barrier
	s_add_i32 s35, 0, 0x18000
	v_add_u32_e32 v130, s35, v156
	s_add_i32 s20, 0, 0x1c000
	ds_read_b128 v[160:163], v130
	ds_read_b128 v[164:167], v130 offset:1024
	ds_read_b128 v[168:171], v130 offset:2048
	ds_read_b128 v[172:175], v130 offset:3072
	v_add_u32_e32 v130, s20, v156
	ds_read_b128 v[176:179], v130
	ds_read_b128 v[180:183], v130 offset:1024
	ds_read_b128 v[184:187], v130 offset:2048
	ds_read_b128 v[188:191], v130 offset:3072
	s_mov_b32 m0, s15
	v_lshl_add_u64 v[230:231], v[228:229], 0, s[36:37]
	ds_read_b128 v[192:195], v158 offset:32768
	ds_read_b128 v[196:199], v158 offset:33792
	ds_read_b128 v[200:203], v158 offset:34816
	ds_read_b128 v[204:207], v158 offset:35840
	ds_read_b128 v[210:213], v158 offset:36864
	ds_read_b128 v[214:217], v158 offset:37888
	ds_read_b128 v[218:221], v158 offset:38912
	ds_read_b128 v[222:225], v158 offset:39936
	global_load_lds_dwordx4 v[230:231], off
	v_lshl_add_u64 v[230:231], v[228:229], 0, s[38:39]
	s_mov_b32 m0, s16
	s_nop 0
	global_load_lds_dwordx4 v[230:231], off
	s_waitcnt vmcnt(8)
	s_waitcnt lgkmcnt(0)
	s_barrier
	s_waitcnt lgkmcnt(0)
	v_mfma_f32_16x16x32_bf16 v[126:129], v[160:163], v[192:195], v[126:129]
	v_mfma_f32_16x16x32_bf16 v[122:125], v[168:171], v[192:195], v[122:125]
	v_mfma_f32_16x16x32_bf16 v[118:121], v[160:163], v[200:203], v[118:121]
	v_mfma_f32_16x16x32_bf16 v[114:117], v[168:171], v[200:203], v[114:117]
	v_mfma_f32_16x16x32_bf16 v[102:105], v[160:163], v[210:213], v[102:105]
	v_mfma_f32_16x16x32_bf16 v[98:101], v[168:171], v[210:213], v[98:101]
	v_mfma_f32_16x16x32_bf16 v[86:89], v[160:163], v[218:221], v[86:89]
	v_mfma_f32_16x16x32_bf16 v[82:85], v[168:171], v[218:221], v[82:85]
	v_mfma_f32_16x16x32_bf16 v[126:129], v[164:167], v[196:199], v[126:129]
	v_mfma_f32_16x16x32_bf16 v[122:125], v[172:175], v[196:199], v[122:125]
	v_mfma_f32_16x16x32_bf16 v[118:121], v[164:167], v[204:207], v[118:121]
	v_mfma_f32_16x16x32_bf16 v[114:117], v[172:175], v[204:207], v[114:117]
	v_mfma_f32_16x16x32_bf16 v[102:105], v[164:167], v[214:217], v[102:105]
	v_mfma_f32_16x16x32_bf16 v[98:101], v[172:175], v[214:217], v[98:101]
	v_mfma_f32_16x16x32_bf16 v[86:89], v[164:167], v[222:225], v[86:89]
	v_mfma_f32_16x16x32_bf16 v[82:85], v[172:175], v[222:225], v[82:85]
	v_mfma_f32_16x16x32_bf16 v[110:113], v[176:179], v[192:195], v[110:113]
	v_mfma_f32_16x16x32_bf16 v[106:109], v[184:187], v[192:195], v[106:109]
	v_mfma_f32_16x16x32_bf16 v[94:97], v[176:179], v[200:203], v[94:97]
	v_mfma_f32_16x16x32_bf16 v[90:93], v[184:187], v[200:203], v[90:93]
	v_mfma_f32_16x16x32_bf16 v[78:81], v[176:179], v[210:213], v[78:81]
	v_mfma_f32_16x16x32_bf16 v[74:77], v[184:187], v[210:213], v[74:77]
	v_mfma_f32_16x16x32_bf16 v[70:73], v[176:179], v[218:221], v[70:73]
	v_mfma_f32_16x16x32_bf16 v[66:69], v[184:187], v[218:221], v[66:69]
	v_mfma_f32_16x16x32_bf16 v[110:113], v[180:183], v[196:199], v[110:113]
	v_mfma_f32_16x16x32_bf16 v[106:109], v[188:191], v[196:199], v[106:109]
	v_mfma_f32_16x16x32_bf16 v[94:97], v[180:183], v[204:207], v[94:97]
	v_mfma_f32_16x16x32_bf16 v[90:93], v[188:191], v[204:207], v[90:93]
	v_mfma_f32_16x16x32_bf16 v[78:81], v[180:183], v[214:217], v[78:81]
	v_mfma_f32_16x16x32_bf16 v[74:77], v[188:191], v[214:217], v[74:77]
	v_mfma_f32_16x16x32_bf16 v[70:73], v[180:183], v[222:225], v[70:73]
	v_mfma_f32_16x16x32_bf16 v[66:69], v[188:191], v[222:225], v[66:69]
	s_barrier
	ds_read_b128 v[192:195], v158 offset:49152
	ds_read_b128 v[196:199], v158 offset:50176
	ds_read_b128 v[200:203], v158 offset:51200
	ds_read_b128 v[204:207], v158 offset:52224
	ds_read_b128 v[210:213], v158 offset:53248
	ds_read_b128 v[214:217], v158 offset:54272
	ds_read_b128 v[218:221], v158 offset:55296
	ds_read_b128 v[222:225], v158 offset:56320
	s_add_i32 s6, s35, s10
	s_mov_b32 m0, s6
	v_lshl_add_u64 v[230:231], v[226:227], 0, s[40:41]
	global_load_lds_dwordx4 v[230:231], off
	v_lshl_add_u64 v[230:231], v[226:227], 0, s[42:43]
	s_add_i32 m0, s6, 0x2000
	s_add_i32 s6, s20, s10
	global_load_lds_dwordx4 v[230:231], off
	v_lshl_add_u64 v[230:231], v[226:227], 0, s[48:49]
	s_mov_b32 m0, s6
	v_lshl_add_u64 v[226:227], v[226:227], 0, s[52:53]
	global_load_lds_dwordx4 v[230:231], off
	s_add_i32 m0, s6, 0x2000
	s_nop 0
	global_load_lds_dwordx4 v[226:227], off
	v_lshl_add_u64 v[226:227], v[228:229], 0, s[8:9]
	s_mov_b32 m0, s24
	s_nop 0
	global_load_lds_dwordx4 v[226:227], off
	v_lshl_add_u64 v[226:227], v[228:229], 0, s[44:45]
	s_mov_b32 m0, s25
	s_nop 0
	global_load_lds_dwordx4 v[226:227], off
	s_waitcnt vmcnt(8)
	s_waitcnt lgkmcnt(0)
	s_barrier
	s_waitcnt lgkmcnt(0)
	v_mfma_f32_16x16x32_bf16 v[62:65], v[160:163], v[192:195], v[62:65]
	v_mfma_f32_16x16x32_bf16 v[58:61], v[168:171], v[192:195], v[58:61]
	v_mfma_f32_16x16x32_bf16 v[54:57], v[160:163], v[200:203], v[54:57]
	v_mfma_f32_16x16x32_bf16 v[50:53], v[168:171], v[200:203], v[50:53]
	s_add_i32 s47, s47, 2
	v_mfma_f32_16x16x32_bf16 v[38:41], v[160:163], v[210:213], v[38:41]
	s_add_u32 s28, s28, 0x40000
	v_mfma_f32_16x16x32_bf16 v[34:37], v[168:171], v[210:213], v[34:37]
	s_addc_u32 s29, s29, 0
	v_mfma_f32_16x16x32_bf16 v[22:25], v[160:163], v[218:221], v[22:25]
	s_add_u32 s94, s94, 0x10000
	v_mfma_f32_16x16x32_bf16 v[18:21], v[168:171], v[218:221], v[18:21]
	s_addc_u32 s95, s95, 0
	v_mfma_f32_16x16x32_bf16 v[62:65], v[164:167], v[196:199], v[62:65]
	s_cmp_gt_u32 s47, 5
	v_mfma_f32_16x16x32_bf16 v[58:61], v[172:175], v[196:199], v[58:61]
	v_mfma_f32_16x16x32_bf16 v[54:57], v[164:167], v[204:207], v[54:57]
	v_mfma_f32_16x16x32_bf16 v[50:53], v[172:175], v[204:207], v[50:53]
	v_mfma_f32_16x16x32_bf16 v[38:41], v[164:167], v[214:217], v[38:41]
	v_mfma_f32_16x16x32_bf16 v[34:37], v[172:175], v[214:217], v[34:37]
	v_mfma_f32_16x16x32_bf16 v[22:25], v[164:167], v[222:225], v[22:25]
	v_mfma_f32_16x16x32_bf16 v[18:21], v[172:175], v[222:225], v[18:21]
	v_mfma_f32_16x16x32_bf16 v[46:49], v[176:179], v[192:195], v[46:49]
	v_mfma_f32_16x16x32_bf16 v[42:45], v[184:187], v[192:195], v[42:45]
	v_mfma_f32_16x16x32_bf16 v[30:33], v[176:179], v[200:203], v[30:33]
	v_mfma_f32_16x16x32_bf16 v[26:29], v[184:187], v[200:203], v[26:29]
	v_mfma_f32_16x16x32_bf16 v[14:17], v[176:179], v[210:213], v[14:17]
	v_mfma_f32_16x16x32_bf16 v[10:13], v[184:187], v[210:213], v[10:13]
	v_mfma_f32_16x16x32_bf16 v[6:9], v[176:179], v[218:221], v[6:9]
	v_mfma_f32_16x16x32_bf16 v[2:5], v[184:187], v[218:221], v[2:5]
	v_mfma_f32_16x16x32_bf16 v[46:49], v[180:183], v[196:199], v[46:49]
	v_mfma_f32_16x16x32_bf16 v[42:45], v[188:191], v[196:199], v[42:45]
	v_mfma_f32_16x16x32_bf16 v[30:33], v[180:183], v[204:207], v[30:33]
	v_mfma_f32_16x16x32_bf16 v[26:29], v[188:191], v[204:207], v[26:29]
	v_mfma_f32_16x16x32_bf16 v[14:17], v[180:183], v[214:217], v[14:17]
	v_mfma_f32_16x16x32_bf16 v[10:13], v[188:191], v[214:217], v[10:13]
	v_mfma_f32_16x16x32_bf16 v[6:9], v[180:183], v[222:225], v[6:9]
	v_mfma_f32_16x16x32_bf16 v[2:5], v[188:191], v[222:225], v[2:5]
	s_barrier
	s_cbranch_scc0 .LBB0_539
	s_and_b64 vcc, exec, s[86:87]
	s_cbranch_vccz .LBB0_542
	s_barrier

; #define G8_STA(bufoff, ptr, sg, h) G8_STAGE1(bufoff, (ptr) + (h) * ((sg) ? hA1 : hA0), ((sg) ? voffA1 : voffA0), ((sg) ? r64A1 : r64A0))
; #define G8_STB(bufoff, ptr, sg, h) G8_STAGE1(bufoff, (ptr) + (h) * ((sg) ? hB1 : hB0), ((sg) ? voffB1 : voffB0), ((sg) ? r64B1 : r64B0))
; #define G8_LDA(dst, b, h) do { _Pragma("unroll") for (int m = 0; m < 4; ++m) _Pragma("unroll") for (int k = 0; k < 2; ++k) dst[m][k] = *(const LAS bf16x8*)(lds + G8_SA(b, h) + aoff + m * 2048 + k * 1024); } while (0)
; #define G8_LDB(dst, b, h) do { _Pragma("unroll") for (int n = 0; n < 2; ++n) _Pragma("unroll") for (int k = 0; k < 2; ++k) dst[n][k] = *(const LAS bf16x8*)(lds + G8_SB(b, h) + boff + n * 2048 + k * 1024); } while (0)
; #define G8_MMA(ai, bj, At, Bt) do { __builtin_amdgcn_s_setprio(1); _Pragma("unroll") for (int m = 0; m < 4; ++m) _Pragma("unroll") for (int n = 0; n < 2; ++n) _Pragma("unroll") for (int k = 0; k < 2; ++k) \
;         acc[ai][bj][m][n] = __builtin_amdgcn_mfma_f32_16x16x32_bf16(Bt[n][k], At[m][k], acc[ai][bj][m][n], 0, 0, 0); __builtin_amdgcn_s_setprio(0); } while (0)
; #define G8_WAIT_V(n) asm volatile("s_waitcnt vmcnt(" #n ")" ::: "memory")
; #define G8_WAIT_L(n) asm volatile("s_waitcnt lgkmcnt(" #n ")" ::: "memory")
; #define G8_BAR __builtin_amdgcn_s_barrier()
; #define G8_SCHED __builtin_amdgcn_sched_barrier(0)
; template <class P>
; __device__ __forceinline__ void gemm_phase(LAS unsigned char* lds, const P& p, const int G, const int c) {
;     ...
;             G8_LDB(B0, 0, 0); G8_LDB(B1, 0, 1); G8_SCHED; G8_LDA(At, 0, 0); G8_STA(G8_SA(1, 1), a1, sg1, 1);
;             G8_WAIT_V(8); G8_WAIT_L(0); G8_BAR; G8_MMA(0, 0, At, B0); G8_MMA(0, 1, At, B1); G8_BAR; G8_SCHED;
;             G8_LDA(At, 0, 1); G8_STB(G8_SB(0, 0), b2, sg2, 0); G8_STB(G8_SB(0, 1), b2, sg2, 1); G8_STA(G8_SA(0, 0), a2, sg2, 0);
;             G8_WAIT_V(8); G8_WAIT_L(0); G8_BAR; G8_MMA(1, 0, At, B0); G8_MMA(1, 1, At, B1); G8_BAR; G8_SCHED;
.Lpeel_679:
	v_add_u32_e32 v153, s50, v1
	ds_read_b128 v[170:173], v153
	ds_read_b128 v[174:177], v153 offset:1024
	ds_read_b128 v[178:181], v153 offset:2048
	ds_read_b128 v[182:185], v153 offset:3072
	v_add_u32_e32 v153, s51, v1
	ds_read_b128 v[186:189], v153
	ds_read_b128 v[190:193], v153 offset:1024
	ds_read_b128 v[194:197], v153 offset:2048
	ds_read_b128 v[198:201], v153 offset:3072
	s_and_b64 s[30:31], exec, s[30:31]
	s_cselect_b32 s31, s18, s59
	s_cselect_b32 s30, s19, s53
	v_lshl_add_u64 v[206:207], v[168:169], 0, s[62:63]
	v_lshl_add_u64 v[238:239], v[206:207], 0, s[40:41]
	s_add_i32 m0, s27, 0xc000
	ds_read_b128 v[202:205], v151
	ds_read_b128 v[210:213], v151 offset:1024
	ds_read_b128 v[214:217], v151 offset:2048
	ds_read_b128 v[218:221], v151 offset:3072
	ds_read_b128 v[222:225], v151 offset:4096
	ds_read_b128 v[226:229], v151 offset:5120
	ds_read_b128 v[230:233], v151 offset:6144
	ds_read_b128 v[234:237], v151 offset:7168
	global_load_lds_dwordx4 v[238:239], off
	v_lshl_add_u64 v[206:207], v[206:207], 0, s[42:43]
	s_add_i32 m0, s27, 0xe000
	s_nop 0
	global_load_lds_dwordx4 v[206:207], off
	s_waitcnt vmcnt(8)
	s_waitcnt lgkmcnt(0)
	s_barrier
	s_waitcnt lgkmcnt(0)
	v_mfma_f32_16x16x32_bf16 v[126:129], v[170:173], v[202:205], 0
	v_mfma_f32_16x16x32_bf16 v[122:125], v[178:181], v[202:205], 0
	v_mfma_f32_16x16x32_bf16 v[110:113], v[170:173], v[214:217], 0
	v_mfma_f32_16x16x32_bf16 v[106:109], v[178:181], v[214:217], 0
	v_mfma_f32_16x16x32_bf16 v[94:97], v[170:173], v[222:225], 0
	v_mfma_f32_16x16x32_bf16 v[90:93], v[178:181], v[222:225], 0
	v_mfma_f32_16x16x32_bf16 v[78:81], v[170:173], v[230:233], 0
	v_mfma_f32_16x16x32_bf16 v[74:77], v[178:181], v[230:233], 0
	v_mfma_f32_16x16x32_bf16 v[126:129], v[174:177], v[210:213], v[126:129]
	v_mfma_f32_16x16x32_bf16 v[122:125], v[182:185], v[210:213], v[122:125]
	v_mfma_f32_16x16x32_bf16 v[110:113], v[174:177], v[218:221], v[110:113]
	v_mfma_f32_16x16x32_bf16 v[106:109], v[182:185], v[218:221], v[106:109]
	v_mfma_f32_16x16x32_bf16 v[94:97], v[174:177], v[226:229], v[94:97]
	v_mfma_f32_16x16x32_bf16 v[90:93], v[182:185], v[226:229], v[90:93]
	v_mfma_f32_16x16x32_bf16 v[78:81], v[174:177], v[234:237], v[78:81]
	v_mfma_f32_16x16x32_bf16 v[74:77], v[182:185], v[234:237], v[74:77]
	v_mfma_f32_16x16x32_bf16 v[118:121], v[186:189], v[202:205], 0
	v_mfma_f32_16x16x32_bf16 v[114:117], v[194:197], v[202:205], 0
	v_mfma_f32_16x16x32_bf16 v[102:105], v[186:189], v[214:217], 0
	v_mfma_f32_16x16x32_bf16 v[98:101], v[194:197], v[214:217], 0
	v_mfma_f32_16x16x32_bf16 v[86:89], v[186:189], v[222:225], 0
	v_mfma_f32_16x16x32_bf16 v[82:85], v[194:197], v[222:225], 0
	v_mfma_f32_16x16x32_bf16 v[70:73], v[186:189], v[230:233], 0
	v_mfma_f32_16x16x32_bf16 v[66:69], v[194:197], v[230:233], 0
	v_mfma_f32_16x16x32_bf16 v[118:121], v[190:193], v[210:213], v[118:121]
	v_mfma_f32_16x16x32_bf16 v[114:117], v[198:201], v[210:213], v[114:117]
	v_mfma_f32_16x16x32_bf16 v[102:105], v[190:193], v[218:221], v[102:105]
	v_mfma_f32_16x16x32_bf16 v[98:101], v[198:201], v[218:221], v[98:101]
	v_mfma_f32_16x16x32_bf16 v[86:89], v[190:193], v[226:229], v[86:89]
	v_mfma_f32_16x16x32_bf16 v[82:85], v[198:201], v[226:229], v[82:85]
	v_mfma_f32_16x16x32_bf16 v[70:73], v[190:193], v[234:237], v[70:73]
	v_mfma_f32_16x16x32_bf16 v[66:69], v[198:201], v[234:237], v[66:69]
	s_barrier
	ds_read_b128 v[202:205], v151 offset:16384
	ds_read_b128 v[210:213], v151 offset:17408
	ds_read_b128 v[214:217], v151 offset:18432
	ds_read_b128 v[218:221], v151 offset:19456
	ds_read_b128 v[222:225], v151 offset:20480
	ds_read_b128 v[226:229], v151 offset:21504
	ds_read_b128 v[230:233], v151 offset:22528
	ds_read_b128 v[234:237], v151 offset:23552
	v_lshl_add_u64 v[206:207], s[30:31], 0, v[130:131]
	s_add_i32 s30, s50, s26
	s_mov_b32 m0, s30
	s_nop 0
	global_load_lds_dwordx4 v[206:207], off
	v_lshl_add_u64 v[238:239], v[206:207], 0, s[0:1]
	s_add_i32 m0, s30, 0x2000
	s_add_i32 s30, s51, s26
	global_load_lds_dwordx4 v[238:239], off
	v_lshl_add_u64 v[238:239], v[206:207], 0, s[4:5]
	s_mov_b32 m0, s30
	s_nop 0
	global_load_lds_dwordx4 v[238:239], off
	v_lshl_add_u64 v[238:239], v[206:207], 0, s[6:7]
	s_add_i32 m0, s30, 0x2000
	s_nop 0
	global_load_lds_dwordx4 v[238:239], off
	v_lshl_add_u64 v[238:239], s[28:29], 0, v[132:133]
	s_mov_b32 m0, s27
	v_lshl_add_u64 v[240:241], v[238:239], 0, s[0:1]
	global_load_lds_dwordx4 v[238:239], off
	s_mov_b32 m0, s33
	s_nop 0
	global_load_lds_dwordx4 v[240:241], off
	s_waitcnt vmcnt(8)
	s_waitcnt lgkmcnt(0)
	s_barrier
	s_waitcnt lgkmcnt(0)
	v_mfma_f32_16x16x32_bf16 v[62:65], v[170:173], v[202:205], 0
	v_mfma_f32_16x16x32_bf16 v[58:61], v[178:181], v[202:205], 0
	v_mfma_f32_16x16x32_bf16 v[46:49], v[170:173], v[214:217], 0
	v_mfma_f32_16x16x32_bf16 v[42:45], v[178:181], v[214:217], 0
	v_mfma_f32_16x16x32_bf16 v[30:33], v[170:173], v[222:225], 0
	v_mfma_f32_16x16x32_bf16 v[26:29], v[178:181], v[222:225], 0
	v_mfma_f32_16x16x32_bf16 v[14:17], v[170:173], v[230:233], 0
	v_mfma_f32_16x16x32_bf16 v[10:13], v[178:181], v[230:233], 0
	v_mfma_f32_16x16x32_bf16 v[62:65], v[174:177], v[210:213], v[62:65]
	v_mfma_f32_16x16x32_bf16 v[58:61], v[182:185], v[210:213], v[58:61]
	v_mfma_f32_16x16x32_bf16 v[46:49], v[174:177], v[218:221], v[46:49]
	v_mfma_f32_16x16x32_bf16 v[42:45], v[182:185], v[218:221], v[42:45]
	v_mfma_f32_16x16x32_bf16 v[30:33], v[174:177], v[226:229], v[30:33]
	v_mfma_f32_16x16x32_bf16 v[26:29], v[182:185], v[226:229], v[26:29]
	v_mfma_f32_16x16x32_bf16 v[14:17], v[174:177], v[234:237], v[14:17]
	v_mfma_f32_16x16x32_bf16 v[10:13], v[182:185], v[234:237], v[10:13]
	v_mfma_f32_16x16x32_bf16 v[54:57], v[186:189], v[202:205], 0
	v_mfma_f32_16x16x32_bf16 v[50:53], v[194:197], v[202:205], 0
	v_mfma_f32_16x16x32_bf16 v[38:41], v[186:189], v[214:217], 0
	v_mfma_f32_16x16x32_bf16 v[34:37], v[194:197], v[214:217], 0
	v_mfma_f32_16x16x32_bf16 v[22:25], v[186:189], v[222:225], 0
	v_mfma_f32_16x16x32_bf16 v[18:21], v[194:197], v[222:225], 0
	v_mfma_f32_16x16x32_bf16 v[6:9], v[186:189], v[230:233], 0
	v_mfma_f32_16x16x32_bf16 v[2:5], v[194:197], v[230:233], 0
	v_mfma_f32_16x16x32_bf16 v[54:57], v[190:193], v[210:213], v[54:57]
	v_mfma_f32_16x16x32_bf16 v[50:53], v[198:201], v[210:213], v[50:53]
	v_mfma_f32_16x16x32_bf16 v[38:41], v[190:193], v[218:221], v[38:41]
	v_mfma_f32_16x16x32_bf16 v[34:37], v[198:201], v[218:221], v[34:37]
	v_mfma_f32_16x16x32_bf16 v[22:25], v[190:193], v[226:229], v[22:25]
	v_mfma_f32_16x16x32_bf16 v[18:21], v[198:201], v[226:229], v[18:21]
	v_mfma_f32_16x16x32_bf16 v[6:9], v[190:193], v[234:237], v[6:9]
	v_mfma_f32_16x16x32_bf16 v[2:5], v[198:201], v[234:237], v[2:5]
	s_branch .Lmid_679
; #define G8_STA(bufoff, ptr, sg, h) G8_STAGE1(bufoff, (ptr) + (h) * ((sg) ? hA1 : hA0), ((sg) ? voffA1 : voffA0), ((sg) ? r64A1 : r64A0))
; #define G8_STB(bufoff, ptr, sg, h) G8_STAGE1(bufoff, (ptr) + (h) * ((sg) ? hB1 : hB0), ((sg) ? voffB1 : voffB0), ((sg) ? r64B1 : r64B0))
; #define G8_LDA(dst, b, h) do { _Pragma("unroll") for (int m = 0; m < 4; ++m) _Pragma("unroll") for (int k = 0; k < 2; ++k) dst[m][k] = *(const LAS bf16x8*)(lds + G8_SA(b, h) + aoff + m * 2048 + k * 1024); } while (0)
; #define G8_LDB(dst, b, h) do { _Pragma("unroll") for (int n = 0; n < 2; ++n) _Pragma("unroll") for (int k = 0; k < 2; ++k) dst[n][k] = *(const LAS bf16x8*)(lds + G8_SB(b, h) + boff + n * 2048 + k * 1024); } while (0)
; #define G8_MMA(ai, bj, At, Bt) do { __builtin_amdgcn_s_setprio(1); _Pragma("unroll") for (int m = 0; m < 4; ++m) _Pragma("unroll") for (int n = 0; n < 2; ++n) _Pragma("unroll") for (int k = 0; k < 2; ++k) \
;         acc[ai][bj][m][n] = __builtin_amdgcn_mfma_f32_16x16x32_bf16(Bt[n][k], At[m][k], acc[ai][bj][m][n], 0, 0, 0); __builtin_amdgcn_s_setprio(0); } while (0)
; #define G8_BAR __builtin_amdgcn_s_barrier()
; template <class P>
; __device__ __forceinline__ void gemm_phase(LAS unsigned char* lds, const P& p, const int G, const int c) {
;     ...
;         for (int t = 0; t < nt; t += 2) {
;             const bool last = (t == nt - 2);
;             const bool sg1 = (NS > 1) && (t + 1 >= nt0);
;             const bool sg2 = (NS > 1) && !last && (t + 2 >= nt0);
;             const char* a1 = sg1 ? cA1 + (long)(t + 1 - nt0) * ksA1 : cA0 + (long)(t + 1) * ksA0;
;             const char* a2 = last ? nA0 : (sg2 ? cA1 + (long)(t + 2 - nt0) * ksA1 : cA0 + (long)(t + 2) * ksA0);
;             const char* b2 = last ? nB0 : (sg2 ? cB1 + (long)(t + 2 - nt0) * ksB1 : cB0 + (long)(t + 2) * ksB0);
;             const char* a3 = a2 + (sg2 ? ksA1 : ksA0); const char* b3 = b2 + (sg2 ? ksB1 : ksB0);
;             G8_LDB(B0, 0, 0); G8_LDB(B1, 0, 1); G8_SCHED; G8_LDA(At, 0, 0); G8_STA(G8_SA(1, 1), a1, sg1, 1);
;             G8_WAIT_V(8); G8_WAIT_L(0); G8_BAR; G8_MMA(0, 0, At, B0); G8_MMA(0, 1, At, B1); G8_BAR; G8_SCHED;
;             G8_LDA(At, 0, 1); G8_STB(G8_SB(0, 0), b2, sg2, 0); G8_STB(G8_SB(0, 1), b2, sg2, 1); G8_STA(G8_SA(0, 0), a2, sg2, 0);
;             G8_WAIT_V(8); G8_WAIT_L(0); G8_BAR; G8_MMA(1, 0, At, B0); G8_MMA(1, 1, At, B1); G8_BAR; G8_SCHED;
.LBB0_679:
	v_add_u32_e32 v153, s50, v1
	ds_read_b128 v[170:173], v153
	ds_read_b128 v[174:177], v153 offset:1024
	ds_read_b128 v[178:181], v153 offset:2048
	ds_read_b128 v[182:185], v153 offset:3072
	v_add_u32_e32 v153, s51, v1
	ds_read_b128 v[186:189], v153
	ds_read_b128 v[190:193], v153 offset:1024
	ds_read_b128 v[194:197], v153 offset:2048
	ds_read_b128 v[198:201], v153 offset:3072
	s_and_b64 s[30:31], exec, s[30:31]
	s_cselect_b32 s31, s18, s59
	s_cselect_b32 s30, s19, s53
	v_lshl_add_u64 v[206:207], v[168:169], 0, s[62:63]
	v_lshl_add_u64 v[238:239], v[206:207], 0, s[40:41]
	s_add_i32 m0, s27, 0xc000
	ds_read_b128 v[202:205], v151
	ds_read_b128 v[210:213], v151 offset:1024
	ds_read_b128 v[214:217], v151 offset:2048
	ds_read_b128 v[218:221], v151 offset:3072
	ds_read_b128 v[222:225], v151 offset:4096
	ds_read_b128 v[226:229], v151 offset:5120
	ds_read_b128 v[230:233], v151 offset:6144
	ds_read_b128 v[234:237], v151 offset:7168
	global_load_lds_dwordx4 v[238:239], off
	v_lshl_add_u64 v[206:207], v[206:207], 0, s[42:43]
	s_add_i32 m0, s27, 0xe000
	s_nop 0
	global_load_lds_dwordx4 v[206:207], off
	s_waitcnt vmcnt(8)
	s_waitcnt lgkmcnt(0)
	s_barrier
	s_waitcnt lgkmcnt(0)
	v_mfma_f32_16x16x32_bf16 v[126:129], v[170:173], v[202:205], v[126:129]
	v_mfma_f32_16x16x32_bf16 v[122:125], v[178:181], v[202:205], v[122:125]
	v_mfma_f32_16x16x32_bf16 v[110:113], v[170:173], v[214:217], v[110:113]
	v_mfma_f32_16x16x32_bf16 v[106:109], v[178:181], v[214:217], v[106:109]
	v_mfma_f32_16x16x32_bf16 v[94:97], v[170:173], v[222:225], v[94:97]
	v_mfma_f32_16x16x32_bf16 v[90:93], v[178:181], v[222:225], v[90:93]
	v_mfma_f32_16x16x32_bf16 v[78:81], v[170:173], v[230:233], v[78:81]
	v_mfma_f32_16x16x32_bf16 v[74:77], v[178:181], v[230:233], v[74:77]
	v_mfma_f32_16x16x32_bf16 v[126:129], v[174:177], v[210:213], v[126:129]
	v_mfma_f32_16x16x32_bf16 v[122:125], v[182:185], v[210:213], v[122:125]
	v_mfma_f32_16x16x32_bf16 v[110:113], v[174:177], v[218:221], v[110:113]
	v_mfma_f32_16x16x32_bf16 v[106:109], v[182:185], v[218:221], v[106:109]
	v_mfma_f32_16x16x32_bf16 v[94:97], v[174:177], v[226:229], v[94:97]
	v_mfma_f32_16x16x32_bf16 v[90:93], v[182:185], v[226:229], v[90:93]
	v_mfma_f32_16x16x32_bf16 v[78:81], v[174:177], v[234:237], v[78:81]
	v_mfma_f32_16x16x32_bf16 v[74:77], v[182:185], v[234:237], v[74:77]
	v_mfma_f32_16x16x32_bf16 v[118:121], v[186:189], v[202:205], v[118:121]
	v_mfma_f32_16x16x32_bf16 v[114:117], v[194:197], v[202:205], v[114:117]
	v_mfma_f32_16x16x32_bf16 v[102:105], v[186:189], v[214:217], v[102:105]
	v_mfma_f32_16x16x32_bf16 v[98:101], v[194:197], v[214:217], v[98:101]
	v_mfma_f32_16x16x32_bf16 v[86:89], v[186:189], v[222:225], v[86:89]
	v_mfma_f32_16x16x32_bf16 v[82:85], v[194:197], v[222:225], v[82:85]
	v_mfma_f32_16x16x32_bf16 v[70:73], v[186:189], v[230:233], v[70:73]
	v_mfma_f32_16x16x32_bf16 v[66:69], v[194:197], v[230:233], v[66:69]
	v_mfma_f32_16x16x32_bf16 v[118:121], v[190:193], v[210:213], v[118:121]
	v_mfma_f32_16x16x32_bf16 v[114:117], v[198:201], v[210:213], v[114:117]
	v_mfma_f32_16x16x32_bf16 v[102:105], v[190:193], v[218:221], v[102:105]
	v_mfma_f32_16x16x32_bf16 v[98:101], v[198:201], v[218:221], v[98:101]
	v_mfma_f32_16x16x32_bf16 v[86:89], v[190:193], v[226:229], v[86:89]
	v_mfma_f32_16x16x32_bf16 v[82:85], v[198:201], v[226:229], v[82:85]
	v_mfma_f32_16x16x32_bf16 v[70:73], v[190:193], v[234:237], v[70:73]
	v_mfma_f32_16x16x32_bf16 v[66:69], v[198:201], v[234:237], v[66:69]
	s_barrier
	ds_read_b128 v[202:205], v151 offset:16384
	ds_read_b128 v[210:213], v151 offset:17408
	ds_read_b128 v[214:217], v151 offset:18432
	ds_read_b128 v[218:221], v151 offset:19456
	ds_read_b128 v[222:225], v151 offset:20480
	ds_read_b128 v[226:229], v151 offset:21504
	ds_read_b128 v[230:233], v151 offset:22528
	ds_read_b128 v[234:237], v151 offset:23552
	v_lshl_add_u64 v[206:207], s[30:31], 0, v[130:131]
	s_add_i32 s30, s50, s26
	s_mov_b32 m0, s30
	s_nop 0
	global_load_lds_dwordx4 v[206:207], off
	v_lshl_add_u64 v[238:239], v[206:207], 0, s[0:1]
	s_add_i32 m0, s30, 0x2000
	s_add_i32 s30, s51, s26
	global_load_lds_dwordx4 v[238:239], off
	v_lshl_add_u64 v[238:239], v[206:207], 0, s[4:5]
	s_mov_b32 m0, s30
	s_nop 0
	global_load_lds_dwordx4 v[238:239], off
	v_lshl_add_u64 v[238:239], v[206:207], 0, s[6:7]
	s_add_i32 m0, s30, 0x2000
	s_nop 0
	global_load_lds_dwordx4 v[238:239], off
	v_lshl_add_u64 v[238:239], s[28:29], 0, v[132:133]
	s_mov_b32 m0, s27
	v_lshl_add_u64 v[240:241], v[238:239], 0, s[0:1]
	global_load_lds_dwordx4 v[238:239], off
	s_mov_b32 m0, s33
	s_nop 0
	global_load_lds_dwordx4 v[240:241], off
	s_waitcnt vmcnt(8)
	s_waitcnt lgkmcnt(0)
	s_barrier
	s_waitcnt lgkmcnt(0)
	v_mfma_f32_16x16x32_bf16 v[62:65], v[170:173], v[202:205], v[62:65]
	v_mfma_f32_16x16x32_bf16 v[58:61], v[178:181], v[202:205], v[58:61]
	v_mfma_f32_16x16x32_bf16 v[46:49], v[170:173], v[214:217], v[46:49]
	v_mfma_f32_16x16x32_bf16 v[42:45], v[178:181], v[214:217], v[42:45]
	v_mfma_f32_16x16x32_bf16 v[30:33], v[170:173], v[222:225], v[30:33]
	v_mfma_f32_16x16x32_bf16 v[26:29], v[178:181], v[222:225], v[26:29]
	v_mfma_f32_16x16x32_bf16 v[14:17], v[170:173], v[230:233], v[14:17]
	v_mfma_f32_16x16x32_bf16 v[10:13], v[178:181], v[230:233], v[10:13]
	v_mfma_f32_16x16x32_bf16 v[62:65], v[174:177], v[210:213], v[62:65]
	v_mfma_f32_16x16x32_bf16 v[58:61], v[182:185], v[210:213], v[58:61]
	v_mfma_f32_16x16x32_bf16 v[46:49], v[174:177], v[218:221], v[46:49]
	v_mfma_f32_16x16x32_bf16 v[42:45], v[182:185], v[218:221], v[42:45]
	v_mfma_f32_16x16x32_bf16 v[30:33], v[174:177], v[226:229], v[30:33]
	v_mfma_f32_16x16x32_bf16 v[26:29], v[182:185], v[226:229], v[26:29]
	v_mfma_f32_16x16x32_bf16 v[14:17], v[174:177], v[234:237], v[14:17]
	v_mfma_f32_16x16x32_bf16 v[10:13], v[182:185], v[234:237], v[10:13]
	v_mfma_f32_16x16x32_bf16 v[54:57], v[186:189], v[202:205], v[54:57]
	v_mfma_f32_16x16x32_bf16 v[50:53], v[194:197], v[202:205], v[50:53]
	v_mfma_f32_16x16x32_bf16 v[38:41], v[186:189], v[214:217], v[38:41]
	v_mfma_f32_16x16x32_bf16 v[34:37], v[194:197], v[214:217], v[34:37]
	v_mfma_f32_16x16x32_bf16 v[22:25], v[186:189], v[222:225], v[22:25]
	v_mfma_f32_16x16x32_bf16 v[18:21], v[194:197], v[222:225], v[18:21]
	v_mfma_f32_16x16x32_bf16 v[6:9], v[186:189], v[230:233], v[6:9]
	v_mfma_f32_16x16x32_bf16 v[2:5], v[194:197], v[230:233], v[2:5]
	v_mfma_f32_16x16x32_bf16 v[54:57], v[190:193], v[210:213], v[54:57]
	v_mfma_f32_16x16x32_bf16 v[50:53], v[198:201], v[210:213], v[50:53]
	v_mfma_f32_16x16x32_bf16 v[38:41], v[190:193], v[218:221], v[38:41]
	v_mfma_f32_16x16x32_bf16 v[34:37], v[198:201], v[218:221], v[34:37]
	v_mfma_f32_16x16x32_bf16 v[22:25], v[190:193], v[226:229], v[22:25]
	v_mfma_f32_16x16x32_bf16 v[18:21], v[198:201], v[226:229], v[18:21]
	v_mfma_f32_16x16x32_bf16 v[6:9], v[190:193], v[234:237], v[6:9]
	v_mfma_f32_16x16x32_bf16 v[2:5], v[198:201], v[234:237], v[2:5]
; #define G8_STA(bufoff, ptr, sg, h) G8_STAGE1(bufoff, (ptr) + (h) * ((sg) ? hA1 : hA0), ((sg) ? voffA1 : voffA0), ((sg) ? r64A1 : r64A0))
; #define G8_STB(bufoff, ptr, sg, h) G8_STAGE1(bufoff, (ptr) + (h) * ((sg) ? hB1 : hB0), ((sg) ? voffB1 : voffB0), ((sg) ? r64B1 : r64B0))
; #define G8_LDA(dst, b, h) do { _Pragma("unroll") for (int m = 0; m < 4; ++m) _Pragma("unroll") for (int k = 0; k < 2; ++k) dst[m][k] = *(const LAS bf16x8*)(lds + G8_SA(b, h) + aoff + m * 2048 + k * 1024); } while (0)
; #define G8_LDB(dst, b, h) do { _Pragma("unroll") for (int n = 0; n < 2; ++n) _Pragma("unroll") for (int k = 0; k < 2; ++k) dst[n][k] = *(const LAS bf16x8*)(lds + G8_SB(b, h) + boff + n * 2048 + k * 1024); } while (0)
; #define G8_MMA(ai, bj, At, Bt) do { __builtin_amdgcn_s_setprio(1); _Pragma("unroll") for (int m = 0; m < 4; ++m) _Pragma("unroll") for (int n = 0; n < 2; ++n) _Pragma("unroll") for (int k = 0; k < 2; ++k) \
;         acc[ai][bj][m][n] = __builtin_amdgcn_mfma_f32_16x16x32_bf16(Bt[n][k], At[m][k], acc[ai][bj][m][n], 0, 0, 0); __builtin_amdgcn_s_setprio(0); } while (0)
; #define G8_WAIT_V(n) asm volatile("s_waitcnt vmcnt(" #n ")" ::: "memory")
; #define G8_WAIT_L(n) asm volatile("s_waitcnt lgkmcnt(" #n ")" ::: "memory")
; #define G8_BAR __builtin_amdgcn_s_barrier()
; #define G8_SCHED __builtin_amdgcn_sched_barrier(0)
; template <class P>
; __device__ __forceinline__ void gemm_phase(LAS unsigned char* lds, const P& p, const int G, const int c) {
;     ...
;             G8_LDB(B0, 1, 0); G8_LDB(B1, 1, 1); G8_SCHED; G8_LDA(At, 1, 0); G8_STA(G8_SA(0, 1), a2, sg2, 1);
;             G8_WAIT_V(8); G8_WAIT_L(0); G8_BAR; G8_MMA(0, 0, At, B0); G8_MMA(0, 1, At, B1); G8_BAR; G8_SCHED;
;             G8_LDA(At, 1, 1); G8_STB(G8_SB(1, 0), b3, sg2, 0); G8_STB(G8_SB(1, 1), b3, sg2, 1); G8_STA(G8_SA(1, 0), a3, sg2, 0);
;             G8_WAIT_V(8); G8_WAIT_L(0); G8_BAR; G8_MMA(1, 0, At, B0); G8_MMA(1, 1, At, B1); G8_BAR; G8_SCHED;
;         }
.Lmid_679:
	s_barrier
	s_add_i32 s28, 0, 0x18000
	v_add_u32_e32 v153, s28, v1
	s_add_i32 s29, 0, 0x1c000
	ds_read_b128 v[170:173], v153
	ds_read_b128 v[174:177], v153 offset:1024
	ds_read_b128 v[178:181], v153 offset:2048
	ds_read_b128 v[182:185], v153 offset:3072
	v_add_u32_e32 v153, s29, v1
	ds_read_b128 v[186:189], v153
	ds_read_b128 v[190:193], v153 offset:1024
	ds_read_b128 v[194:197], v153 offset:2048
	ds_read_b128 v[198:201], v153 offset:3072
	s_mov_b32 m0, s34
	v_lshl_add_u64 v[240:241], v[238:239], 0, s[4:5]
	ds_read_b128 v[202:205], v151 offset:32768
	ds_read_b128 v[210:213], v151 offset:33792
	ds_read_b128 v[214:217], v151 offset:34816
	ds_read_b128 v[218:221], v151 offset:35840
	ds_read_b128 v[222:225], v151 offset:36864
	ds_read_b128 v[226:229], v151 offset:37888
	ds_read_b128 v[230:233], v151 offset:38912
	ds_read_b128 v[234:237], v151 offset:39936
	global_load_lds_dwordx4 v[240:241], off
	v_lshl_add_u64 v[240:241], v[238:239], 0, s[6:7]
	s_mov_b32 m0, s35
	s_nop 0
	global_load_lds_dwordx4 v[240:241], off
	s_waitcnt vmcnt(8)
	s_waitcnt lgkmcnt(0)
	s_barrier
	s_waitcnt lgkmcnt(0)
	v_mfma_f32_16x16x32_bf16 v[126:129], v[170:173], v[202:205], v[126:129]
	v_mfma_f32_16x16x32_bf16 v[122:125], v[178:181], v[202:205], v[122:125]
	v_mfma_f32_16x16x32_bf16 v[110:113], v[170:173], v[214:217], v[110:113]
	v_mfma_f32_16x16x32_bf16 v[106:109], v[178:181], v[214:217], v[106:109]
	v_mfma_f32_16x16x32_bf16 v[94:97], v[170:173], v[222:225], v[94:97]
	v_mfma_f32_16x16x32_bf16 v[90:93], v[178:181], v[222:225], v[90:93]
	v_mfma_f32_16x16x32_bf16 v[78:81], v[170:173], v[230:233], v[78:81]
	v_mfma_f32_16x16x32_bf16 v[74:77], v[178:181], v[230:233], v[74:77]
	v_mfma_f32_16x16x32_bf16 v[126:129], v[174:177], v[210:213], v[126:129]
	v_mfma_f32_16x16x32_bf16 v[122:125], v[182:185], v[210:213], v[122:125]
	v_mfma_f32_16x16x32_bf16 v[110:113], v[174:177], v[218:221], v[110:113]
	v_mfma_f32_16x16x32_bf16 v[106:109], v[182:185], v[218:221], v[106:109]
	v_mfma_f32_16x16x32_bf16 v[94:97], v[174:177], v[226:229], v[94:97]
	v_mfma_f32_16x16x32_bf16 v[90:93], v[182:185], v[226:229], v[90:93]
	v_mfma_f32_16x16x32_bf16 v[78:81], v[174:177], v[234:237], v[78:81]
	v_mfma_f32_16x16x32_bf16 v[74:77], v[182:185], v[234:237], v[74:77]
	v_mfma_f32_16x16x32_bf16 v[118:121], v[186:189], v[202:205], v[118:121]
	v_mfma_f32_16x16x32_bf16 v[114:117], v[194:197], v[202:205], v[114:117]
	v_mfma_f32_16x16x32_bf16 v[102:105], v[186:189], v[214:217], v[102:105]
	v_mfma_f32_16x16x32_bf16 v[98:101], v[194:197], v[214:217], v[98:101]
	v_mfma_f32_16x16x32_bf16 v[86:89], v[186:189], v[222:225], v[86:89]
	v_mfma_f32_16x16x32_bf16 v[82:85], v[194:197], v[222:225], v[82:85]
	v_mfma_f32_16x16x32_bf16 v[70:73], v[186:189], v[230:233], v[70:73]
	v_mfma_f32_16x16x32_bf16 v[66:69], v[194:197], v[230:233], v[66:69]
	v_mfma_f32_16x16x32_bf16 v[118:121], v[190:193], v[210:213], v[118:121]
	v_mfma_f32_16x16x32_bf16 v[114:117], v[198:201], v[210:213], v[114:117]
	v_mfma_f32_16x16x32_bf16 v[102:105], v[190:193], v[218:221], v[102:105]
	v_mfma_f32_16x16x32_bf16 v[98:101], v[198:201], v[218:221], v[98:101]
	v_mfma_f32_16x16x32_bf16 v[86:89], v[190:193], v[226:229], v[86:89]
	v_mfma_f32_16x16x32_bf16 v[82:85], v[198:201], v[226:229], v[82:85]
	v_mfma_f32_16x16x32_bf16 v[70:73], v[190:193], v[234:237], v[70:73]
	v_mfma_f32_16x16x32_bf16 v[66:69], v[198:201], v[234:237], v[66:69]
	s_barrier
	ds_read_b128 v[202:205], v151 offset:49152
	ds_read_b128 v[210:213], v151 offset:50176
	ds_read_b128 v[214:217], v151 offset:51200
	ds_read_b128 v[218:221], v151 offset:52224
	ds_read_b128 v[222:225], v151 offset:53248
	ds_read_b128 v[226:229], v151 offset:54272
	ds_read_b128 v[230:233], v151 offset:55296
	ds_read_b128 v[234:237], v151 offset:56320
	s_add_i32 s28, s28, s26
	s_mov_b32 m0, s28
	v_lshl_add_u64 v[240:241], v[206:207], 0, s[12:13]
	global_load_lds_dwordx4 v[240:241], off
	v_lshl_add_u64 v[240:241], v[206:207], 0, s[14:15]
	s_add_i32 m0, s28, 0x2000
	s_add_i32 s28, s29, s26
	global_load_lds_dwordx4 v[240:241], off
	v_lshl_add_u64 v[240:241], v[206:207], 0, s[22:23]
	s_mov_b32 m0, s28
	v_lshl_add_u64 v[206:207], v[206:207], 0, s[36:37]
	global_load_lds_dwordx4 v[240:241], off
	s_add_i32 m0, s28, 0x2000
	s_nop 0
	global_load_lds_dwordx4 v[206:207], off
	v_lshl_add_u64 v[206:207], v[238:239], 0, s[16:17]
	s_mov_b32 m0, s46
	s_nop 0
	global_load_lds_dwordx4 v[206:207], off
	v_lshl_add_u64 v[206:207], v[238:239], 0, s[20:21]
	s_mov_b32 m0, s47
	s_nop 0
	global_load_lds_dwordx4 v[206:207], off
	s_waitcnt vmcnt(8)
	s_waitcnt lgkmcnt(0)
	s_barrier
	s_waitcnt lgkmcnt(0)
	v_mfma_f32_16x16x32_bf16 v[62:65], v[170:173], v[202:205], v[62:65]
	v_mfma_f32_16x16x32_bf16 v[58:61], v[178:181], v[202:205], v[58:61]
	v_mfma_f32_16x16x32_bf16 v[46:49], v[170:173], v[214:217], v[46:49]
	v_mfma_f32_16x16x32_bf16 v[42:45], v[178:181], v[214:217], v[42:45]
	s_add_i32 s66, s66, 2
	v_mfma_f32_16x16x32_bf16 v[30:33], v[170:173], v[222:225], v[30:33]
	s_add_u32 s53, s53, 0x100000
	v_mfma_f32_16x16x32_bf16 v[26:29], v[178:181], v[222:225], v[26:29]
	s_addc_u32 s59, s59, 0
	v_mfma_f32_16x16x32_bf16 v[14:17], v[170:173], v[230:233], v[14:17]
	s_add_u32 s62, s62, 0x820000
	v_mfma_f32_16x16x32_bf16 v[10:13], v[178:181], v[230:233], v[10:13]
	s_addc_u32 s63, s63, 0
	v_mfma_f32_16x16x32_bf16 v[62:65], v[174:177], v[210:213], v[62:65]
	s_cmp_gt_u32 s66, 13
	v_mfma_f32_16x16x32_bf16 v[58:61], v[182:185], v[210:213], v[58:61]
	v_mfma_f32_16x16x32_bf16 v[46:49], v[174:177], v[218:221], v[46:49]
	v_mfma_f32_16x16x32_bf16 v[42:45], v[182:185], v[218:221], v[42:45]
	v_mfma_f32_16x16x32_bf16 v[30:33], v[174:177], v[226:229], v[30:33]
	v_mfma_f32_16x16x32_bf16 v[26:29], v[182:185], v[226:229], v[26:29]
	v_mfma_f32_16x16x32_bf16 v[14:17], v[174:177], v[234:237], v[14:17]
	v_mfma_f32_16x16x32_bf16 v[10:13], v[182:185], v[234:237], v[10:13]
	v_mfma_f32_16x16x32_bf16 v[54:57], v[186:189], v[202:205], v[54:57]
	v_mfma_f32_16x16x32_bf16 v[50:53], v[194:197], v[202:205], v[50:53]
	v_mfma_f32_16x16x32_bf16 v[38:41], v[186:189], v[214:217], v[38:41]
	v_mfma_f32_16x16x32_bf16 v[34:37], v[194:197], v[214:217], v[34:37]
	v_mfma_f32_16x16x32_bf16 v[22:25], v[186:189], v[222:225], v[22:25]
	v_mfma_f32_16x16x32_bf16 v[18:21], v[194:197], v[222:225], v[18:21]
	v_mfma_f32_16x16x32_bf16 v[6:9], v[186:189], v[230:233], v[6:9]
	v_mfma_f32_16x16x32_bf16 v[2:5], v[194:197], v[230:233], v[2:5]
	v_mfma_f32_16x16x32_bf16 v[54:57], v[190:193], v[210:213], v[54:57]
	v_mfma_f32_16x16x32_bf16 v[50:53], v[198:201], v[210:213], v[50:53]
	v_mfma_f32_16x16x32_bf16 v[38:41], v[190:193], v[218:221], v[38:41]
	v_mfma_f32_16x16x32_bf16 v[34:37], v[198:201], v[218:221], v[34:37]
	v_mfma_f32_16x16x32_bf16 v[22:25], v[190:193], v[226:229], v[22:25]
	v_mfma_f32_16x16x32_bf16 v[18:21], v[198:201], v[226:229], v[18:21]
	v_mfma_f32_16x16x32_bf16 v[6:9], v[190:193], v[234:237], v[6:9]
	v_mfma_f32_16x16x32_bf16 v[2:5], v[198:201], v[234:237], v[2:5]
	s_barrier
	s_cbranch_scc1 .LBB0_682

; #define G8_STA(bufoff, ptr, sg, h) G8_STAGE1(bufoff, (ptr) + (h) * ((sg) ? hA1 : hA0), ((sg) ? voffA1 : voffA0), ((sg) ? r64A1 : r64A0))
; #define G8_STB(bufoff, ptr, sg, h) G8_STAGE1(bufoff, (ptr) + (h) * ((sg) ? hB1 : hB0), ((sg) ? voffB1 : voffB0), ((sg) ? r64B1 : r64B0))
; #define G8_LDA(dst, b, h) do { _Pragma("unroll") for (int m = 0; m < 4; ++m) _Pragma("unroll") for (int k = 0; k < 2; ++k) dst[m][k] = *(const LAS bf16x8*)(lds + G8_SA(b, h) + aoff + m * 2048 + k * 1024); } while (0)
; #define G8_LDB(dst, b, h) do { _Pragma("unroll") for (int n = 0; n < 2; ++n) _Pragma("unroll") for (int k = 0; k < 2; ++k) dst[n][k] = *(const LAS bf16x8*)(lds + G8_SB(b, h) + boff + n * 2048 + k * 1024); } while (0)
; #define G8_BAR __builtin_amdgcn_s_barrier()
; template <class P>
; __device__ __forceinline__ void gemm_phase(LAS unsigned char* lds, const P& p, const int G, const int c) {
;     ...
;         const bool has_next = p.unit((ui + 1) * G + c, nxt);
;         const int nt = p.nt(cur);
;         const char* nA0 = has_next ? p.a_base(nxt, 0) - p.a_bias(0) : cA0; const char* nA1 = has_next ? p.a_base(nxt, S1) - p.a_bias(S1) : cA1;
;         const char* nB0 = has_next ? p.b_base(nxt, 0) - p.b_bias(0) : cB0; const char* nB1 = has_next ? p.b_base(nxt, S1) - p.b_bias(S1) : cB1;
;         for (int t = 0; t < nt; t += 2) {
;             const bool last = (t == nt - 2);
;             const bool sg1 = (NS > 1) && (t + 1 >= nt0);
;             const bool sg2 = (NS > 1) && !last && (t + 2 >= nt0);
;             const char* a1 = sg1 ? cA1 + (long)(t + 1 - nt0) * ksA1 : cA0 + (long)(t + 1) * ksA0;
;             const char* a2 = last ? nA0 : (sg2 ? cA1 + (long)(t + 2 - nt0) * ksA1 : cA0 + (long)(t + 2) * ksA0);
;             const char* b2 = last ? nB0 : (sg2 ? cB1 + (long)(t + 2 - nt0) * ksB1 : cB0 + (long)(t + 2) * ksB0);
;             const char* a3 = a2 + (sg2 ? ksA1 : ksA0); const char* b3 = b2 + (sg2 ? ksB1 : ksB0);
;             G8_LDB(B0, 0, 0); G8_LDB(B1, 0, 1); G8_SCHED; G8_LDA(At, 0, 0); G8_STA(G8_SA(1, 1), a1, sg1, 1);
;             G8_WAIT_V(8); G8_WAIT_L(0); G8_BAR; G8_MMA(0, 0, At, B0); G8_MMA(0, 1, At, B1); G8_BAR; G8_SCHED;
;             G8_LDA(At, 0, 1); G8_STB(G8_SB(0, 0), b2, sg2, 0); G8_STB(G8_SB(0, 1), b2, sg2, 1); G8_STA(G8_SA(0, 0), a2, sg2, 0);
;             G8_WAIT_V(8); G8_WAIT_L(0); G8_BAR; G8_MMA(1, 0, At, B0); G8_MMA(1, 1, At, B1); G8_BAR; G8_SCHED;
.LBB0_706:
	s_ashr_i32 s61, s60, 31
	s_lshl_b64 s[18:19], s[60:61], 13
	s_add_u32 s68, s4, s18
	s_addc_u32 s69, s5, s19
	s_and_b64 s[18:19], s[58:59], exec
	s_cselect_b32 s18, s69, s75
	s_cselect_b32 s19, s68, s74
	s_ashr_i32 s63, s62, 31
	s_lshl_b64 s[64:65], s[62:63], 15
	s_add_u32 s70, s2, s64
	s_addc_u32 s71, s3, s65
	s_and_b64 s[64:65], s[58:59], exec
	s_cselect_b32 s61, s71, s29
	s_cselect_b32 s63, s70, s28
	s_add_u32 s28, s28, 0x80000
	s_addc_u32 s29, s29, 0
	v_lshl_add_u64 v[66:67], s[74:75], 0, v[212:213]
	s_mov_b32 s64, -2
	s_mov_b64 s[76:77], 0
	ds_read_b128 v[68:71], v230
	ds_read_b128 v[72:75], v230 offset:1024
	ds_read_b128 v[76:79], v230 offset:2048
	ds_read_b128 v[138:141], v230 offset:3072
	ds_read_b128 v[142:145], v231
	ds_read_b128 v[154:157], v231 offset:1024
	ds_read_b128 v[158:161], v231 offset:2048
	ds_read_b128 v[162:165], v231 offset:3072
	s_add_u32 s65, s74, s76
	s_addc_u32 s66, s75, s77
	s_add_u32 s65, s65, 0x800000
	s_addc_u32 s66, s66, 0
	s_cmp_eq_u32 s76, 0x7800000
	s_cselect_b32 s67, s18, s66
	s_cselect_b32 s66, s19, s65
	s_cselect_b32 s79, s61, s29
	s_cselect_b32 s78, s63, s28
	v_lshl_add_u64 v[80:81], v[66:67], 0, s[76:77]
	s_mov_b64 s[80:81], 0x401000
	v_lshl_add_u64 v[198:199], v[80:81], 0, s[80:81]
	s_add_i32 m0, s25, 0xc000
	ds_read_b128 v[166:169], v232
	ds_read_b128 v[170:173], v232 offset:1024
	ds_read_b128 v[174:177], v232 offset:2048
	ds_read_b128 v[178:181], v232 offset:3072
	ds_read_b128 v[182:185], v232 offset:4096
	ds_read_b128 v[186:189], v232 offset:5120
	ds_read_b128 v[190:193], v232 offset:6144
	ds_read_b128 v[194:197], v232 offset:7168
	global_load_lds_dwordx4 v[198:199], off
	v_lshl_add_u64 v[80:81], v[80:81], 0, s[54:55]
	s_add_i32 m0, s25, 0xe000
	s_nop 0
	global_load_lds_dwordx4 v[80:81], off
	s_waitcnt vmcnt(8)
	s_waitcnt lgkmcnt(0)
	s_barrier
	s_waitcnt lgkmcnt(0)
	v_mfma_f32_16x16x32_bf16 v[150:153], v[68:71], v[166:169], 0
	v_mfma_f32_16x16x32_bf16 v[146:149], v[76:79], v[166:169], 0
	v_mfma_f32_16x16x32_bf16 v[126:129], v[68:71], v[174:177], 0
	v_mfma_f32_16x16x32_bf16 v[122:125], v[76:79], v[174:177], 0
	v_mfma_f32_16x16x32_bf16 v[110:113], v[68:71], v[182:185], 0
	v_mfma_f32_16x16x32_bf16 v[106:109], v[76:79], v[182:185], 0
	v_mfma_f32_16x16x32_bf16 v[94:97], v[68:71], v[190:193], 0
	v_mfma_f32_16x16x32_bf16 v[90:93], v[76:79], v[190:193], 0
	v_mfma_f32_16x16x32_bf16 v[150:153], v[72:75], v[170:173], v[150:153]
	v_mfma_f32_16x16x32_bf16 v[146:149], v[138:141], v[170:173], v[146:149]
	v_mfma_f32_16x16x32_bf16 v[126:129], v[72:75], v[178:181], v[126:129]
	v_mfma_f32_16x16x32_bf16 v[122:125], v[138:141], v[178:181], v[122:125]
	v_mfma_f32_16x16x32_bf16 v[110:113], v[72:75], v[186:189], v[110:113]
	v_mfma_f32_16x16x32_bf16 v[106:109], v[138:141], v[186:189], v[106:109]
	v_mfma_f32_16x16x32_bf16 v[94:97], v[72:75], v[194:197], v[94:97]
	v_mfma_f32_16x16x32_bf16 v[90:93], v[138:141], v[194:197], v[90:93]
	v_mfma_f32_16x16x32_bf16 v[134:137], v[142:145], v[166:169], 0
	v_mfma_f32_16x16x32_bf16 v[130:133], v[158:161], v[166:169], 0
	v_mfma_f32_16x16x32_bf16 v[118:121], v[142:145], v[174:177], 0
	v_mfma_f32_16x16x32_bf16 v[114:117], v[158:161], v[174:177], 0
	v_mfma_f32_16x16x32_bf16 v[102:105], v[142:145], v[182:185], 0
	v_mfma_f32_16x16x32_bf16 v[98:101], v[158:161], v[182:185], 0
	v_mfma_f32_16x16x32_bf16 v[86:89], v[142:145], v[190:193], 0
	v_mfma_f32_16x16x32_bf16 v[80:83], v[158:161], v[190:193], 0
	v_mfma_f32_16x16x32_bf16 v[134:137], v[154:157], v[170:173], v[134:137]
	v_mfma_f32_16x16x32_bf16 v[130:133], v[162:165], v[170:173], v[130:133]
	v_mfma_f32_16x16x32_bf16 v[118:121], v[154:157], v[178:181], v[118:121]
	v_mfma_f32_16x16x32_bf16 v[114:117], v[162:165], v[178:181], v[114:117]
	v_mfma_f32_16x16x32_bf16 v[102:105], v[154:157], v[186:189], v[102:105]
	v_mfma_f32_16x16x32_bf16 v[98:101], v[162:165], v[186:189], v[98:101]
	v_mfma_f32_16x16x32_bf16 v[86:89], v[154:157], v[194:197], v[86:89]
	v_mfma_f32_16x16x32_bf16 v[80:83], v[162:165], v[194:197], v[80:83]
	s_barrier
	ds_read_b128 v[166:169], v232 offset:16384
	ds_read_b128 v[170:173], v232 offset:17408
	ds_read_b128 v[174:177], v232 offset:18432
	ds_read_b128 v[178:181], v232 offset:19456
	ds_read_b128 v[182:185], v232 offset:20480
	ds_read_b128 v[186:189], v232 offset:21504
	ds_read_b128 v[190:193], v232 offset:22528
	ds_read_b128 v[194:197], v232 offset:23552
	s_add_i32 s65, s50, s24
	s_mov_b32 m0, s65
	v_lshl_add_u64 v[198:199], s[78:79], 0, v[202:203]
	global_load_lds_dwordx4 v[198:199], off
	v_lshl_add_u64 v[84:85], v[198:199], 0, s[6:7]
	s_add_i32 m0, s65, 0x2000
	s_add_i32 s65, s51, s24
	global_load_lds_dwordx4 v[84:85], off
	v_lshl_add_u64 v[84:85], v[198:199], 0, s[8:9]
	s_mov_b32 m0, s65
	v_lshl_add_u64 v[200:201], s[66:67], 0, v[204:205]
	global_load_lds_dwordx4 v[84:85], off
	v_lshl_add_u64 v[84:85], v[198:199], 0, s[10:11]
	s_add_i32 m0, s65, 0x2000
	s_nop 0
	global_load_lds_dwordx4 v[84:85], off
	s_mov_b32 m0, s25
	v_lshl_add_u64 v[84:85], v[200:201], 0, s[12:13]
	global_load_lds_dwordx4 v[200:201], off
	s_mov_b32 m0, s26
	s_nop 0
	global_load_lds_dwordx4 v[84:85], off
	s_waitcnt vmcnt(8)
	s_waitcnt lgkmcnt(0)
	s_barrier
; #define G8_STA(bufoff, ptr, sg, h) G8_STAGE1(bufoff, (ptr) + (h) * ((sg) ? hA1 : hA0), ((sg) ? voffA1 : voffA0), ((sg) ? r64A1 : r64A0))
; #define G8_STB(bufoff, ptr, sg, h) G8_STAGE1(bufoff, (ptr) + (h) * ((sg) ? hB1 : hB0), ((sg) ? voffB1 : voffB0), ((sg) ? r64B1 : r64B0))
; #define G8_LDA(dst, b, h) do { _Pragma("unroll") for (int m = 0; m < 4; ++m) _Pragma("unroll") for (int k = 0; k < 2; ++k) dst[m][k] = *(const LAS bf16x8*)(lds + G8_SA(b, h) + aoff + m * 2048 + k * 1024); } while (0)
; #define G8_LDB(dst, b, h) do { _Pragma("unroll") for (int n = 0; n < 2; ++n) _Pragma("unroll") for (int k = 0; k < 2; ++k) dst[n][k] = *(const LAS bf16x8*)(lds + G8_SB(b, h) + boff + n * 2048 + k * 1024); } while (0)
; #define G8_MMA(ai, bj, At, Bt) do { __builtin_amdgcn_s_setprio(1); _Pragma("unroll") for (int m = 0; m < 4; ++m) _Pragma("unroll") for (int n = 0; n < 2; ++n) _Pragma("unroll") for (int k = 0; k < 2; ++k) \
;         acc[ai][bj][m][n] = __builtin_amdgcn_mfma_f32_16x16x32_bf16(Bt[n][k], At[m][k], acc[ai][bj][m][n], 0, 0, 0); __builtin_amdgcn_s_setprio(0); } while (0)
; #define G8_WAIT_V(n) asm volatile("s_waitcnt vmcnt(" #n ")" ::: "memory")
; #define G8_WAIT_L(n) asm volatile("s_waitcnt lgkmcnt(" #n ")" ::: "memory")
; #define G8_BAR __builtin_amdgcn_s_barrier()
; #define G8_SCHED __builtin_amdgcn_sched_barrier(0)
; template <class P>
; __device__ __forceinline__ void gemm_phase(LAS unsigned char* lds, const P& p, const int G, const int c) {
;     ...
;             G8_LDB(B0, 0, 0); G8_LDB(B1, 0, 1); G8_SCHED; G8_LDA(At, 0, 0); G8_STA(G8_SA(1, 1), a1, sg1, 1);
;             G8_WAIT_V(8); G8_WAIT_L(0); G8_BAR; G8_MMA(0, 0, At, B0); G8_MMA(0, 1, At, B1); G8_BAR; G8_SCHED;
;             G8_LDA(At, 0, 1); G8_STB(G8_SB(0, 0), b2, sg2, 0); G8_STB(G8_SB(0, 1), b2, sg2, 1); G8_STA(G8_SA(0, 0), a2, sg2, 0);
;             G8_WAIT_V(8); G8_WAIT_L(0); G8_BAR; G8_MMA(1, 0, At, B0); G8_MMA(1, 1, At, B1); G8_BAR; G8_SCHED;
	s_waitcnt lgkmcnt(0)
	v_mfma_f32_16x16x32_bf16 v[62:65], v[68:71], v[166:169], 0
	v_mfma_f32_16x16x32_bf16 v[58:61], v[76:79], v[166:169], 0
	v_mfma_f32_16x16x32_bf16 v[46:49], v[68:71], v[174:177], 0
	v_mfma_f32_16x16x32_bf16 v[42:45], v[76:79], v[174:177], 0
	v_mfma_f32_16x16x32_bf16 v[30:33], v[68:71], v[182:185], 0
	v_mfma_f32_16x16x32_bf16 v[26:29], v[76:79], v[182:185], 0
	v_mfma_f32_16x16x32_bf16 v[14:17], v[68:71], v[190:193], 0
	v_mfma_f32_16x16x32_bf16 v[10:13], v[76:79], v[190:193], 0
	v_mfma_f32_16x16x32_bf16 v[62:65], v[72:75], v[170:173], v[62:65]
	v_mfma_f32_16x16x32_bf16 v[58:61], v[138:141], v[170:173], v[58:61]
	v_mfma_f32_16x16x32_bf16 v[46:49], v[72:75], v[178:181], v[46:49]
	v_mfma_f32_16x16x32_bf16 v[42:45], v[138:141], v[178:181], v[42:45]
	v_mfma_f32_16x16x32_bf16 v[30:33], v[72:75], v[186:189], v[30:33]
	v_mfma_f32_16x16x32_bf16 v[26:29], v[138:141], v[186:189], v[26:29]
	v_mfma_f32_16x16x32_bf16 v[14:17], v[72:75], v[194:197], v[14:17]
	v_mfma_f32_16x16x32_bf16 v[10:13], v[138:141], v[194:197], v[10:13]
	v_mfma_f32_16x16x32_bf16 v[54:57], v[142:145], v[166:169], 0
	v_mfma_f32_16x16x32_bf16 v[50:53], v[158:161], v[166:169], 0
	v_mfma_f32_16x16x32_bf16 v[38:41], v[142:145], v[174:177], 0
	v_mfma_f32_16x16x32_bf16 v[34:37], v[158:161], v[174:177], 0
	v_mfma_f32_16x16x32_bf16 v[22:25], v[142:145], v[182:185], 0
	v_mfma_f32_16x16x32_bf16 v[18:21], v[158:161], v[182:185], 0
	v_mfma_f32_16x16x32_bf16 v[6:9], v[142:145], v[190:193], 0
	v_mfma_f32_16x16x32_bf16 v[2:5], v[158:161], v[190:193], 0
	v_mfma_f32_16x16x32_bf16 v[54:57], v[154:157], v[170:173], v[54:57]
	v_mfma_f32_16x16x32_bf16 v[50:53], v[162:165], v[170:173], v[50:53]
	v_mfma_f32_16x16x32_bf16 v[38:41], v[154:157], v[178:181], v[38:41]
	v_mfma_f32_16x16x32_bf16 v[34:37], v[162:165], v[178:181], v[34:37]
	v_mfma_f32_16x16x32_bf16 v[22:25], v[154:157], v[186:189], v[22:25]
	v_mfma_f32_16x16x32_bf16 v[18:21], v[162:165], v[186:189], v[18:21]
	v_mfma_f32_16x16x32_bf16 v[6:9], v[154:157], v[194:197], v[6:9]
	v_mfma_f32_16x16x32_bf16 v[2:5], v[162:165], v[194:197], v[2:5]
	s_branch .Lmid_707
.LBB0_707:
	ds_read_b128 v[68:71], v230
	ds_read_b128 v[72:75], v230 offset:1024
	ds_read_b128 v[76:79], v230 offset:2048
	ds_read_b128 v[138:141], v230 offset:3072
	ds_read_b128 v[142:145], v231
	ds_read_b128 v[154:157], v231 offset:1024
	ds_read_b128 v[158:161], v231 offset:2048
	ds_read_b128 v[162:165], v231 offset:3072
	s_add_u32 s65, s74, s76
	s_addc_u32 s66, s75, s77
	s_add_u32 s65, s65, 0x800000
	s_addc_u32 s66, s66, 0
	s_cmp_eq_u32 s76, 0x7800000
	s_cselect_b32 s67, s18, s66
	s_cselect_b32 s66, s19, s65
	s_cselect_b32 s79, s61, s29
	s_cselect_b32 s78, s63, s28
	v_lshl_add_u64 v[80:81], v[66:67], 0, s[76:77]
	s_mov_b64 s[80:81], 0x401000
	v_lshl_add_u64 v[198:199], v[80:81], 0, s[80:81]
	s_add_i32 m0, s25, 0xc000
	ds_read_b128 v[166:169], v232
	ds_read_b128 v[170:173], v232 offset:1024
	ds_read_b128 v[174:177], v232 offset:2048
	ds_read_b128 v[178:181], v232 offset:3072
	ds_read_b128 v[182:185], v232 offset:4096
	ds_read_b128 v[186:189], v232 offset:5120
	ds_read_b128 v[190:193], v232 offset:6144
	ds_read_b128 v[194:197], v232 offset:7168
	global_load_lds_dwordx4 v[198:199], off
	v_lshl_add_u64 v[80:81], v[80:81], 0, s[54:55]
	s_add_i32 m0, s25, 0xe000
	s_nop 0
	global_load_lds_dwordx4 v[80:81], off
	s_waitcnt vmcnt(8)
	s_waitcnt lgkmcnt(0)
	s_barrier
	s_waitcnt lgkmcnt(0)
	v_mfma_f32_16x16x32_bf16 v[150:153], v[68:71], v[166:169], v[150:153]
	v_mfma_f32_16x16x32_bf16 v[146:149], v[76:79], v[166:169], v[146:149]
	v_mfma_f32_16x16x32_bf16 v[126:129], v[68:71], v[174:177], v[126:129]
	v_mfma_f32_16x16x32_bf16 v[122:125], v[76:79], v[174:177], v[122:125]
	v_mfma_f32_16x16x32_bf16 v[110:113], v[68:71], v[182:185], v[110:113]
	v_mfma_f32_16x16x32_bf16 v[106:109], v[76:79], v[182:185], v[106:109]
	v_mfma_f32_16x16x32_bf16 v[94:97], v[68:71], v[190:193], v[94:97]
	v_mfma_f32_16x16x32_bf16 v[90:93], v[76:79], v[190:193], v[90:93]
	v_mfma_f32_16x16x32_bf16 v[150:153], v[72:75], v[170:173], v[150:153]
	v_mfma_f32_16x16x32_bf16 v[146:149], v[138:141], v[170:173], v[146:149]
	v_mfma_f32_16x16x32_bf16 v[126:129], v[72:75], v[178:181], v[126:129]
	v_mfma_f32_16x16x32_bf16 v[122:125], v[138:141], v[178:181], v[122:125]
	v_mfma_f32_16x16x32_bf16 v[110:113], v[72:75], v[186:189], v[110:113]
	v_mfma_f32_16x16x32_bf16 v[106:109], v[138:141], v[186:189], v[106:109]
	v_mfma_f32_16x16x32_bf16 v[94:97], v[72:75], v[194:197], v[94:97]
	v_mfma_f32_16x16x32_bf16 v[90:93], v[138:141], v[194:197], v[90:93]
	v_mfma_f32_16x16x32_bf16 v[134:137], v[142:145], v[166:169], v[134:137]
	v_mfma_f32_16x16x32_bf16 v[130:133], v[158:161], v[166:169], v[130:133]
	v_mfma_f32_16x16x32_bf16 v[118:121], v[142:145], v[174:177], v[118:121]
	v_mfma_f32_16x16x32_bf16 v[114:117], v[158:161], v[174:177], v[114:117]
	v_mfma_f32_16x16x32_bf16 v[102:105], v[142:145], v[182:185], v[102:105]
	v_mfma_f32_16x16x32_bf16 v[98:101], v[158:161], v[182:185], v[98:101]
	v_mfma_f32_16x16x32_bf16 v[86:89], v[142:145], v[190:193], v[86:89]
	v_mfma_f32_16x16x32_bf16 v[80:83], v[158:161], v[190:193], v[82:85]
	v_mfma_f32_16x16x32_bf16 v[134:137], v[154:157], v[170:173], v[134:137]
	v_mfma_f32_16x16x32_bf16 v[130:133], v[162:165], v[170:173], v[130:133]
	v_mfma_f32_16x16x32_bf16 v[118:121], v[154:157], v[178:181], v[118:121]
	v_mfma_f32_16x16x32_bf16 v[114:117], v[162:165], v[178:181], v[114:117]
	v_mfma_f32_16x16x32_bf16 v[102:105], v[154:157], v[186:189], v[102:105]
	v_mfma_f32_16x16x32_bf16 v[98:101], v[162:165], v[186:189], v[98:101]
	v_mfma_f32_16x16x32_bf16 v[86:89], v[154:157], v[194:197], v[86:89]
	v_mfma_f32_16x16x32_bf16 v[80:83], v[162:165], v[194:197], v[80:83]
	s_barrier
; #define G8_STA(bufoff, ptr, sg, h) G8_STAGE1(bufoff, (ptr) + (h) * ((sg) ? hA1 : hA0), ((sg) ? voffA1 : voffA0), ((sg) ? r64A1 : r64A0))
; #define G8_STB(bufoff, ptr, sg, h) G8_STAGE1(bufoff, (ptr) + (h) * ((sg) ? hB1 : hB0), ((sg) ? voffB1 : voffB0), ((sg) ? r64B1 : r64B0))
; #define G8_LDA(dst, b, h) do { _Pragma("unroll") for (int m = 0; m < 4; ++m) _Pragma("unroll") for (int k = 0; k < 2; ++k) dst[m][k] = *(const LAS bf16x8*)(lds + G8_SA(b, h) + aoff + m * 2048 + k * 1024); } while (0)
; #define G8_MMA(ai, bj, At, Bt) do { __builtin_amdgcn_s_setprio(1); _Pragma("unroll") for (int m = 0; m < 4; ++m) _Pragma("unroll") for (int n = 0; n < 2; ++n) _Pragma("unroll") for (int k = 0; k < 2; ++k) \
;         acc[ai][bj][m][n] = __builtin_amdgcn_mfma_f32_16x16x32_bf16(Bt[n][k], At[m][k], acc[ai][bj][m][n], 0, 0, 0); __builtin_amdgcn_s_setprio(0); } while (0)
; #define G8_WAIT_V(n) asm volatile("s_waitcnt vmcnt(" #n ")" ::: "memory")
; #define G8_WAIT_L(n) asm volatile("s_waitcnt lgkmcnt(" #n ")" ::: "memory")
; #define G8_BAR __builtin_amdgcn_s_barrier()
; #define G8_SCHED __builtin_amdgcn_sched_barrier(0)
; template <class P>
; __device__ __forceinline__ void gemm_phase(LAS unsigned char* lds, const P& p, const int G, const int c) {
;     ...
;             G8_LDA(At, 0, 1); G8_STB(G8_SB(0, 0), b2, sg2, 0); G8_STB(G8_SB(0, 1), b2, sg2, 1); G8_STA(G8_SA(0, 0), a2, sg2, 0);
;             G8_WAIT_V(8); G8_WAIT_L(0); G8_BAR; G8_MMA(1, 0, At, B0); G8_MMA(1, 1, At, B1); G8_BAR; G8_SCHED;
	ds_read_b128 v[166:169], v232 offset:16384
	ds_read_b128 v[170:173], v232 offset:17408
	ds_read_b128 v[174:177], v232 offset:18432
	ds_read_b128 v[178:181], v232 offset:19456
	ds_read_b128 v[182:185], v232 offset:20480
	ds_read_b128 v[186:189], v232 offset:21504
	ds_read_b128 v[190:193], v232 offset:22528
	ds_read_b128 v[194:197], v232 offset:23552
	s_add_i32 s65, s50, s24
	s_mov_b32 m0, s65
	v_lshl_add_u64 v[198:199], s[78:79], 0, v[202:203]
	global_load_lds_dwordx4 v[198:199], off
	v_lshl_add_u64 v[84:85], v[198:199], 0, s[6:7]
	s_add_i32 m0, s65, 0x2000
	s_add_i32 s65, s51, s24
	global_load_lds_dwordx4 v[84:85], off
	v_lshl_add_u64 v[84:85], v[198:199], 0, s[8:9]
	s_mov_b32 m0, s65
	v_lshl_add_u64 v[200:201], s[66:67], 0, v[204:205]
	global_load_lds_dwordx4 v[84:85], off
	v_lshl_add_u64 v[84:85], v[198:199], 0, s[10:11]
	s_add_i32 m0, s65, 0x2000
	s_nop 0
	global_load_lds_dwordx4 v[84:85], off
	s_mov_b32 m0, s25
	v_lshl_add_u64 v[84:85], v[200:201], 0, s[12:13]
	global_load_lds_dwordx4 v[200:201], off
	s_mov_b32 m0, s26
	s_nop 0
	global_load_lds_dwordx4 v[84:85], off
	s_waitcnt vmcnt(8)
	s_waitcnt lgkmcnt(0)
	s_barrier
	s_waitcnt lgkmcnt(0)
	v_mfma_f32_16x16x32_bf16 v[62:65], v[68:71], v[166:169], v[62:65]
	v_mfma_f32_16x16x32_bf16 v[58:61], v[76:79], v[166:169], v[58:61]
	v_mfma_f32_16x16x32_bf16 v[46:49], v[68:71], v[174:177], v[46:49]
	v_mfma_f32_16x16x32_bf16 v[42:45], v[76:79], v[174:177], v[42:45]
	v_mfma_f32_16x16x32_bf16 v[30:33], v[68:71], v[182:185], v[30:33]
	v_mfma_f32_16x16x32_bf16 v[26:29], v[76:79], v[182:185], v[26:29]
	v_mfma_f32_16x16x32_bf16 v[14:17], v[68:71], v[190:193], v[14:17]
	v_mfma_f32_16x16x32_bf16 v[10:13], v[76:79], v[190:193], v[10:13]
	v_mfma_f32_16x16x32_bf16 v[62:65], v[72:75], v[170:173], v[62:65]
	v_mfma_f32_16x16x32_bf16 v[58:61], v[138:141], v[170:173], v[58:61]
	v_mfma_f32_16x16x32_bf16 v[46:49], v[72:75], v[178:181], v[46:49]
	v_mfma_f32_16x16x32_bf16 v[42:45], v[138:141], v[178:181], v[42:45]
	v_mfma_f32_16x16x32_bf16 v[30:33], v[72:75], v[186:189], v[30:33]
	v_mfma_f32_16x16x32_bf16 v[26:29], v[138:141], v[186:189], v[26:29]
	v_mfma_f32_16x16x32_bf16 v[14:17], v[72:75], v[194:197], v[14:17]
	v_mfma_f32_16x16x32_bf16 v[10:13], v[138:141], v[194:197], v[10:13]
	v_mfma_f32_16x16x32_bf16 v[54:57], v[142:145], v[166:169], v[54:57]
	v_mfma_f32_16x16x32_bf16 v[50:53], v[158:161], v[166:169], v[50:53]
	v_mfma_f32_16x16x32_bf16 v[38:41], v[142:145], v[174:177], v[38:41]
	v_mfma_f32_16x16x32_bf16 v[34:37], v[158:161], v[174:177], v[34:37]
	v_mfma_f32_16x16x32_bf16 v[22:25], v[142:145], v[182:185], v[22:25]
	v_mfma_f32_16x16x32_bf16 v[18:21], v[158:161], v[182:185], v[18:21]
	v_mfma_f32_16x16x32_bf16 v[6:9], v[142:145], v[190:193], v[6:9]
	v_mfma_f32_16x16x32_bf16 v[2:5], v[158:161], v[190:193], v[2:5]
	v_mfma_f32_16x16x32_bf16 v[54:57], v[154:157], v[170:173], v[54:57]
	v_mfma_f32_16x16x32_bf16 v[50:53], v[162:165], v[170:173], v[50:53]
	v_mfma_f32_16x16x32_bf16 v[38:41], v[154:157], v[178:181], v[38:41]
	v_mfma_f32_16x16x32_bf16 v[34:37], v[162:165], v[178:181], v[34:37]
	v_mfma_f32_16x16x32_bf16 v[22:25], v[154:157], v[186:189], v[22:25]
	v_mfma_f32_16x16x32_bf16 v[18:21], v[162:165], v[186:189], v[18:21]
	v_mfma_f32_16x16x32_bf16 v[6:9], v[154:157], v[194:197], v[6:9]
	v_mfma_f32_16x16x32_bf16 v[2:5], v[162:165], v[194:197], v[2:5]
; #define G8_STA(bufoff, ptr, sg, h) G8_STAGE1(bufoff, (ptr) + (h) * ((sg) ? hA1 : hA0), ((sg) ? voffA1 : voffA0), ((sg) ? r64A1 : r64A0))
; #define G8_STB(bufoff, ptr, sg, h) G8_STAGE1(bufoff, (ptr) + (h) * ((sg) ? hB1 : hB0), ((sg) ? voffB1 : voffB0), ((sg) ? r64B1 : r64B0))
; #define G8_LDA(dst, b, h) do { _Pragma("unroll") for (int m = 0; m < 4; ++m) _Pragma("unroll") for (int k = 0; k < 2; ++k) dst[m][k] = *(const LAS bf16x8*)(lds + G8_SA(b, h) + aoff + m * 2048 + k * 1024); } while (0)
; #define G8_LDB(dst, b, h) do { _Pragma("unroll") for (int n = 0; n < 2; ++n) _Pragma("unroll") for (int k = 0; k < 2; ++k) dst[n][k] = *(const LAS bf16x8*)(lds + G8_SB(b, h) + boff + n * 2048 + k * 1024); } while (0)
; #define G8_MMA(ai, bj, At, Bt) do { __builtin_amdgcn_s_setprio(1); _Pragma("unroll") for (int m = 0; m < 4; ++m) _Pragma("unroll") for (int n = 0; n < 2; ++n) _Pragma("unroll") for (int k = 0; k < 2; ++k) \
;         acc[ai][bj][m][n] = __builtin_amdgcn_mfma_f32_16x16x32_bf16(Bt[n][k], At[m][k], acc[ai][bj][m][n], 0, 0, 0); __builtin_amdgcn_s_setprio(0); } while (0)
; #define G8_WAIT_V(n) asm volatile("s_waitcnt vmcnt(" #n ")" ::: "memory")
; #define G8_WAIT_L(n) asm volatile("s_waitcnt lgkmcnt(" #n ")" ::: "memory")
; #define G8_BAR __builtin_amdgcn_s_barrier()
; #define G8_SCHED __builtin_amdgcn_sched_barrier(0)
; template <class P>
; __device__ __forceinline__ void gemm_phase(LAS unsigned char* lds, const P& p, const int G, const int c) {
;     ...
;             G8_LDB(B0, 1, 0); G8_LDB(B1, 1, 1); G8_SCHED; G8_LDA(At, 1, 0); G8_STA(G8_SA(0, 1), a2, sg2, 1);
;             G8_WAIT_V(8); G8_WAIT_L(0); G8_BAR; G8_MMA(0, 0, At, B0); G8_MMA(0, 1, At, B1); G8_BAR; G8_SCHED;
;             G8_LDA(At, 1, 1); G8_STB(G8_SB(1, 0), b3, sg2, 0); G8_STB(G8_SB(1, 1), b3, sg2, 1); G8_STA(G8_SA(1, 0), a3, sg2, 0);
;             G8_WAIT_V(8); G8_WAIT_L(0); G8_BAR; G8_MMA(1, 0, At, B0); G8_MMA(1, 1, At, B1); G8_BAR; G8_SCHED;
;         }
;         if (wr == 0) G8_BAR;
.Lmid_707:
	s_barrier
	s_add_i32 s65, 0, 0x18000
	v_add_u32_e32 v84, s65, v229
	s_add_i32 s66, 0, 0x1c000
	ds_read_b128 v[68:71], v84
	ds_read_b128 v[72:75], v84 offset:1024
	ds_read_b128 v[76:79], v84 offset:2048
	ds_read_b128 v[138:141], v84 offset:3072
	v_add_u32_e32 v84, s66, v229
	ds_read_b128 v[142:145], v84
	ds_read_b128 v[154:157], v84 offset:1024
	ds_read_b128 v[158:161], v84 offset:2048
	ds_read_b128 v[162:165], v84 offset:3072
	s_mov_b32 m0, s27
	v_lshl_add_u64 v[84:85], v[200:201], 0, s[14:15]
	ds_read_b128 v[166:169], v232 offset:32768
	ds_read_b128 v[170:173], v232 offset:33792
	ds_read_b128 v[174:177], v232 offset:34816
	ds_read_b128 v[178:181], v232 offset:35840
	ds_read_b128 v[182:185], v232 offset:36864
	ds_read_b128 v[186:189], v232 offset:37888
	ds_read_b128 v[190:193], v232 offset:38912
	ds_read_b128 v[194:197], v232 offset:39936
	global_load_lds_dwordx4 v[84:85], off
	v_lshl_add_u64 v[84:85], v[200:201], 0, s[16:17]
	s_mov_b32 m0, s31
	s_nop 0
	global_load_lds_dwordx4 v[84:85], off
	s_waitcnt vmcnt(8)
	s_waitcnt lgkmcnt(0)
	s_barrier
	s_waitcnt lgkmcnt(0)
	v_mfma_f32_16x16x32_bf16 v[150:153], v[68:71], v[166:169], v[150:153]
	v_mfma_f32_16x16x32_bf16 v[146:149], v[76:79], v[166:169], v[146:149]
	v_mfma_f32_16x16x32_bf16 v[126:129], v[68:71], v[174:177], v[126:129]
	v_mfma_f32_16x16x32_bf16 v[122:125], v[76:79], v[174:177], v[122:125]
	v_mfma_f32_16x16x32_bf16 v[110:113], v[68:71], v[182:185], v[110:113]
	v_mfma_f32_16x16x32_bf16 v[106:109], v[76:79], v[182:185], v[106:109]
	v_mfma_f32_16x16x32_bf16 v[94:97], v[68:71], v[190:193], v[94:97]
	v_mfma_f32_16x16x32_bf16 v[90:93], v[76:79], v[190:193], v[90:93]
	v_mfma_f32_16x16x32_bf16 v[150:153], v[72:75], v[170:173], v[150:153]
	v_mfma_f32_16x16x32_bf16 v[146:149], v[138:141], v[170:173], v[146:149]
	v_mfma_f32_16x16x32_bf16 v[126:129], v[72:75], v[178:181], v[126:129]
	v_mfma_f32_16x16x32_bf16 v[122:125], v[138:141], v[178:181], v[122:125]
	v_mfma_f32_16x16x32_bf16 v[110:113], v[72:75], v[186:189], v[110:113]
	v_mfma_f32_16x16x32_bf16 v[106:109], v[138:141], v[186:189], v[106:109]
	v_mfma_f32_16x16x32_bf16 v[94:97], v[72:75], v[194:197], v[94:97]
	v_mfma_f32_16x16x32_bf16 v[90:93], v[138:141], v[194:197], v[90:93]
	v_mfma_f32_16x16x32_bf16 v[134:137], v[142:145], v[166:169], v[134:137]
	v_mfma_f32_16x16x32_bf16 v[130:133], v[158:161], v[166:169], v[130:133]
	v_mfma_f32_16x16x32_bf16 v[118:121], v[142:145], v[174:177], v[118:121]
	v_mfma_f32_16x16x32_bf16 v[114:117], v[158:161], v[174:177], v[114:117]
	v_mfma_f32_16x16x32_bf16 v[102:105], v[142:145], v[182:185], v[102:105]
	v_mfma_f32_16x16x32_bf16 v[98:101], v[158:161], v[182:185], v[98:101]
	v_mfma_f32_16x16x32_bf16 v[84:87], v[142:145], v[190:193], v[86:89]
	v_mfma_f32_16x16x32_bf16 v[80:83], v[158:161], v[190:193], v[80:83]
	v_mfma_f32_16x16x32_bf16 v[134:137], v[154:157], v[170:173], v[134:137]
	v_mfma_f32_16x16x32_bf16 v[130:133], v[162:165], v[170:173], v[130:133]
	v_mfma_f32_16x16x32_bf16 v[118:121], v[154:157], v[178:181], v[118:121]
	v_mfma_f32_16x16x32_bf16 v[114:117], v[162:165], v[178:181], v[114:117]
	v_mfma_f32_16x16x32_bf16 v[102:105], v[154:157], v[186:189], v[102:105]
	v_mfma_f32_16x16x32_bf16 v[98:101], v[162:165], v[186:189], v[98:101]
	v_mfma_f32_16x16x32_bf16 v[86:89], v[154:157], v[194:197], v[84:87]
	v_mfma_f32_16x16x32_bf16 v[82:85], v[162:165], v[194:197], v[80:83]
	s_barrier
	ds_read_b128 v[166:169], v232 offset:49152
	ds_read_b128 v[170:173], v232 offset:50176
	ds_read_b128 v[174:177], v232 offset:51200
	ds_read_b128 v[178:181], v232 offset:52224
	ds_read_b128 v[182:185], v232 offset:53248
	ds_read_b128 v[186:189], v232 offset:54272
	ds_read_b128 v[190:193], v232 offset:55296
	ds_read_b128 v[194:197], v232 offset:56320
	s_add_i32 s65, s65, s24
	s_mov_b32 m0, s65
	v_lshl_add_u64 v[80:81], v[198:199], 0, s[36:37]
	global_load_lds_dwordx4 v[80:81], off
	v_lshl_add_u64 v[80:81], v[198:199], 0, s[38:39]
	s_add_i32 m0, s65, 0x2000
	s_add_i32 s65, s66, s24
	global_load_lds_dwordx4 v[80:81], off
	v_lshl_add_u64 v[80:81], v[198:199], 0, s[44:45]
	s_mov_b32 m0, s65
	s_nop 0
	global_load_lds_dwordx4 v[80:81], off
	v_lshl_add_u64 v[80:81], v[198:199], 0, s[48:49]
	s_add_i32 m0, s65, 0x2000
	s_nop 0
	global_load_lds_dwordx4 v[80:81], off
	v_lshl_add_u64 v[80:81], v[200:201], 0, s[40:41]
	s_mov_b32 m0, s46
	s_nop 0
	global_load_lds_dwordx4 v[80:81], off
	v_lshl_add_u64 v[80:81], v[200:201], 0, s[42:43]
	s_mov_b32 m0, s47
	s_nop 0
	global_load_lds_dwordx4 v[80:81], off
	s_waitcnt vmcnt(8)
	s_waitcnt lgkmcnt(0)
	s_barrier
	s_waitcnt lgkmcnt(0)
	v_mfma_f32_16x16x32_bf16 v[62:65], v[68:71], v[166:169], v[62:65]
	v_mfma_f32_16x16x32_bf16 v[58:61], v[76:79], v[166:169], v[58:61]
	v_mfma_f32_16x16x32_bf16 v[46:49], v[68:71], v[174:177], v[46:49]
	v_mfma_f32_16x16x32_bf16 v[42:45], v[76:79], v[174:177], v[42:45]
	s_add_i32 s64, s64, 2
	v_mfma_f32_16x16x32_bf16 v[30:33], v[68:71], v[182:185], v[30:33]
	s_add_u32 s28, s28, 0x80000
	v_mfma_f32_16x16x32_bf16 v[26:29], v[76:79], v[182:185], v[26:29]
	s_addc_u32 s29, s29, 0
	v_mfma_f32_16x16x32_bf16 v[14:17], v[68:71], v[190:193], v[14:17]
	s_add_u32 s76, s76, 0x800000
	v_mfma_f32_16x16x32_bf16 v[10:13], v[76:79], v[190:193], v[10:13]
	s_addc_u32 s77, s77, 0
	v_mfma_f32_16x16x32_bf16 v[62:65], v[72:75], v[170:173], v[62:65]
	s_cmp_gt_u32 s64, 29
	v_mfma_f32_16x16x32_bf16 v[58:61], v[138:141], v[170:173], v[58:61]
	v_mfma_f32_16x16x32_bf16 v[46:49], v[72:75], v[178:181], v[46:49]
	v_mfma_f32_16x16x32_bf16 v[42:45], v[138:141], v[178:181], v[42:45]
	v_mfma_f32_16x16x32_bf16 v[30:33], v[72:75], v[186:189], v[30:33]
	v_mfma_f32_16x16x32_bf16 v[26:29], v[138:141], v[186:189], v[26:29]
	v_mfma_f32_16x16x32_bf16 v[14:17], v[72:75], v[194:197], v[14:17]
	v_mfma_f32_16x16x32_bf16 v[10:13], v[138:141], v[194:197], v[10:13]
	v_mfma_f32_16x16x32_bf16 v[54:57], v[142:145], v[166:169], v[54:57]
	v_mfma_f32_16x16x32_bf16 v[50:53], v[158:161], v[166:169], v[50:53]
	v_mfma_f32_16x16x32_bf16 v[38:41], v[142:145], v[174:177], v[38:41]
	v_mfma_f32_16x16x32_bf16 v[34:37], v[158:161], v[174:177], v[34:37]
	v_mfma_f32_16x16x32_bf16 v[22:25], v[142:145], v[182:185], v[22:25]
	v_mfma_f32_16x16x32_bf16 v[18:21], v[158:161], v[182:185], v[18:21]
	v_mfma_f32_16x16x32_bf16 v[6:9], v[142:145], v[190:193], v[6:9]
	v_mfma_f32_16x16x32_bf16 v[2:5], v[158:161], v[190:193], v[2:5]
	v_mfma_f32_16x16x32_bf16 v[54:57], v[154:157], v[170:173], v[54:57]
	v_mfma_f32_16x16x32_bf16 v[50:53], v[162:165], v[170:173], v[50:53]
	v_mfma_f32_16x16x32_bf16 v[38:41], v[154:157], v[178:181], v[38:41]
	v_mfma_f32_16x16x32_bf16 v[34:37], v[162:165], v[178:181], v[34:37]
	v_mfma_f32_16x16x32_bf16 v[22:25], v[154:157], v[186:189], v[22:25]
	v_mfma_f32_16x16x32_bf16 v[18:21], v[162:165], v[186:189], v[18:21]
	v_mfma_f32_16x16x32_bf16 v[6:9], v[154:157], v[194:197], v[6:9]
	v_mfma_f32_16x16x32_bf16 v[2:5], v[162:165], v[194:197], v[2:5]
	s_barrier
	s_cbranch_scc0 .LBB0_707
	s_and_b64 vcc, exec, s[52:53]
	s_cbranch_vccz .LBB0_710
	s_barrier

; #define G8_STA(bufoff, ptr, sg, h) G8_STAGE1(bufoff, (ptr) + (h) * ((sg) ? hA1 : hA0), ((sg) ? voffA1 : voffA0), ((sg) ? r64A1 : r64A0))
; #define G8_STB(bufoff, ptr, sg, h) G8_STAGE1(bufoff, (ptr) + (h) * ((sg) ? hB1 : hB0), ((sg) ? voffB1 : voffB0), ((sg) ? r64B1 : r64B0))
; #define G8_LDA(dst, b, h) do { _Pragma("unroll") for (int m = 0; m < 4; ++m) _Pragma("unroll") for (int k = 0; k < 2; ++k) dst[m][k] = *(const LAS bf16x8*)(lds + G8_SA(b, h) + aoff + m * 2048 + k * 1024); } while (0)
; #define G8_LDB(dst, b, h) do { _Pragma("unroll") for (int n = 0; n < 2; ++n) _Pragma("unroll") for (int k = 0; k < 2; ++k) dst[n][k] = *(const LAS bf16x8*)(lds + G8_SB(b, h) + boff + n * 2048 + k * 1024); } while (0)
; #define G8_BAR __builtin_amdgcn_s_barrier()
; template <class P>
; __device__ __forceinline__ void gemm_phase(LAS unsigned char* lds, const P& p, const int G, const int c) {
;     ...
;         const bool has_next = p.unit((ui + 1) * G + c, nxt);
;         const int nt = p.nt(cur);
;         const char* nA0 = has_next ? p.a_base(nxt, 0) - p.a_bias(0) : cA0; const char* nA1 = has_next ? p.a_base(nxt, S1) - p.a_bias(S1) : cA1;
;         const char* nB0 = has_next ? p.b_base(nxt, 0) - p.b_bias(0) : cB0; const char* nB1 = has_next ? p.b_base(nxt, S1) - p.b_bias(S1) : cB1;
;         for (int t = 0; t < nt; t += 2) {
;             const bool last = (t == nt - 2);
;             const bool sg1 = (NS > 1) && (t + 1 >= nt0);
;             const bool sg2 = (NS > 1) && !last && (t + 2 >= nt0);
;             const char* a1 = sg1 ? cA1 + (long)(t + 1 - nt0) * ksA1 : cA0 + (long)(t + 1) * ksA0;
;             const char* a2 = last ? nA0 : (sg2 ? cA1 + (long)(t + 2 - nt0) * ksA1 : cA0 + (long)(t + 2) * ksA0);
;             const char* b2 = last ? nB0 : (sg2 ? cB1 + (long)(t + 2 - nt0) * ksB1 : cB0 + (long)(t + 2) * ksB0);
;             const char* a3 = a2 + (sg2 ? ksA1 : ksA0); const char* b3 = b2 + (sg2 ? ksB1 : ksB0);
;             G8_LDB(B0, 0, 0); G8_LDB(B1, 0, 1); G8_SCHED; G8_LDA(At, 0, 0); G8_STA(G8_SA(1, 1), a1, sg1, 1);
;             G8_WAIT_V(8); G8_WAIT_L(0); G8_BAR; G8_MMA(0, 0, At, B0); G8_MMA(0, 1, At, B1); G8_BAR; G8_SCHED;
;             G8_LDA(At, 0, 1); G8_STB(G8_SB(0, 0), b2, sg2, 0); G8_STB(G8_SB(0, 1), b2, sg2, 1); G8_STA(G8_SA(0, 0), a2, sg2, 0);
;             G8_WAIT_V(8); G8_WAIT_L(0); G8_BAR; G8_MMA(1, 0, At, B0); G8_MMA(1, 1, At, B1); G8_BAR; G8_SCHED;
.LBB0_769:
	s_ashr_i32 s57, s56, 31
	s_lshl_b64 s[18:19], s[56:57], 15
	s_add_u32 s60, s2, s18
	s_addc_u32 s61, s3, s19
	s_and_b64 s[18:19], s[54:55], exec
	s_cselect_b32 s18, s61, s71
	s_cselect_b32 s19, s60, s70
	s_ashr_i32 s59, s58, 31
	s_lshl_b64 s[62:63], s[58:59], 15
	s_add_u32 s62, s24, s62
	s_addc_u32 s63, s25, s63
	s_and_b64 s[72:73], s[54:55], exec
	s_cselect_b32 s57, s63, s29
	s_cselect_b32 s59, s62, s28
	s_add_u32 s28, s28, 0x40000
	s_addc_u32 s29, s29, 0
	v_lshl_add_u64 v[128:129], s[70:71], 0, v[152:153]
	s_mov_b32 s76, -2
	s_mov_b64 s[72:73], 0
	ds_read_b128 v[130:133], v158
	ds_read_b128 v[134:137], v158 offset:1024
	ds_read_b128 v[138:141], v158 offset:2048
	ds_read_b128 v[162:165], v158 offset:3072
	ds_read_b128 v[166:169], v159
	ds_read_b128 v[170:173], v159 offset:1024
	ds_read_b128 v[174:177], v159 offset:2048
	ds_read_b128 v[178:181], v159 offset:3072
	s_add_u32 s77, s70, s72
	s_addc_u32 s78, s71, s73
	s_add_u32 s77, s77, 0x800000
	s_addc_u32 s78, s78, 0
	s_cmp_eq_u32 s72, 0x7800000
	s_cselect_b32 s79, s18, s78
	s_cselect_b32 s78, s19, s77
	s_cselect_b32 s81, s57, s29
	s_cselect_b32 s80, s59, s28
	v_lshl_add_u64 v[142:143], v[128:129], 0, s[72:73]
	v_lshl_add_u64 v[154:155], v[142:143], 0, s[40:41]
	s_add_i32 m0, s27, 0xc000
	ds_read_b128 v[182:185], v160
	ds_read_b128 v[186:189], v160 offset:1024
	ds_read_b128 v[190:193], v160 offset:2048
	ds_read_b128 v[194:197], v160 offset:3072
	ds_read_b128 v[198:201], v160 offset:4096
	ds_read_b128 v[202:205], v160 offset:5120
	ds_read_b128 v[210:213], v160 offset:6144
	ds_read_b128 v[214:217], v160 offset:7168
	global_load_lds_dwordx4 v[154:155], off
	v_lshl_add_u64 v[142:143], v[142:143], 0, s[42:43]
	s_add_i32 m0, s27, 0xe000
	s_nop 0
	global_load_lds_dwordx4 v[142:143], off
	s_waitcnt vmcnt(8)
	s_waitcnt lgkmcnt(0)
	s_barrier
	s_waitcnt lgkmcnt(0)
	v_mfma_f32_16x16x32_bf16 v[120:123], v[130:133], v[182:185], 0
	v_mfma_f32_16x16x32_bf16 v[124:127], v[138:141], v[182:185], 0
	v_mfma_f32_16x16x32_bf16 v[112:115], v[130:133], v[190:193], 0
	v_mfma_f32_16x16x32_bf16 v[116:119], v[138:141], v[190:193], 0
	v_mfma_f32_16x16x32_bf16 v[100:103], v[130:133], v[198:201], 0
	v_mfma_f32_16x16x32_bf16 v[108:111], v[138:141], v[198:201], 0
	v_mfma_f32_16x16x32_bf16 v[84:87], v[130:133], v[210:213], 0
	v_mfma_f32_16x16x32_bf16 v[72:75], v[138:141], v[210:213], 0
	v_mfma_f32_16x16x32_bf16 v[120:123], v[134:137], v[186:189], v[120:123]
	v_mfma_f32_16x16x32_bf16 v[124:127], v[162:165], v[186:189], v[124:127]
	v_mfma_f32_16x16x32_bf16 v[112:115], v[134:137], v[194:197], v[112:115]
	v_mfma_f32_16x16x32_bf16 v[116:119], v[162:165], v[194:197], v[116:119]
	v_mfma_f32_16x16x32_bf16 v[100:103], v[134:137], v[202:205], v[100:103]
	v_mfma_f32_16x16x32_bf16 v[108:111], v[162:165], v[202:205], v[108:111]
	v_mfma_f32_16x16x32_bf16 v[84:87], v[134:137], v[214:217], v[84:87]
	v_mfma_f32_16x16x32_bf16 v[72:75], v[162:165], v[214:217], v[72:75]
	v_mfma_f32_16x16x32_bf16 v[104:107], v[166:169], v[182:185], 0
	v_mfma_f32_16x16x32_bf16 v[92:95], v[174:177], v[182:185], 0
	v_mfma_f32_16x16x32_bf16 v[96:99], v[166:169], v[190:193], 0
	v_mfma_f32_16x16x32_bf16 v[80:83], v[174:177], v[190:193], 0
	v_mfma_f32_16x16x32_bf16 v[88:91], v[166:169], v[198:201], 0
	v_mfma_f32_16x16x32_bf16 v[76:79], v[174:177], v[198:201], 0
	v_mfma_f32_16x16x32_bf16 v[68:71], v[166:169], v[210:213], 0
	v_mfma_f32_16x16x32_bf16 v[64:67], v[174:177], v[210:213], 0
	v_mfma_f32_16x16x32_bf16 v[104:107], v[170:173], v[186:189], v[104:107]
	v_mfma_f32_16x16x32_bf16 v[92:95], v[178:181], v[186:189], v[92:95]
	v_mfma_f32_16x16x32_bf16 v[96:99], v[170:173], v[194:197], v[96:99]
	v_mfma_f32_16x16x32_bf16 v[80:83], v[178:181], v[194:197], v[80:83]
	v_mfma_f32_16x16x32_bf16 v[88:91], v[170:173], v[202:205], v[88:91]
	v_mfma_f32_16x16x32_bf16 v[76:79], v[178:181], v[202:205], v[76:79]
	v_mfma_f32_16x16x32_bf16 v[68:71], v[170:173], v[214:217], v[68:71]
	v_mfma_f32_16x16x32_bf16 v[64:67], v[178:181], v[214:217], v[64:67]
	s_barrier
	ds_read_b128 v[182:185], v160 offset:16384
	ds_read_b128 v[186:189], v160 offset:17408
	ds_read_b128 v[190:193], v160 offset:18432
	ds_read_b128 v[194:197], v160 offset:19456
	ds_read_b128 v[198:201], v160 offset:20480
	ds_read_b128 v[202:205], v160 offset:21504
	ds_read_b128 v[210:213], v160 offset:22528
	ds_read_b128 v[214:217], v160 offset:23552
	s_add_i32 s77, s30, s26
	s_mov_b32 m0, s77
	v_lshl_add_u64 v[142:143], s[80:81], 0, v[144:145]
	global_load_lds_dwordx4 v[142:143], off
	v_lshl_add_u64 v[154:155], v[142:143], 0, s[4:5]
	s_add_i32 m0, s77, 0x2000
	s_add_i32 s77, s74, s26
	global_load_lds_dwordx4 v[154:155], off
	v_lshl_add_u64 v[154:155], v[142:143], 0, s[6:7]
	s_mov_b32 m0, s77
	s_nop 0
	global_load_lds_dwordx4 v[154:155], off
	v_lshl_add_u64 v[154:155], v[142:143], 0, s[8:9]
	s_add_i32 m0, s77, 0x2000
	s_nop 0
	global_load_lds_dwordx4 v[154:155], off
	v_lshl_add_u64 v[154:155], s[78:79], 0, v[146:147]
	s_mov_b32 m0, s27
	v_lshl_add_u64 v[206:207], v[154:155], 0, s[4:5]
	global_load_lds_dwordx4 v[154:155], off
	s_mov_b32 m0, s31
	s_nop 0
	global_load_lds_dwordx4 v[206:207], off
	s_waitcnt vmcnt(8)
	s_waitcnt lgkmcnt(0)
	s_barrier
; #define G8_STA(bufoff, ptr, sg, h) G8_STAGE1(bufoff, (ptr) + (h) * ((sg) ? hA1 : hA0), ((sg) ? voffA1 : voffA0), ((sg) ? r64A1 : r64A0))
; #define G8_STB(bufoff, ptr, sg, h) G8_STAGE1(bufoff, (ptr) + (h) * ((sg) ? hB1 : hB0), ((sg) ? voffB1 : voffB0), ((sg) ? r64B1 : r64B0))
; #define G8_LDA(dst, b, h) do { _Pragma("unroll") for (int m = 0; m < 4; ++m) _Pragma("unroll") for (int k = 0; k < 2; ++k) dst[m][k] = *(const LAS bf16x8*)(lds + G8_SA(b, h) + aoff + m * 2048 + k * 1024); } while (0)
; #define G8_LDB(dst, b, h) do { _Pragma("unroll") for (int n = 0; n < 2; ++n) _Pragma("unroll") for (int k = 0; k < 2; ++k) dst[n][k] = *(const LAS bf16x8*)(lds + G8_SB(b, h) + boff + n * 2048 + k * 1024); } while (0)
; #define G8_MMA(ai, bj, At, Bt) do { __builtin_amdgcn_s_setprio(1); _Pragma("unroll") for (int m = 0; m < 4; ++m) _Pragma("unroll") for (int n = 0; n < 2; ++n) _Pragma("unroll") for (int k = 0; k < 2; ++k) \
;         acc[ai][bj][m][n] = __builtin_amdgcn_mfma_f32_16x16x32_bf16(Bt[n][k], At[m][k], acc[ai][bj][m][n], 0, 0, 0); __builtin_amdgcn_s_setprio(0); } while (0)
; #define G8_WAIT_V(n) asm volatile("s_waitcnt vmcnt(" #n ")" ::: "memory")
; #define G8_WAIT_L(n) asm volatile("s_waitcnt lgkmcnt(" #n ")" ::: "memory")
; #define G8_BAR __builtin_amdgcn_s_barrier()
; #define G8_SCHED __builtin_amdgcn_sched_barrier(0)
; template <class P>
; __device__ __forceinline__ void gemm_phase(LAS unsigned char* lds, const P& p, const int G, const int c) {
;     ...
;             G8_LDB(B0, 0, 0); G8_LDB(B1, 0, 1); G8_SCHED; G8_LDA(At, 0, 0); G8_STA(G8_SA(1, 1), a1, sg1, 1);
;             G8_WAIT_V(8); G8_WAIT_L(0); G8_BAR; G8_MMA(0, 0, At, B0); G8_MMA(0, 1, At, B1); G8_BAR; G8_SCHED;
;             G8_LDA(At, 0, 1); G8_STB(G8_SB(0, 0), b2, sg2, 0); G8_STB(G8_SB(0, 1), b2, sg2, 1); G8_STA(G8_SA(0, 0), a2, sg2, 0);
;             G8_WAIT_V(8); G8_WAIT_L(0); G8_BAR; G8_MMA(1, 0, At, B0); G8_MMA(1, 1, At, B1); G8_BAR; G8_SCHED;
	s_waitcnt lgkmcnt(0)
	v_mfma_f32_16x16x32_bf16 v[60:63], v[130:133], v[182:185], 0
	v_mfma_f32_16x16x32_bf16 v[56:59], v[138:141], v[182:185], 0
	v_mfma_f32_16x16x32_bf16 v[52:55], v[130:133], v[190:193], 0
	v_mfma_f32_16x16x32_bf16 v[44:47], v[138:141], v[190:193], 0
	v_mfma_f32_16x16x32_bf16 v[36:39], v[130:133], v[198:201], 0
	v_mfma_f32_16x16x32_bf16 v[28:31], v[138:141], v[198:201], 0
	v_mfma_f32_16x16x32_bf16 v[20:23], v[130:133], v[210:213], 0
	v_mfma_f32_16x16x32_bf16 v[12:15], v[138:141], v[210:213], 0
	v_mfma_f32_16x16x32_bf16 v[60:63], v[134:137], v[186:189], v[60:63]
	v_mfma_f32_16x16x32_bf16 v[56:59], v[162:165], v[186:189], v[56:59]
	v_mfma_f32_16x16x32_bf16 v[52:55], v[134:137], v[194:197], v[52:55]
	v_mfma_f32_16x16x32_bf16 v[44:47], v[162:165], v[194:197], v[44:47]
	v_mfma_f32_16x16x32_bf16 v[36:39], v[134:137], v[202:205], v[36:39]
	v_mfma_f32_16x16x32_bf16 v[28:31], v[162:165], v[202:205], v[28:31]
	v_mfma_f32_16x16x32_bf16 v[20:23], v[134:137], v[214:217], v[20:23]
	v_mfma_f32_16x16x32_bf16 v[12:15], v[162:165], v[214:217], v[12:15]
	v_mfma_f32_16x16x32_bf16 v[48:51], v[166:169], v[182:185], 0
	v_mfma_f32_16x16x32_bf16 v[40:43], v[174:177], v[182:185], 0
	v_mfma_f32_16x16x32_bf16 v[32:35], v[166:169], v[190:193], 0
	v_mfma_f32_16x16x32_bf16 v[24:27], v[174:177], v[190:193], 0
	v_mfma_f32_16x16x32_bf16 v[16:19], v[166:169], v[198:201], 0
	v_mfma_f32_16x16x32_bf16 v[8:11], v[174:177], v[198:201], 0
	v_mfma_f32_16x16x32_bf16 v[4:7], v[166:169], v[210:213], 0
	v_mfma_f32_16x16x32_bf16 v[0:3], v[174:177], v[210:213], 0
	v_mfma_f32_16x16x32_bf16 v[48:51], v[170:173], v[186:189], v[48:51]
	v_mfma_f32_16x16x32_bf16 v[40:43], v[178:181], v[186:189], v[40:43]
	v_mfma_f32_16x16x32_bf16 v[32:35], v[170:173], v[194:197], v[32:35]
	v_mfma_f32_16x16x32_bf16 v[24:27], v[178:181], v[194:197], v[24:27]
	v_mfma_f32_16x16x32_bf16 v[16:19], v[170:173], v[202:205], v[16:19]
	v_mfma_f32_16x16x32_bf16 v[8:11], v[178:181], v[202:205], v[8:11]
	v_mfma_f32_16x16x32_bf16 v[4:7], v[170:173], v[214:217], v[4:7]
	v_mfma_f32_16x16x32_bf16 v[0:3], v[178:181], v[214:217], v[0:3]
	s_branch .Lmid_770
.LBB0_770:
	ds_read_b128 v[130:133], v158
	ds_read_b128 v[134:137], v158 offset:1024
	ds_read_b128 v[138:141], v158 offset:2048
	ds_read_b128 v[162:165], v158 offset:3072
	ds_read_b128 v[166:169], v159
	ds_read_b128 v[170:173], v159 offset:1024
	ds_read_b128 v[174:177], v159 offset:2048
	ds_read_b128 v[178:181], v159 offset:3072
	s_add_u32 s77, s70, s72
	s_addc_u32 s78, s71, s73
	s_add_u32 s77, s77, 0x800000
	s_addc_u32 s78, s78, 0
	s_cmp_eq_u32 s72, 0x7800000
	s_cselect_b32 s79, s18, s78
	s_cselect_b32 s78, s19, s77
	s_cselect_b32 s81, s57, s29
	s_cselect_b32 s80, s59, s28
	v_lshl_add_u64 v[142:143], v[128:129], 0, s[72:73]
	v_lshl_add_u64 v[154:155], v[142:143], 0, s[40:41]
	s_add_i32 m0, s27, 0xc000
	ds_read_b128 v[182:185], v160
	ds_read_b128 v[186:189], v160 offset:1024
	ds_read_b128 v[190:193], v160 offset:2048
	ds_read_b128 v[194:197], v160 offset:3072
	ds_read_b128 v[198:201], v160 offset:4096
	ds_read_b128 v[202:205], v160 offset:5120
	ds_read_b128 v[210:213], v160 offset:6144
	ds_read_b128 v[214:217], v160 offset:7168
	global_load_lds_dwordx4 v[154:155], off
	v_lshl_add_u64 v[142:143], v[142:143], 0, s[42:43]
	s_add_i32 m0, s27, 0xe000
	s_nop 0
	global_load_lds_dwordx4 v[142:143], off
	s_waitcnt vmcnt(8)
	s_waitcnt lgkmcnt(0)
	s_barrier
	s_waitcnt lgkmcnt(0)
	v_mfma_f32_16x16x32_bf16 v[120:123], v[130:133], v[182:185], v[120:123]
	v_mfma_f32_16x16x32_bf16 v[124:127], v[138:141], v[182:185], v[124:127]
	v_mfma_f32_16x16x32_bf16 v[112:115], v[130:133], v[190:193], v[112:115]
	v_mfma_f32_16x16x32_bf16 v[116:119], v[138:141], v[190:193], v[116:119]
	v_mfma_f32_16x16x32_bf16 v[100:103], v[130:133], v[198:201], v[100:103]
	v_mfma_f32_16x16x32_bf16 v[108:111], v[138:141], v[198:201], v[108:111]
	v_mfma_f32_16x16x32_bf16 v[84:87], v[130:133], v[210:213], v[84:87]
	v_mfma_f32_16x16x32_bf16 v[72:75], v[138:141], v[210:213], v[72:75]
	v_mfma_f32_16x16x32_bf16 v[120:123], v[134:137], v[186:189], v[120:123]
	v_mfma_f32_16x16x32_bf16 v[124:127], v[162:165], v[186:189], v[124:127]
	v_mfma_f32_16x16x32_bf16 v[112:115], v[134:137], v[194:197], v[112:115]
	v_mfma_f32_16x16x32_bf16 v[116:119], v[162:165], v[194:197], v[116:119]
	v_mfma_f32_16x16x32_bf16 v[100:103], v[134:137], v[202:205], v[100:103]
	v_mfma_f32_16x16x32_bf16 v[108:111], v[162:165], v[202:205], v[108:111]
	v_mfma_f32_16x16x32_bf16 v[84:87], v[134:137], v[214:217], v[84:87]
	v_mfma_f32_16x16x32_bf16 v[72:75], v[162:165], v[214:217], v[72:75]
	v_mfma_f32_16x16x32_bf16 v[104:107], v[166:169], v[182:185], v[104:107]
	v_mfma_f32_16x16x32_bf16 v[92:95], v[174:177], v[182:185], v[92:95]
	v_mfma_f32_16x16x32_bf16 v[96:99], v[166:169], v[190:193], v[96:99]
	v_mfma_f32_16x16x32_bf16 v[80:83], v[174:177], v[190:193], v[80:83]
	v_mfma_f32_16x16x32_bf16 v[88:91], v[166:169], v[198:201], v[88:91]
	v_mfma_f32_16x16x32_bf16 v[76:79], v[174:177], v[198:201], v[76:79]
	v_mfma_f32_16x16x32_bf16 v[68:71], v[166:169], v[210:213], v[68:71]
	v_mfma_f32_16x16x32_bf16 v[64:67], v[174:177], v[210:213], v[64:67]
	v_mfma_f32_16x16x32_bf16 v[104:107], v[170:173], v[186:189], v[104:107]
	v_mfma_f32_16x16x32_bf16 v[92:95], v[178:181], v[186:189], v[92:95]
	v_mfma_f32_16x16x32_bf16 v[96:99], v[170:173], v[194:197], v[96:99]
	v_mfma_f32_16x16x32_bf16 v[80:83], v[178:181], v[194:197], v[80:83]
	v_mfma_f32_16x16x32_bf16 v[88:91], v[170:173], v[202:205], v[88:91]
	v_mfma_f32_16x16x32_bf16 v[76:79], v[178:181], v[202:205], v[76:79]
	v_mfma_f32_16x16x32_bf16 v[68:71], v[170:173], v[214:217], v[68:71]
	v_mfma_f32_16x16x32_bf16 v[64:67], v[178:181], v[214:217], v[64:67]
	s_barrier
; #define G8_STA(bufoff, ptr, sg, h) G8_STAGE1(bufoff, (ptr) + (h) * ((sg) ? hA1 : hA0), ((sg) ? voffA1 : voffA0), ((sg) ? r64A1 : r64A0))
; #define G8_STB(bufoff, ptr, sg, h) G8_STAGE1(bufoff, (ptr) + (h) * ((sg) ? hB1 : hB0), ((sg) ? voffB1 : voffB0), ((sg) ? r64B1 : r64B0))
; #define G8_LDA(dst, b, h) do { _Pragma("unroll") for (int m = 0; m < 4; ++m) _Pragma("unroll") for (int k = 0; k < 2; ++k) dst[m][k] = *(const LAS bf16x8*)(lds + G8_SA(b, h) + aoff + m * 2048 + k * 1024); } while (0)
; #define G8_MMA(ai, bj, At, Bt) do { __builtin_amdgcn_s_setprio(1); _Pragma("unroll") for (int m = 0; m < 4; ++m) _Pragma("unroll") for (int n = 0; n < 2; ++n) _Pragma("unroll") for (int k = 0; k < 2; ++k) \
;         acc[ai][bj][m][n] = __builtin_amdgcn_mfma_f32_16x16x32_bf16(Bt[n][k], At[m][k], acc[ai][bj][m][n], 0, 0, 0); __builtin_amdgcn_s_setprio(0); } while (0)
; #define G8_WAIT_V(n) asm volatile("s_waitcnt vmcnt(" #n ")" ::: "memory")
; #define G8_WAIT_L(n) asm volatile("s_waitcnt lgkmcnt(" #n ")" ::: "memory")
; #define G8_BAR __builtin_amdgcn_s_barrier()
; #define G8_SCHED __builtin_amdgcn_sched_barrier(0)
; template <class P>
; __device__ __forceinline__ void gemm_phase(LAS unsigned char* lds, const P& p, const int G, const int c) {
;     ...
;             G8_LDA(At, 0, 1); G8_STB(G8_SB(0, 0), b2, sg2, 0); G8_STB(G8_SB(0, 1), b2, sg2, 1); G8_STA(G8_SA(0, 0), a2, sg2, 0);
;             G8_WAIT_V(8); G8_WAIT_L(0); G8_BAR; G8_MMA(1, 0, At, B0); G8_MMA(1, 1, At, B1); G8_BAR; G8_SCHED;
	ds_read_b128 v[182:185], v160 offset:16384
	ds_read_b128 v[186:189], v160 offset:17408
	ds_read_b128 v[190:193], v160 offset:18432
	ds_read_b128 v[194:197], v160 offset:19456
	ds_read_b128 v[198:201], v160 offset:20480
	ds_read_b128 v[202:205], v160 offset:21504
	ds_read_b128 v[210:213], v160 offset:22528
	ds_read_b128 v[214:217], v160 offset:23552
	s_add_i32 s77, s30, s26
	s_mov_b32 m0, s77
	v_lshl_add_u64 v[142:143], s[80:81], 0, v[144:145]
	global_load_lds_dwordx4 v[142:143], off
	v_lshl_add_u64 v[154:155], v[142:143], 0, s[4:5]
	s_add_i32 m0, s77, 0x2000
	s_add_i32 s77, s74, s26
	global_load_lds_dwordx4 v[154:155], off
	v_lshl_add_u64 v[154:155], v[142:143], 0, s[6:7]
	s_mov_b32 m0, s77
	s_nop 0
	global_load_lds_dwordx4 v[154:155], off
	v_lshl_add_u64 v[154:155], v[142:143], 0, s[8:9]
	s_add_i32 m0, s77, 0x2000
	s_nop 0
	global_load_lds_dwordx4 v[154:155], off
	v_lshl_add_u64 v[154:155], s[78:79], 0, v[146:147]
	s_mov_b32 m0, s27
	v_lshl_add_u64 v[206:207], v[154:155], 0, s[4:5]
	global_load_lds_dwordx4 v[154:155], off
	s_mov_b32 m0, s31
	s_nop 0
	global_load_lds_dwordx4 v[206:207], off
	s_waitcnt vmcnt(8)
	s_waitcnt lgkmcnt(0)
	s_barrier
	s_waitcnt lgkmcnt(0)
	v_mfma_f32_16x16x32_bf16 v[60:63], v[130:133], v[182:185], v[60:63]
	v_mfma_f32_16x16x32_bf16 v[56:59], v[138:141], v[182:185], v[56:59]
	v_mfma_f32_16x16x32_bf16 v[52:55], v[130:133], v[190:193], v[52:55]
	v_mfma_f32_16x16x32_bf16 v[44:47], v[138:141], v[190:193], v[44:47]
	v_mfma_f32_16x16x32_bf16 v[36:39], v[130:133], v[198:201], v[36:39]
	v_mfma_f32_16x16x32_bf16 v[28:31], v[138:141], v[198:201], v[28:31]
	v_mfma_f32_16x16x32_bf16 v[20:23], v[130:133], v[210:213], v[20:23]
	v_mfma_f32_16x16x32_bf16 v[12:15], v[138:141], v[210:213], v[12:15]
	v_mfma_f32_16x16x32_bf16 v[60:63], v[134:137], v[186:189], v[60:63]
	v_mfma_f32_16x16x32_bf16 v[56:59], v[162:165], v[186:189], v[56:59]
	v_mfma_f32_16x16x32_bf16 v[52:55], v[134:137], v[194:197], v[52:55]
	v_mfma_f32_16x16x32_bf16 v[44:47], v[162:165], v[194:197], v[44:47]
	v_mfma_f32_16x16x32_bf16 v[36:39], v[134:137], v[202:205], v[36:39]
	v_mfma_f32_16x16x32_bf16 v[28:31], v[162:165], v[202:205], v[28:31]
	v_mfma_f32_16x16x32_bf16 v[20:23], v[134:137], v[214:217], v[20:23]
	v_mfma_f32_16x16x32_bf16 v[12:15], v[162:165], v[214:217], v[12:15]
	v_mfma_f32_16x16x32_bf16 v[48:51], v[166:169], v[182:185], v[48:51]
	v_mfma_f32_16x16x32_bf16 v[40:43], v[174:177], v[182:185], v[40:43]
	v_mfma_f32_16x16x32_bf16 v[32:35], v[166:169], v[190:193], v[32:35]
	v_mfma_f32_16x16x32_bf16 v[24:27], v[174:177], v[190:193], v[24:27]
	v_mfma_f32_16x16x32_bf16 v[16:19], v[166:169], v[198:201], v[16:19]
	v_mfma_f32_16x16x32_bf16 v[8:11], v[174:177], v[198:201], v[8:11]
	v_mfma_f32_16x16x32_bf16 v[4:7], v[166:169], v[210:213], v[4:7]
	v_mfma_f32_16x16x32_bf16 v[0:3], v[174:177], v[210:213], v[0:3]
	v_mfma_f32_16x16x32_bf16 v[48:51], v[170:173], v[186:189], v[48:51]
	v_mfma_f32_16x16x32_bf16 v[40:43], v[178:181], v[186:189], v[40:43]
	v_mfma_f32_16x16x32_bf16 v[32:35], v[170:173], v[194:197], v[32:35]
	v_mfma_f32_16x16x32_bf16 v[24:27], v[178:181], v[194:197], v[24:27]
	v_mfma_f32_16x16x32_bf16 v[16:19], v[170:173], v[202:205], v[16:19]
	v_mfma_f32_16x16x32_bf16 v[8:11], v[178:181], v[202:205], v[8:11]
	v_mfma_f32_16x16x32_bf16 v[4:7], v[170:173], v[214:217], v[4:7]
	v_mfma_f32_16x16x32_bf16 v[0:3], v[178:181], v[214:217], v[0:3]
; #define G8_STA(bufoff, ptr, sg, h) G8_STAGE1(bufoff, (ptr) + (h) * ((sg) ? hA1 : hA0), ((sg) ? voffA1 : voffA0), ((sg) ? r64A1 : r64A0))
; #define G8_STB(bufoff, ptr, sg, h) G8_STAGE1(bufoff, (ptr) + (h) * ((sg) ? hB1 : hB0), ((sg) ? voffB1 : voffB0), ((sg) ? r64B1 : r64B0))
; #define G8_LDA(dst, b, h) do { _Pragma("unroll") for (int m = 0; m < 4; ++m) _Pragma("unroll") for (int k = 0; k < 2; ++k) dst[m][k] = *(const LAS bf16x8*)(lds + G8_SA(b, h) + aoff + m * 2048 + k * 1024); } while (0)
; #define G8_LDB(dst, b, h) do { _Pragma("unroll") for (int n = 0; n < 2; ++n) _Pragma("unroll") for (int k = 0; k < 2; ++k) dst[n][k] = *(const LAS bf16x8*)(lds + G8_SB(b, h) + boff + n * 2048 + k * 1024); } while (0)
; #define G8_MMA(ai, bj, At, Bt) do { __builtin_amdgcn_s_setprio(1); _Pragma("unroll") for (int m = 0; m < 4; ++m) _Pragma("unroll") for (int n = 0; n < 2; ++n) _Pragma("unroll") for (int k = 0; k < 2; ++k) \
;         acc[ai][bj][m][n] = __builtin_amdgcn_mfma_f32_16x16x32_bf16(Bt[n][k], At[m][k], acc[ai][bj][m][n], 0, 0, 0); __builtin_amdgcn_s_setprio(0); } while (0)
; #define G8_WAIT_V(n) asm volatile("s_waitcnt vmcnt(" #n ")" ::: "memory")
; #define G8_WAIT_L(n) asm volatile("s_waitcnt lgkmcnt(" #n ")" ::: "memory")
; #define G8_BAR __builtin_amdgcn_s_barrier()
; #define G8_SCHED __builtin_amdgcn_sched_barrier(0)
; template <class P>
; __device__ __forceinline__ void gemm_phase(LAS unsigned char* lds, const P& p, const int G, const int c) {
;     ...
;             G8_LDB(B0, 1, 0); G8_LDB(B1, 1, 1); G8_SCHED; G8_LDA(At, 1, 0); G8_STA(G8_SA(0, 1), a2, sg2, 1);
;             G8_WAIT_V(8); G8_WAIT_L(0); G8_BAR; G8_MMA(0, 0, At, B0); G8_MMA(0, 1, At, B1); G8_BAR; G8_SCHED;
;             G8_LDA(At, 1, 1); G8_STB(G8_SB(1, 0), b3, sg2, 0); G8_STB(G8_SB(1, 1), b3, sg2, 1); G8_STA(G8_SA(1, 0), a3, sg2, 0);
;             G8_WAIT_V(8); G8_WAIT_L(0); G8_BAR; G8_MMA(1, 0, At, B0); G8_MMA(1, 1, At, B1); G8_BAR; G8_SCHED;
;         }
;         if (wr == 0) G8_BAR;
.Lmid_770:
	s_barrier
	s_add_i32 s77, 0, 0x18000
	v_add_u32_e32 v161, s77, v156
	s_add_i32 s78, 0, 0x1c000
	ds_read_b128 v[130:133], v161
	ds_read_b128 v[134:137], v161 offset:1024
	ds_read_b128 v[138:141], v161 offset:2048
	ds_read_b128 v[162:165], v161 offset:3072
	v_add_u32_e32 v161, s78, v156
	ds_read_b128 v[166:169], v161
	ds_read_b128 v[170:173], v161 offset:1024
	ds_read_b128 v[174:177], v161 offset:2048
	ds_read_b128 v[178:181], v161 offset:3072
	s_mov_b32 m0, s33
	v_lshl_add_u64 v[206:207], v[154:155], 0, s[6:7]
	ds_read_b128 v[182:185], v160 offset:32768
	ds_read_b128 v[186:189], v160 offset:33792
	ds_read_b128 v[190:193], v160 offset:34816
	ds_read_b128 v[194:197], v160 offset:35840
	ds_read_b128 v[198:201], v160 offset:36864
	ds_read_b128 v[202:205], v160 offset:37888
	ds_read_b128 v[210:213], v160 offset:38912
	ds_read_b128 v[214:217], v160 offset:39936
	global_load_lds_dwordx4 v[206:207], off
	v_lshl_add_u64 v[206:207], v[154:155], 0, s[8:9]
	s_mov_b32 m0, s34
	s_nop 0
	global_load_lds_dwordx4 v[206:207], off
	s_waitcnt vmcnt(8)
	s_waitcnt lgkmcnt(0)
	s_barrier
	s_waitcnt lgkmcnt(0)
	v_mfma_f32_16x16x32_bf16 v[120:123], v[130:133], v[182:185], v[120:123]
	v_mfma_f32_16x16x32_bf16 v[124:127], v[138:141], v[182:185], v[124:127]
	v_mfma_f32_16x16x32_bf16 v[112:115], v[130:133], v[190:193], v[112:115]
	v_mfma_f32_16x16x32_bf16 v[116:119], v[138:141], v[190:193], v[116:119]
	v_mfma_f32_16x16x32_bf16 v[100:103], v[130:133], v[198:201], v[100:103]
	v_mfma_f32_16x16x32_bf16 v[108:111], v[138:141], v[198:201], v[108:111]
	v_mfma_f32_16x16x32_bf16 v[84:87], v[130:133], v[210:213], v[84:87]
	v_mfma_f32_16x16x32_bf16 v[72:75], v[138:141], v[210:213], v[72:75]
	v_mfma_f32_16x16x32_bf16 v[120:123], v[134:137], v[186:189], v[120:123]
	v_mfma_f32_16x16x32_bf16 v[124:127], v[162:165], v[186:189], v[124:127]
	v_mfma_f32_16x16x32_bf16 v[112:115], v[134:137], v[194:197], v[112:115]
	v_mfma_f32_16x16x32_bf16 v[116:119], v[162:165], v[194:197], v[116:119]
	v_mfma_f32_16x16x32_bf16 v[100:103], v[134:137], v[202:205], v[100:103]
	v_mfma_f32_16x16x32_bf16 v[108:111], v[162:165], v[202:205], v[108:111]
	v_mfma_f32_16x16x32_bf16 v[84:87], v[134:137], v[214:217], v[84:87]
	v_mfma_f32_16x16x32_bf16 v[72:75], v[162:165], v[214:217], v[72:75]
	v_mfma_f32_16x16x32_bf16 v[104:107], v[166:169], v[182:185], v[104:107]
	v_mfma_f32_16x16x32_bf16 v[92:95], v[174:177], v[182:185], v[92:95]
	v_mfma_f32_16x16x32_bf16 v[96:99], v[166:169], v[190:193], v[96:99]
	v_mfma_f32_16x16x32_bf16 v[80:83], v[174:177], v[190:193], v[80:83]
	v_mfma_f32_16x16x32_bf16 v[88:91], v[166:169], v[198:201], v[88:91]
	v_mfma_f32_16x16x32_bf16 v[76:79], v[174:177], v[198:201], v[76:79]
	v_mfma_f32_16x16x32_bf16 v[68:71], v[166:169], v[210:213], v[68:71]
	v_mfma_f32_16x16x32_bf16 v[64:67], v[174:177], v[210:213], v[64:67]
	v_mfma_f32_16x16x32_bf16 v[104:107], v[170:173], v[186:189], v[104:107]
	v_mfma_f32_16x16x32_bf16 v[92:95], v[178:181], v[186:189], v[92:95]
	v_mfma_f32_16x16x32_bf16 v[96:99], v[170:173], v[194:197], v[96:99]
	v_mfma_f32_16x16x32_bf16 v[80:83], v[178:181], v[194:197], v[80:83]
	v_mfma_f32_16x16x32_bf16 v[88:91], v[170:173], v[202:205], v[88:91]
	v_mfma_f32_16x16x32_bf16 v[76:79], v[178:181], v[202:205], v[76:79]
	v_mfma_f32_16x16x32_bf16 v[68:71], v[170:173], v[214:217], v[68:71]
	v_mfma_f32_16x16x32_bf16 v[64:67], v[178:181], v[214:217], v[64:67]
	s_barrier
	ds_read_b128 v[182:185], v160 offset:49152
	ds_read_b128 v[186:189], v160 offset:50176
	ds_read_b128 v[190:193], v160 offset:51200
	ds_read_b128 v[194:197], v160 offset:52224
	ds_read_b128 v[198:201], v160 offset:53248
	ds_read_b128 v[202:205], v160 offset:54272
	ds_read_b128 v[210:213], v160 offset:55296
	ds_read_b128 v[214:217], v160 offset:56320
	s_add_i32 s77, s77, s26
	s_mov_b32 m0, s77
	v_lshl_add_u64 v[206:207], v[142:143], 0, s[12:13]
	global_load_lds_dwordx4 v[206:207], off
	v_lshl_add_u64 v[206:207], v[142:143], 0, s[14:15]
	s_add_i32 m0, s77, 0x2000
	s_add_i32 s77, s78, s26
	global_load_lds_dwordx4 v[206:207], off
	v_lshl_add_u64 v[206:207], v[142:143], 0, s[22:23]
	s_mov_b32 m0, s77
	v_lshl_add_u64 v[142:143], v[142:143], 0, s[36:37]
	global_load_lds_dwordx4 v[206:207], off
	s_add_i32 m0, s77, 0x2000
	s_nop 0
	global_load_lds_dwordx4 v[142:143], off
	v_lshl_add_u64 v[142:143], v[154:155], 0, s[16:17]
	s_mov_b32 m0, s67
	s_nop 0
	global_load_lds_dwordx4 v[142:143], off
	v_lshl_add_u64 v[142:143], v[154:155], 0, s[20:21]
	s_mov_b32 m0, s69
	s_nop 0
	global_load_lds_dwordx4 v[142:143], off
	s_waitcnt vmcnt(8)
	s_waitcnt lgkmcnt(0)
	s_barrier
	s_waitcnt lgkmcnt(0)
	v_mfma_f32_16x16x32_bf16 v[60:63], v[130:133], v[182:185], v[60:63]
	v_mfma_f32_16x16x32_bf16 v[56:59], v[138:141], v[182:185], v[56:59]
	v_mfma_f32_16x16x32_bf16 v[52:55], v[130:133], v[190:193], v[52:55]
	v_mfma_f32_16x16x32_bf16 v[44:47], v[138:141], v[190:193], v[44:47]
	s_add_i32 s76, s76, 2
	v_mfma_f32_16x16x32_bf16 v[36:39], v[130:133], v[198:201], v[36:39]
	s_add_u32 s28, s28, 0x40000
	v_mfma_f32_16x16x32_bf16 v[28:31], v[138:141], v[198:201], v[28:31]
	s_addc_u32 s29, s29, 0
	v_mfma_f32_16x16x32_bf16 v[20:23], v[130:133], v[210:213], v[20:23]
	s_add_u32 s72, s72, 0x800000
	v_mfma_f32_16x16x32_bf16 v[12:15], v[138:141], v[210:213], v[12:15]
	s_addc_u32 s73, s73, 0
	v_mfma_f32_16x16x32_bf16 v[60:63], v[134:137], v[186:189], v[60:63]
	s_cmp_gt_u32 s76, 29
	v_mfma_f32_16x16x32_bf16 v[56:59], v[162:165], v[186:189], v[56:59]
	v_mfma_f32_16x16x32_bf16 v[52:55], v[134:137], v[194:197], v[52:55]
	v_mfma_f32_16x16x32_bf16 v[44:47], v[162:165], v[194:197], v[44:47]
	v_mfma_f32_16x16x32_bf16 v[36:39], v[134:137], v[202:205], v[36:39]
	v_mfma_f32_16x16x32_bf16 v[28:31], v[162:165], v[202:205], v[28:31]
	v_mfma_f32_16x16x32_bf16 v[20:23], v[134:137], v[214:217], v[20:23]
	v_mfma_f32_16x16x32_bf16 v[12:15], v[162:165], v[214:217], v[12:15]
	v_mfma_f32_16x16x32_bf16 v[48:51], v[166:169], v[182:185], v[48:51]
	v_mfma_f32_16x16x32_bf16 v[40:43], v[174:177], v[182:185], v[40:43]
	v_mfma_f32_16x16x32_bf16 v[32:35], v[166:169], v[190:193], v[32:35]
	v_mfma_f32_16x16x32_bf16 v[24:27], v[174:177], v[190:193], v[24:27]
	v_mfma_f32_16x16x32_bf16 v[16:19], v[166:169], v[198:201], v[16:19]
	v_mfma_f32_16x16x32_bf16 v[8:11], v[174:177], v[198:201], v[8:11]
	v_mfma_f32_16x16x32_bf16 v[4:7], v[166:169], v[210:213], v[4:7]
	v_mfma_f32_16x16x32_bf16 v[0:3], v[174:177], v[210:213], v[0:3]
	v_mfma_f32_16x16x32_bf16 v[48:51], v[170:173], v[186:189], v[48:51]
	v_mfma_f32_16x16x32_bf16 v[40:43], v[178:181], v[186:189], v[40:43]
	v_mfma_f32_16x16x32_bf16 v[32:35], v[170:173], v[194:197], v[32:35]
	v_mfma_f32_16x16x32_bf16 v[24:27], v[178:181], v[194:197], v[24:27]
	v_mfma_f32_16x16x32_bf16 v[16:19], v[170:173], v[202:205], v[16:19]
	v_mfma_f32_16x16x32_bf16 v[8:11], v[178:181], v[202:205], v[8:11]
	v_mfma_f32_16x16x32_bf16 v[4:7], v[170:173], v[214:217], v[4:7]
	v_mfma_f32_16x16x32_bf16 v[0:3], v[178:181], v[214:217], v[0:3]
	s_barrier
	s_cbranch_scc0 .LBB0_770
	s_and_b64 vcc, exec, s[38:39]
	s_cbranch_vccz .LBB0_773
	s_barrier
